# v42 + remove redundant expf range clamps (cmp+cndmask pairs, 384 sites) in gemm_in sigmoid and gemm_f1 silu epilogues; v_exp/ldexp saturate identically
# speedup vs baseline: 1.0025x; 1.0025x over previous
; DEVI float sigmf(float x) { return 1.f / (1.f + expf(-x)); }
; DEVI void phase_gemm_in(const Params& p, int l, char* lds) {
;     ...
;       for (int mi = 0; mi < 2; ++mi) {
;         const int m = m0 + wm * 64 + mi * 32 + r32;
; #pragma unroll
;         for (int q = 0; q < 4; ++q) {
;           const int ci = q * 8 + hi * 4;
;           float x1[4], x2[4];
; #pragma unroll
;           for (int j = 0; j < 4; ++j) { x1[j] = acc[2 * cg2][mi][q * 4 + j]; x2[j] = acc[2 * cg2 + 1][mi][q * 4 + j]; }
;           if (mode == 1) {
; #pragma unroll
;             for (int j = 0; j < 4; ++j) { x1[j] *= 0.08838834764831845f; x2[j] *= 0.08838834764831845f; }
;           } else if (mode == 2) {
;             if (rr_of(m) < SEQ) {
;               const f32x4 cs = *(const f32x4*)(rope + (long)rr_of(m) * 64 + ci);
;               const f32x4 sn = *(const f32x4*)(rope + (long)rr_of(m) * 64 + 32 + ci);
; #pragma unroll
;               for (int j = 0; j < 4; ++j) { const float a = x1[j], bb = x2[j]; x1[j] = a * cs[j] - bb * sn[j]; x2[j] = a * sn[j] + bb * cs[j]; }
;             }
;           } else if (mode == 3) {
; #pragma unroll
;             for (int j = 0; j < 4; ++j) { x1[j] = sigmf(x1[j]); x2[j] = sigmf(x2[j]); }
;           }
.LBB0_141:
	s_or_b64 exec, exec, s[6:7]
	v_or_b32_e32 v139, s26, v220
	v_add_u32_e32 v128, 0xffffdf00, v139
	v_cmp_lt_i32_e32 vcc, s53, v139
	s_xor_b64 s[12:13], s[8:9], -1
	v_readlane_b32 s8, v252, 45
	v_cndmask_b32_e32 v128, v139, v128, vcc
	v_ashrrev_i32_e32 v129, 31, v128
	v_cmp_gt_i32_e64 s[6:7], s95, v128
	v_lshlrev_b64 v[128:129], 8, v[128:129]
	v_readlane_b32 s9, v252, 46
	s_nop 1
	v_lshl_add_u64 v[128:129], s[8:9], 0, v[128:129]
	s_and_saveexec_b64 s[8:9], s[10:11]
	s_xor_b64 s[8:9], exec, s[8:9]
	s_cbranch_execz .LBB0_151
	s_and_saveexec_b64 s[14:15], s[12:13]
	s_xor_b64 s[14:15], exec, s[14:15]
	s_cbranch_execz .LBB0_146
	s_waitcnt vmcnt(5)
	v_mov_b32_e32 v135, v115
	v_mov_b32_e32 v134, v114
	v_mov_b32_e32 v131, v113
	v_mov_b32_e32 v130, v112
	v_mov_b32_e32 v137, v99
	v_mov_b32_e32 v136, v98
	v_mov_b32_e32 v133, v97
	v_mov_b32_e32 v132, v96
	s_and_saveexec_b64 s[28:29], s[2:3]
	s_cbranch_execz .LBB0_145
	v_mul_f32_e32 v130, 0xbfb8aa3b, v112
	v_rndne_f32_e32 v131, v130
	v_sub_f32_e32 v132, v130, v131
	v_fma_f32 v130, v112, s54, -v130
	v_fmac_f32_e32 v130, 0xb2a5705f, v112
	v_add_f32_e32 v130, v132, v130
	v_exp_f32_e32 v130, v130
	v_cvt_i32_f32_e32 v131, v131
	v_ldexp_f32 v130, v130, v131
	v_mul_f32_e32 v131, 0xbfb8aa3b, v96
	v_rndne_f32_e32 v132, v131
	v_sub_f32_e32 v133, v131, v132
	v_fma_f32 v131, v96, s54, -v131
	v_fmac_f32_e32 v131, 0xb2a5705f, v96
	v_add_f32_e32 v131, v133, v131
	v_exp_f32_e32 v131, v131
	v_cvt_i32_f32_e32 v132, v132
	v_ldexp_f32 v131, v131, v132
	s_nop 0
	s_nop 1
	s_nop 1
	v_mov_b32_e32 v132, v131
	v_mul_f32_e32 v131, 0xbfb8aa3b, v113
	v_rndne_f32_e32 v133, v131
	v_sub_f32_e32 v134, v131, v133
	v_fma_f32 v131, v113, s54, -v131
	v_fmac_f32_e32 v131, 0xb2a5705f, v113
	v_add_f32_e32 v131, v134, v131
	v_exp_f32_e32 v131, v131
	v_cvt_i32_f32_e32 v133, v133
	v_ldexp_f32 v131, v131, v133
	s_nop 0
	s_nop 1
	v_pk_add_f32 v[130:131], v[130:131], 1.0 op_sel_hi:[1,0]
	s_nop 0
	v_div_scale_f32 v133, s[30:31], v130, v130, 1.0
	v_rcp_f32_e32 v134, v133
	s_nop 0
	v_fma_f32 v135, -v133, v134, 1.0
	v_fmac_f32_e32 v134, v135, v134
	v_div_scale_f32 v135, vcc, 1.0, v130, 1.0
	v_mul_f32_e32 v136, v135, v134
	v_fma_f32 v137, -v133, v136, v135
	v_fmac_f32_e32 v136, v137, v134
	v_fma_f32 v133, -v133, v136, v135
	v_div_fmas_f32 v133, v133, v134, v136
	v_div_fixup_f32 v130, v133, v130, 1.0
	v_div_scale_f32 v133, s[30:31], v131, v131, 1.0
	v_rcp_f32_e32 v134, v133
	s_nop 0
	v_fma_f32 v135, -v133, v134, 1.0
	v_fmac_f32_e32 v134, v135, v134
	v_div_scale_f32 v135, vcc, 1.0, v131, 1.0
	v_mul_f32_e32 v136, v135, v134
	v_fma_f32 v137, -v133, v136, v135
	v_fmac_f32_e32 v136, v137, v134
	v_fma_f32 v133, -v133, v136, v135
	v_div_fmas_f32 v133, v133, v134, v136
	v_div_fixup_f32 v131, v133, v131, 1.0
	v_mul_f32_e32 v133, 0xbfb8aa3b, v97
	v_rndne_f32_e32 v134, v133
	v_sub_f32_e32 v135, v133, v134
	v_fma_f32 v133, v97, s54, -v133
	v_fmac_f32_e32 v133, 0xb2a5705f, v97
	v_add_f32_e32 v133, v135, v133
	v_exp_f32_e32 v133, v133
	v_cvt_i32_f32_e32 v134, v134
	v_ldexp_f32 v133, v133, v134
	s_nop 0
	s_nop 1
	v_pk_add_f32 v[132:133], v[132:133], 1.0 op_sel_hi:[1,0]
	s_nop 0
	v_div_scale_f32 v134, s[30:31], v132, v132, 1.0
	v_rcp_f32_e32 v135, v134
	s_nop 0
	v_fma_f32 v136, -v134, v135, 1.0
	v_fmac_f32_e32 v135, v136, v135
	v_div_scale_f32 v136, vcc, 1.0, v132, 1.0
	v_mul_f32_e32 v137, v136, v135
	s_waitcnt vmcnt(3)
	v_fma_f32 v140, -v134, v137, v136
	v_fmac_f32_e32 v137, v140, v135
	v_fma_f32 v134, -v134, v137, v136
	v_div_fmas_f32 v134, v134, v135, v137
	v_div_fixup_f32 v132, v134, v132, 1.0
	v_div_scale_f32 v134, s[30:31], v133, v133, 1.0
	v_rcp_f32_e32 v135, v134
	s_nop 0
	v_fma_f32 v136, -v134, v135, 1.0
	v_fmac_f32_e32 v135, v136, v135
	v_div_scale_f32 v136, vcc, 1.0, v133, 1.0
	v_mul_f32_e32 v137, v136, v135
	v_fma_f32 v140, -v134, v137, v136
	v_fmac_f32_e32 v137, v140, v135
	v_fma_f32 v134, -v134, v137, v136
	v_div_fmas_f32 v134, v134, v135, v137
	v_div_fixup_f32 v133, v134, v133, 1.0
	v_mul_f32_e32 v134, 0xbfb8aa3b, v114
	v_rndne_f32_e32 v135, v134
	v_sub_f32_e32 v136, v134, v135
	v_fma_f32 v134, v114, s54, -v134
	v_fmac_f32_e32 v134, 0xb2a5705f, v114
	v_add_f32_e32 v134, v136, v134
	v_exp_f32_e32 v134, v134
	v_cvt_i32_f32_e32 v135, v135
	v_ldexp_f32 v134, v134, v135
	v_mul_f32_e32 v135, 0xbfb8aa3b, v98
	v_rndne_f32_e32 v136, v135
	v_sub_f32_e32 v137, v135, v136
	v_fma_f32 v135, v98, s54, -v135
	v_fmac_f32_e32 v135, 0xb2a5705f, v98
	v_add_f32_e32 v135, v137, v135
	v_exp_f32_e32 v135, v135
	v_cvt_i32_f32_e32 v136, v136
	v_ldexp_f32 v135, v135, v136
	s_nop 0
	s_nop 1
	s_nop 1
	v_mov_b32_e32 v136, v135
	v_mul_f32_e32 v135, 0xbfb8aa3b, v115
	v_rndne_f32_e32 v137, v135
	v_sub_f32_e32 v140, v135, v137
	v_fma_f32 v135, v115, s54, -v135
	v_fmac_f32_e32 v135, 0xb2a5705f, v115
	v_add_f32_e32 v135, v140, v135
	v_exp_f32_e32 v135, v135
	v_cvt_i32_f32_e32 v137, v137
	v_ldexp_f32 v135, v135, v137
	s_nop 0
	s_nop 1
	v_pk_add_f32 v[134:135], v[134:135], 1.0 op_sel_hi:[1,0]
	s_nop 0
	v_div_scale_f32 v137, s[30:31], v134, v134, 1.0
	v_rcp_f32_e32 v140, v137
	s_nop 0
	v_fma_f32 v141, -v137, v140, 1.0
	v_fmac_f32_e32 v140, v141, v140
	v_div_scale_f32 v141, vcc, 1.0, v134, 1.0
	v_mul_f32_e32 v142, v141, v140
	v_fma_f32 v143, -v137, v142, v141
	v_fmac_f32_e32 v142, v143, v140
	v_fma_f32 v137, -v137, v142, v141
	v_div_fmas_f32 v137, v137, v140, v142
	v_div_fixup_f32 v134, v137, v134, 1.0
	v_div_scale_f32 v137, s[30:31], v135, v135, 1.0
	v_rcp_f32_e32 v140, v137
	s_nop 0
	v_fma_f32 v141, -v137, v140, 1.0
	v_fmac_f32_e32 v140, v141, v140
	v_div_scale_f32 v141, vcc, 1.0, v135, 1.0
	v_mul_f32_e32 v142, v141, v140
	v_fma_f32 v143, -v137, v142, v141
	v_fmac_f32_e32 v142, v143, v140
	v_fma_f32 v137, -v137, v142, v141
	v_div_fmas_f32 v137, v137, v140, v142
	v_div_fixup_f32 v135, v137, v135, 1.0
	v_mul_f32_e32 v137, 0xbfb8aa3b, v99
	v_rndne_f32_e32 v140, v137
	v_sub_f32_e32 v141, v137, v140
	v_fma_f32 v137, v99, s54, -v137
	v_fmac_f32_e32 v137, 0xb2a5705f, v99
	v_add_f32_e32 v137, v141, v137
	v_exp_f32_e32 v137, v137
	v_cvt_i32_f32_e32 v140, v140
	v_ldexp_f32 v137, v137, v140
	s_nop 0
	s_nop 1
	v_pk_add_f32 v[136:137], v[136:137], 1.0 op_sel_hi:[1,0]
	s_nop 0
	v_div_scale_f32 v140, s[30:31], v136, v136, 1.0
	v_rcp_f32_e32 v141, v140
	s_nop 0
	v_fma_f32 v142, -v140, v141, 1.0
	v_fmac_f32_e32 v141, v142, v141
	v_div_scale_f32 v142, vcc, 1.0, v136, 1.0
	v_mul_f32_e32 v143, v142, v141
	v_fma_f32 v144, -v140, v143, v142
	v_fmac_f32_e32 v143, v144, v141
	v_fma_f32 v140, -v140, v143, v142
	v_div_fmas_f32 v140, v140, v141, v143
	v_div_fixup_f32 v136, v140, v136, 1.0
	v_div_scale_f32 v140, s[30:31], v137, v137, 1.0
	v_rcp_f32_e32 v141, v140
	s_nop 0
	v_fma_f32 v142, -v140, v141, 1.0
	v_fmac_f32_e32 v141, v142, v141
	v_div_scale_f32 v142, vcc, 1.0, v137, 1.0
	v_mul_f32_e32 v143, v142, v141
	v_fma_f32 v144, -v140, v143, v142
	v_fmac_f32_e32 v143, v144, v141
	v_fma_f32 v140, -v140, v143, v142
	v_div_fmas_f32 v140, v140, v141, v143
	v_div_fixup_f32 v137, v140, v137, 1.0

; DEVI float sigmf(float x) { return 1.f / (1.f + expf(-x)); }
; DEVI void lds_put4(char* wl, int RS, int row, int col, float a, float b, float c, float d) { u32x2 w = {cvtpk(a, b), cvtpk(c, d)}; *(u32x2*)(wl + row * RS + col * 2) = w; }
; DEVI void phase_gemm_in(const Params& p, int l, char* lds) {
;     ...
;           } else if (mode == 3) {
; #pragma unroll
;             for (int j = 0; j < 4; ++j) { x1[j] = sigmf(x1[j]); x2[j] = sigmf(x2[j]); }
;           }
;           lds_put4(wl, 272, mi * 32 + r32, cg2 * 64 + ci, x1[0], x1[1], x1[2], x1[3]);
.LBB0_153:
	s_or_b64 exec, exec, s[8:9]
	v_cvt_pk_bf16_f32 v96, v130, v131
	s_waitcnt vmcnt(5)
	v_cvt_pk_bf16_f32 v97, v134, v135
	v_add_u32_e32 v130, v221, v222
	v_cvt_pk_bf16_f32 v98, v132, v133
	v_cvt_pk_bf16_f32 v99, v136, v137
	ds_write2_b64 v130, v[96:97], v[98:99] offset1:8
	s_and_saveexec_b64 s[8:9], s[10:11]
	s_xor_b64 s[8:9], exec, s[8:9]
	s_cbranch_execz .LBB0_163
	s_and_saveexec_b64 s[14:15], s[12:13]
	s_xor_b64 s[14:15], exec, s[14:15]
	s_cbranch_execz .LBB0_158
	v_mov_b32_e32 v113, v119
	v_mov_b32_e32 v112, v118
	v_mov_b32_e32 v97, v117
	v_mov_b32_e32 v96, v116
	v_mov_b32_e32 v115, v103
	v_mov_b32_e32 v114, v102
	v_mov_b32_e32 v99, v101
	v_mov_b32_e32 v98, v100
	s_and_saveexec_b64 s[28:29], s[2:3]
	s_cbranch_execz .LBB0_157
	v_mul_f32_e32 v96, 0xbfb8aa3b, v116
	v_rndne_f32_e32 v97, v96
	v_sub_f32_e32 v98, v96, v97
	v_fma_f32 v96, v116, s54, -v96
	v_fmac_f32_e32 v96, 0xb2a5705f, v116
	v_add_f32_e32 v96, v98, v96
	v_exp_f32_e32 v96, v96
	v_cvt_i32_f32_e32 v97, v97
	v_ldexp_f32 v96, v96, v97
	v_mul_f32_e32 v97, 0xbfb8aa3b, v100
	v_rndne_f32_e32 v98, v97
	v_sub_f32_e32 v99, v97, v98
	v_fma_f32 v97, v100, s54, -v97
	v_fmac_f32_e32 v97, 0xb2a5705f, v100
	v_add_f32_e32 v97, v99, v97
	v_exp_f32_e32 v97, v97
	v_cvt_i32_f32_e32 v98, v98
	v_ldexp_f32 v97, v97, v98
	s_nop 0
	s_nop 1
	s_nop 1
	v_mov_b32_e32 v98, v97
	v_mul_f32_e32 v97, 0xbfb8aa3b, v117
	v_rndne_f32_e32 v99, v97
	v_sub_f32_e32 v112, v97, v99
	v_fma_f32 v97, v117, s54, -v97
	v_fmac_f32_e32 v97, 0xb2a5705f, v117
	v_add_f32_e32 v97, v112, v97
	v_exp_f32_e32 v97, v97
	v_cvt_i32_f32_e32 v99, v99
	v_ldexp_f32 v97, v97, v99
	s_nop 0
	s_nop 1
	v_pk_add_f32 v[96:97], v[96:97], 1.0 op_sel_hi:[1,0]
	s_nop 0
	v_div_scale_f32 v99, s[30:31], v96, v96, 1.0
	v_rcp_f32_e32 v112, v99
	s_nop 0
	v_fma_f32 v113, -v99, v112, 1.0
	v_fmac_f32_e32 v112, v113, v112
	v_div_scale_f32 v113, vcc, 1.0, v96, 1.0
	v_mul_f32_e32 v114, v113, v112
	v_fma_f32 v115, -v99, v114, v113
	v_fmac_f32_e32 v114, v115, v112
	v_fma_f32 v99, -v99, v114, v113
	v_div_fmas_f32 v99, v99, v112, v114
	v_div_fixup_f32 v96, v99, v96, 1.0
	v_div_scale_f32 v99, s[30:31], v97, v97, 1.0
	v_rcp_f32_e32 v112, v99
	s_nop 0
	v_fma_f32 v113, -v99, v112, 1.0
	v_fmac_f32_e32 v112, v113, v112
	v_div_scale_f32 v113, vcc, 1.0, v97, 1.0
	v_mul_f32_e32 v114, v113, v112
	v_fma_f32 v115, -v99, v114, v113
	v_fmac_f32_e32 v114, v115, v112
	v_fma_f32 v99, -v99, v114, v113
	v_div_fmas_f32 v99, v99, v112, v114
	v_div_fixup_f32 v97, v99, v97, 1.0
	v_mul_f32_e32 v99, 0xbfb8aa3b, v101
	v_rndne_f32_e32 v112, v99
	v_sub_f32_e32 v113, v99, v112
	v_fma_f32 v99, v101, s54, -v99
	v_fmac_f32_e32 v99, 0xb2a5705f, v101
	v_add_f32_e32 v99, v113, v99
	v_exp_f32_e32 v99, v99
	v_cvt_i32_f32_e32 v112, v112
	v_ldexp_f32 v99, v99, v112
	s_nop 0
	s_nop 1
	v_pk_add_f32 v[98:99], v[98:99], 1.0 op_sel_hi:[1,0]
	s_nop 0
	v_div_scale_f32 v112, s[30:31], v98, v98, 1.0
	v_rcp_f32_e32 v113, v112
	s_nop 0
	v_fma_f32 v114, -v112, v113, 1.0
	v_fmac_f32_e32 v113, v114, v113
	v_div_scale_f32 v114, vcc, 1.0, v98, 1.0
	v_mul_f32_e32 v115, v114, v113
	v_fma_f32 v131, -v112, v115, v114
	v_fmac_f32_e32 v115, v131, v113
	v_fma_f32 v112, -v112, v115, v114
	v_div_fmas_f32 v112, v112, v113, v115
	v_div_fixup_f32 v98, v112, v98, 1.0
	v_div_scale_f32 v112, s[30:31], v99, v99, 1.0
	v_rcp_f32_e32 v113, v112
	s_nop 0
	v_fma_f32 v114, -v112, v113, 1.0
	v_fmac_f32_e32 v113, v114, v113
	v_div_scale_f32 v114, vcc, 1.0, v99, 1.0
	v_mul_f32_e32 v115, v114, v113
	v_fma_f32 v131, -v112, v115, v114
	v_fmac_f32_e32 v115, v131, v113
	v_fma_f32 v112, -v112, v115, v114
	v_div_fmas_f32 v112, v112, v113, v115
	v_div_fixup_f32 v99, v112, v99, 1.0
	v_mul_f32_e32 v112, 0xbfb8aa3b, v118
	v_rndne_f32_e32 v113, v112
	v_sub_f32_e32 v114, v112, v113
	v_fma_f32 v112, v118, s54, -v112
	v_fmac_f32_e32 v112, 0xb2a5705f, v118
	v_add_f32_e32 v112, v114, v112
	v_exp_f32_e32 v112, v112
	v_cvt_i32_f32_e32 v113, v113
	v_ldexp_f32 v112, v112, v113
	v_mul_f32_e32 v113, 0xbfb8aa3b, v102
	v_rndne_f32_e32 v114, v113
	v_sub_f32_e32 v115, v113, v114
	v_fma_f32 v113, v102, s54, -v113
	v_fmac_f32_e32 v113, 0xb2a5705f, v102
	v_add_f32_e32 v113, v115, v113
	v_exp_f32_e32 v113, v113
	v_cvt_i32_f32_e32 v114, v114
	v_ldexp_f32 v113, v113, v114
	s_nop 0
	s_nop 1
	s_nop 1
	v_mov_b32_e32 v114, v113
	v_mul_f32_e32 v113, 0xbfb8aa3b, v119
	v_rndne_f32_e32 v115, v113
	v_sub_f32_e32 v131, v113, v115
	v_fma_f32 v113, v119, s54, -v113
	v_fmac_f32_e32 v113, 0xb2a5705f, v119
	v_add_f32_e32 v113, v131, v113
	v_exp_f32_e32 v113, v113
	v_cvt_i32_f32_e32 v115, v115
	v_ldexp_f32 v113, v113, v115
	s_nop 0
	s_nop 1
	v_pk_add_f32 v[112:113], v[112:113], 1.0 op_sel_hi:[1,0]
	s_nop 0
	v_div_scale_f32 v115, s[30:31], v112, v112, 1.0
	v_rcp_f32_e32 v131, v115
	s_nop 0
	v_fma_f32 v132, -v115, v131, 1.0
	v_fmac_f32_e32 v131, v132, v131
	v_div_scale_f32 v132, vcc, 1.0, v112, 1.0
	v_mul_f32_e32 v133, v132, v131
	v_fma_f32 v134, -v115, v133, v132
	v_fmac_f32_e32 v133, v134, v131
	v_fma_f32 v115, -v115, v133, v132
	v_div_fmas_f32 v115, v115, v131, v133
	v_div_fixup_f32 v112, v115, v112, 1.0
	v_div_scale_f32 v115, s[30:31], v113, v113, 1.0
	v_rcp_f32_e32 v131, v115
	s_nop 0
	v_fma_f32 v132, -v115, v131, 1.0
	v_fmac_f32_e32 v131, v132, v131
	v_div_scale_f32 v132, vcc, 1.0, v113, 1.0
	v_mul_f32_e32 v133, v132, v131
	v_fma_f32 v134, -v115, v133, v132
	v_fmac_f32_e32 v133, v134, v131
	v_fma_f32 v115, -v115, v133, v132
	v_div_fmas_f32 v115, v115, v131, v133
	v_div_fixup_f32 v113, v115, v113, 1.0
	v_mul_f32_e32 v115, 0xbfb8aa3b, v103
	v_rndne_f32_e32 v131, v115
	v_sub_f32_e32 v132, v115, v131
	v_fma_f32 v115, v103, s54, -v115
	v_fmac_f32_e32 v115, 0xb2a5705f, v103
	v_add_f32_e32 v115, v132, v115
	v_exp_f32_e32 v115, v115
	v_cvt_i32_f32_e32 v131, v131
	v_ldexp_f32 v115, v115, v131
	s_nop 0
	s_nop 1
	v_pk_add_f32 v[114:115], v[114:115], 1.0 op_sel_hi:[1,0]
	s_nop 0
	v_div_scale_f32 v131, s[30:31], v114, v114, 1.0
	v_rcp_f32_e32 v132, v131
	s_nop 0
	v_fma_f32 v133, -v131, v132, 1.0
	v_fmac_f32_e32 v132, v133, v132
	v_div_scale_f32 v133, vcc, 1.0, v114, 1.0
	v_mul_f32_e32 v134, v133, v132
	v_fma_f32 v135, -v131, v134, v133
	v_fmac_f32_e32 v134, v135, v132
	v_fma_f32 v131, -v131, v134, v133
	v_div_fmas_f32 v131, v131, v132, v134
	v_div_fixup_f32 v114, v131, v114, 1.0
	v_div_scale_f32 v131, s[30:31], v115, v115, 1.0
	v_rcp_f32_e32 v132, v131
	s_nop 0
	v_fma_f32 v133, -v131, v132, 1.0
	v_fmac_f32_e32 v132, v133, v132
	v_div_scale_f32 v133, vcc, 1.0, v115, 1.0
	v_mul_f32_e32 v134, v133, v132
	v_fma_f32 v135, -v131, v134, v133
	v_fmac_f32_e32 v134, v135, v132
	v_fma_f32 v131, -v131, v134, v133
	v_div_fmas_f32 v131, v131, v132, v134
	v_div_fixup_f32 v115, v131, v115, 1.0

; DEVI float sigmf(float x) { return 1.f / (1.f + expf(-x)); }
; DEVI void lds_put4(char* wl, int RS, int row, int col, float a, float b, float c, float d) { u32x2 w = {cvtpk(a, b), cvtpk(c, d)}; *(u32x2*)(wl + row * RS + col * 2) = w; }
; DEVI void phase_gemm_in(const Params& p, int l, char* lds) {
;     ...
;           if (mode == 1) {
; #pragma unroll
;             for (int j = 0; j < 4; ++j) { x1[j] *= 0.08838834764831845f; x2[j] *= 0.08838834764831845f; }
;           } else if (mode == 2) {
;             if (rr_of(m) < SEQ) {
;               const f32x4 cs = *(const f32x4*)(rope + (long)rr_of(m) * 64 + ci);
;               const f32x4 sn = *(const f32x4*)(rope + (long)rr_of(m) * 64 + 32 + ci);
; #pragma unroll
;               for (int j = 0; j < 4; ++j) { const float a = x1[j], bb = x2[j]; x1[j] = a * cs[j] - bb * sn[j]; x2[j] = a * sn[j] + bb * cs[j]; }
;             }
;           } else if (mode == 3) {
; #pragma unroll
;             for (int j = 0; j < 4; ++j) { x1[j] = sigmf(x1[j]); x2[j] = sigmf(x2[j]); }
;           }
;           lds_put4(wl, 272, mi * 32 + r32, cg2 * 64 + ci, x1[0], x1[1], x1[2], x1[3]);
.LBB0_163:
	s_andn2_saveexec_b64 s[8:9], s[8:9]
	v_pk_mul_f32 v[96:97], v[116:117], s[96:97] op_sel_hi:[1,0]
	v_pk_mul_f32 v[98:99], v[100:101], s[96:97] op_sel_hi:[1,0]
	v_pk_mul_f32 v[112:113], v[118:119], s[96:97] op_sel_hi:[1,0]
	v_pk_mul_f32 v[114:115], v[102:103], s[96:97] op_sel_hi:[1,0]
	s_or_b64 exec, exec, s[8:9]
	v_cvt_pk_bf16_f32 v96, v96, v97
	v_cvt_pk_bf16_f32 v97, v112, v113
	v_cvt_pk_bf16_f32 v98, v98, v99
	v_cvt_pk_bf16_f32 v99, v114, v115
	ds_write2_b64 v223, v[96:97], v[98:99] offset1:8
	s_and_saveexec_b64 s[8:9], s[10:11]
	s_xor_b64 s[8:9], exec, s[8:9]
	s_cbranch_execz .LBB0_175
	s_and_saveexec_b64 s[14:15], s[12:13]
	s_xor_b64 s[14:15], exec, s[14:15]
	s_cbranch_execz .LBB0_170
	v_mov_b32_e32 v101, v123
	v_mov_b32_e32 v100, v122
	v_mov_b32_e32 v97, v121
	v_mov_b32_e32 v96, v120
	v_mov_b32_e32 v103, v107
	v_mov_b32_e32 v102, v106
	v_mov_b32_e32 v99, v105
	v_mov_b32_e32 v98, v104
	s_and_saveexec_b64 s[28:29], s[2:3]
	s_cbranch_execz .LBB0_169
	v_mul_f32_e32 v96, 0xbfb8aa3b, v120
	v_rndne_f32_e32 v97, v96
	v_sub_f32_e32 v98, v96, v97
	v_fma_f32 v96, v120, s54, -v96
	v_fmac_f32_e32 v96, 0xb2a5705f, v120
	v_add_f32_e32 v96, v98, v96
	v_exp_f32_e32 v96, v96
	v_cvt_i32_f32_e32 v97, v97
	v_ldexp_f32 v96, v96, v97
	v_mul_f32_e32 v97, 0xbfb8aa3b, v104
	v_rndne_f32_e32 v98, v97
	v_sub_f32_e32 v99, v97, v98
	v_fma_f32 v97, v104, s54, -v97
	v_fmac_f32_e32 v97, 0xb2a5705f, v104
	v_add_f32_e32 v97, v99, v97
	v_exp_f32_e32 v97, v97
	v_cvt_i32_f32_e32 v98, v98
	v_ldexp_f32 v97, v97, v98
	s_nop 0
	s_nop 1
	s_nop 1
	v_mov_b32_e32 v98, v97
	v_mul_f32_e32 v97, 0xbfb8aa3b, v121
	v_rndne_f32_e32 v99, v97
	v_sub_f32_e32 v100, v97, v99
	v_fma_f32 v97, v121, s54, -v97
	v_fmac_f32_e32 v97, 0xb2a5705f, v121
	v_add_f32_e32 v97, v100, v97
	v_exp_f32_e32 v97, v97
	v_cvt_i32_f32_e32 v99, v99
	v_ldexp_f32 v97, v97, v99
	s_nop 0
	s_nop 1
	v_pk_add_f32 v[96:97], v[96:97], 1.0 op_sel_hi:[1,0]
	s_nop 0
	v_div_scale_f32 v99, s[30:31], v96, v96, 1.0
	v_rcp_f32_e32 v100, v99
	s_nop 0
	v_fma_f32 v101, -v99, v100, 1.0
	v_fmac_f32_e32 v100, v101, v100
	v_div_scale_f32 v101, vcc, 1.0, v96, 1.0
	v_mul_f32_e32 v102, v101, v100
	v_fma_f32 v103, -v99, v102, v101
	v_fmac_f32_e32 v102, v103, v100
	v_fma_f32 v99, -v99, v102, v101
	v_div_fmas_f32 v99, v99, v100, v102
	v_div_fixup_f32 v96, v99, v96, 1.0
	v_div_scale_f32 v99, s[30:31], v97, v97, 1.0
	v_rcp_f32_e32 v100, v99
	s_nop 0
	v_fma_f32 v101, -v99, v100, 1.0
	v_fmac_f32_e32 v100, v101, v100
	v_div_scale_f32 v101, vcc, 1.0, v97, 1.0
	v_mul_f32_e32 v102, v101, v100
	v_fma_f32 v103, -v99, v102, v101
	v_fmac_f32_e32 v102, v103, v100
	v_fma_f32 v99, -v99, v102, v101
	v_div_fmas_f32 v99, v99, v100, v102
	v_div_fixup_f32 v97, v99, v97, 1.0
	v_mul_f32_e32 v99, 0xbfb8aa3b, v105
	v_rndne_f32_e32 v100, v99
	v_sub_f32_e32 v101, v99, v100
	v_fma_f32 v99, v105, s54, -v99
	v_fmac_f32_e32 v99, 0xb2a5705f, v105
	v_add_f32_e32 v99, v101, v99
	v_exp_f32_e32 v99, v99
	v_cvt_i32_f32_e32 v100, v100
	v_ldexp_f32 v99, v99, v100
	s_nop 0
	s_nop 1
	v_pk_add_f32 v[98:99], v[98:99], 1.0 op_sel_hi:[1,0]
	s_nop 0
	v_div_scale_f32 v100, s[30:31], v98, v98, 1.0
	v_rcp_f32_e32 v101, v100
	s_nop 0
	v_fma_f32 v102, -v100, v101, 1.0
	v_fmac_f32_e32 v101, v102, v101
	v_div_scale_f32 v102, vcc, 1.0, v98, 1.0
	v_mul_f32_e32 v103, v102, v101
	v_fma_f32 v112, -v100, v103, v102
	v_fmac_f32_e32 v103, v112, v101
	v_fma_f32 v100, -v100, v103, v102
	v_div_fmas_f32 v100, v100, v101, v103
	v_div_fixup_f32 v98, v100, v98, 1.0
	v_div_scale_f32 v100, s[30:31], v99, v99, 1.0
	v_rcp_f32_e32 v101, v100
	s_nop 0
	v_fma_f32 v102, -v100, v101, 1.0
	v_fmac_f32_e32 v101, v102, v101
	v_div_scale_f32 v102, vcc, 1.0, v99, 1.0
	v_mul_f32_e32 v103, v102, v101
	v_fma_f32 v112, -v100, v103, v102
	v_fmac_f32_e32 v103, v112, v101
	v_fma_f32 v100, -v100, v103, v102
	v_div_fmas_f32 v100, v100, v101, v103
	v_div_fixup_f32 v99, v100, v99, 1.0
	v_mul_f32_e32 v100, 0xbfb8aa3b, v122
	v_rndne_f32_e32 v101, v100
	v_sub_f32_e32 v102, v100, v101
	v_fma_f32 v100, v122, s54, -v100
	v_fmac_f32_e32 v100, 0xb2a5705f, v122
	v_add_f32_e32 v100, v102, v100
	v_exp_f32_e32 v100, v100
	v_cvt_i32_f32_e32 v101, v101
	v_ldexp_f32 v100, v100, v101
	v_mul_f32_e32 v101, 0xbfb8aa3b, v106
	v_rndne_f32_e32 v102, v101
	v_sub_f32_e32 v103, v101, v102
	v_fma_f32 v101, v106, s54, -v101
	v_fmac_f32_e32 v101, 0xb2a5705f, v106
	v_add_f32_e32 v101, v103, v101
	v_exp_f32_e32 v101, v101
	v_cvt_i32_f32_e32 v102, v102
	v_ldexp_f32 v101, v101, v102
	s_nop 0
	s_nop 1
	s_nop 1
	v_mov_b32_e32 v102, v101
	v_mul_f32_e32 v101, 0xbfb8aa3b, v123
	v_rndne_f32_e32 v103, v101
	v_sub_f32_e32 v112, v101, v103
	v_fma_f32 v101, v123, s54, -v101
	v_fmac_f32_e32 v101, 0xb2a5705f, v123
	v_add_f32_e32 v101, v112, v101
	v_exp_f32_e32 v101, v101
	v_cvt_i32_f32_e32 v103, v103
	v_ldexp_f32 v101, v101, v103
	s_nop 0
	s_nop 1
	v_pk_add_f32 v[100:101], v[100:101], 1.0 op_sel_hi:[1,0]
	s_nop 0
	v_div_scale_f32 v103, s[30:31], v100, v100, 1.0
	v_rcp_f32_e32 v112, v103
	s_nop 0
	v_fma_f32 v113, -v103, v112, 1.0
	v_fmac_f32_e32 v112, v113, v112
	v_div_scale_f32 v113, vcc, 1.0, v100, 1.0
	v_mul_f32_e32 v114, v113, v112
	v_fma_f32 v115, -v103, v114, v113
	v_fmac_f32_e32 v114, v115, v112
	v_fma_f32 v103, -v103, v114, v113
	v_div_fmas_f32 v103, v103, v112, v114
	v_div_fixup_f32 v100, v103, v100, 1.0
	v_div_scale_f32 v103, s[30:31], v101, v101, 1.0
	v_rcp_f32_e32 v112, v103
	s_nop 0
	v_fma_f32 v113, -v103, v112, 1.0
	v_fmac_f32_e32 v112, v113, v112
	v_div_scale_f32 v113, vcc, 1.0, v101, 1.0
	v_mul_f32_e32 v114, v113, v112
	v_fma_f32 v115, -v103, v114, v113
	v_fmac_f32_e32 v114, v115, v112
	v_fma_f32 v103, -v103, v114, v113
	v_div_fmas_f32 v103, v103, v112, v114
	v_div_fixup_f32 v101, v103, v101, 1.0
	v_mul_f32_e32 v103, 0xbfb8aa3b, v107
	v_rndne_f32_e32 v112, v103
	v_sub_f32_e32 v113, v103, v112
	v_fma_f32 v103, v107, s54, -v103
	v_fmac_f32_e32 v103, 0xb2a5705f, v107
	v_add_f32_e32 v103, v113, v103
	v_exp_f32_e32 v103, v103
	v_cvt_i32_f32_e32 v112, v112
	v_ldexp_f32 v103, v103, v112
	s_nop 0
	s_nop 1
	v_pk_add_f32 v[102:103], v[102:103], 1.0 op_sel_hi:[1,0]
	s_nop 0
	v_div_scale_f32 v112, s[30:31], v102, v102, 1.0
	v_rcp_f32_e32 v113, v112
	s_nop 0
	v_fma_f32 v114, -v112, v113, 1.0
	v_fmac_f32_e32 v113, v114, v113
	v_div_scale_f32 v114, vcc, 1.0, v102, 1.0
	v_mul_f32_e32 v115, v114, v113
	v_fma_f32 v116, -v112, v115, v114
	v_fmac_f32_e32 v115, v116, v113
	v_fma_f32 v112, -v112, v115, v114
	v_div_fmas_f32 v112, v112, v113, v115
	v_div_fixup_f32 v102, v112, v102, 1.0
	v_div_scale_f32 v112, s[30:31], v103, v103, 1.0
	v_rcp_f32_e32 v113, v112
	s_nop 0
	v_fma_f32 v114, -v112, v113, 1.0
	v_fmac_f32_e32 v113, v114, v113
	v_div_scale_f32 v114, vcc, 1.0, v103, 1.0
	v_mul_f32_e32 v115, v114, v113
	v_fma_f32 v116, -v112, v115, v114
	v_fmac_f32_e32 v115, v116, v113
	v_fma_f32 v112, -v112, v115, v114
	v_div_fmas_f32 v112, v112, v113, v115
	v_div_fixup_f32 v103, v112, v103, 1.0

; DEVI float sigmf(float x) { return 1.f / (1.f + expf(-x)); }
; DEVI void lds_put4(char* wl, int RS, int row, int col, float a, float b, float c, float d) { u32x2 w = {cvtpk(a, b), cvtpk(c, d)}; *(u32x2*)(wl + row * RS + col * 2) = w; }
; DEVI void phase_gemm_in(const Params& p, int l, char* lds) {
;     ...
;           if (mode == 1) {
; #pragma unroll
;             for (int j = 0; j < 4; ++j) { x1[j] *= 0.08838834764831845f; x2[j] *= 0.08838834764831845f; }
;           } else if (mode == 2) {
;             if (rr_of(m) < SEQ) {
;               const f32x4 cs = *(const f32x4*)(rope + (long)rr_of(m) * 64 + ci);
;               const f32x4 sn = *(const f32x4*)(rope + (long)rr_of(m) * 64 + 32 + ci);
; #pragma unroll
;               for (int j = 0; j < 4; ++j) { const float a = x1[j], bb = x2[j]; x1[j] = a * cs[j] - bb * sn[j]; x2[j] = a * sn[j] + bb * cs[j]; }
;             }
;           } else if (mode == 3) {
; #pragma unroll
;             for (int j = 0; j < 4; ++j) { x1[j] = sigmf(x1[j]); x2[j] = sigmf(x2[j]); }
;           }
;           lds_put4(wl, 272, mi * 32 + r32, cg2 * 64 + ci, x1[0], x1[1], x1[2], x1[3]);
.LBB0_175:
	s_andn2_saveexec_b64 s[8:9], s[8:9]
	v_pk_mul_f32 v[96:97], v[120:121], s[96:97] op_sel_hi:[1,0]
	v_pk_mul_f32 v[98:99], v[104:105], s[96:97] op_sel_hi:[1,0]
	v_pk_mul_f32 v[100:101], v[122:123], s[96:97] op_sel_hi:[1,0]
	v_pk_mul_f32 v[102:103], v[106:107], s[96:97] op_sel_hi:[1,0]
	s_or_b64 exec, exec, s[8:9]
	v_cvt_pk_bf16_f32 v96, v96, v97
	v_cvt_pk_bf16_f32 v97, v100, v101
	v_cvt_pk_bf16_f32 v98, v98, v99
	v_cvt_pk_bf16_f32 v99, v102, v103
	ds_write2_b64 v224, v[96:97], v[98:99] offset1:8
	s_and_saveexec_b64 s[8:9], s[10:11]
	s_xor_b64 s[8:9], exec, s[8:9]
	s_cbranch_execz .LBB0_187
	s_and_saveexec_b64 s[14:15], s[12:13]
	s_xor_b64 s[14:15], exec, s[14:15]
	s_cbranch_execz .LBB0_182
	s_and_saveexec_b64 s[28:29], s[2:3]
	s_cbranch_execz .LBB0_181
	v_mul_f32_e32 v96, 0xbfb8aa3b, v124
	v_rndne_f32_e32 v97, v96
	v_sub_f32_e32 v98, v96, v97
	v_fma_f32 v96, v124, s54, -v96
	v_fmac_f32_e32 v96, 0xb2a5705f, v124
	v_add_f32_e32 v96, v98, v96
	v_exp_f32_e32 v96, v96
	v_cvt_i32_f32_e32 v97, v97
	v_ldexp_f32 v96, v96, v97
	v_mul_f32_e32 v97, 0xbfb8aa3b, v108
	v_rndne_f32_e32 v98, v97
	v_sub_f32_e32 v99, v97, v98
	v_fma_f32 v97, v108, s54, -v97
	v_fmac_f32_e32 v97, 0xb2a5705f, v108
	v_add_f32_e32 v97, v99, v97
	v_exp_f32_e32 v97, v97
	v_cvt_i32_f32_e32 v98, v98
	v_ldexp_f32 v97, v97, v98
	s_nop 0
	s_nop 1
	s_nop 1
	v_mov_b32_e32 v98, v97
	v_mul_f32_e32 v97, 0xbfb8aa3b, v125
	v_rndne_f32_e32 v99, v97
	v_sub_f32_e32 v100, v97, v99
	v_fma_f32 v97, v125, s54, -v97
	v_fmac_f32_e32 v97, 0xb2a5705f, v125
	v_add_f32_e32 v97, v100, v97
	v_exp_f32_e32 v97, v97
	v_cvt_i32_f32_e32 v99, v99
	v_ldexp_f32 v97, v97, v99
	s_nop 0
	s_nop 1
	v_pk_add_f32 v[96:97], v[96:97], 1.0 op_sel_hi:[1,0]
	s_nop 0
	v_div_scale_f32 v99, s[30:31], v96, v96, 1.0
	v_rcp_f32_e32 v100, v99
	s_nop 0
	v_fma_f32 v101, -v99, v100, 1.0
	v_fmac_f32_e32 v100, v101, v100
	v_div_scale_f32 v101, vcc, 1.0, v96, 1.0
	v_mul_f32_e32 v102, v101, v100
	v_fma_f32 v103, -v99, v102, v101
	v_fmac_f32_e32 v102, v103, v100
	v_fma_f32 v99, -v99, v102, v101
	v_div_fmas_f32 v99, v99, v100, v102
	v_div_fixup_f32 v124, v99, v96, 1.0
	v_div_scale_f32 v96, s[30:31], v97, v97, 1.0
	v_rcp_f32_e32 v99, v96
	s_nop 0
	v_fma_f32 v100, -v96, v99, 1.0
	v_fmac_f32_e32 v99, v100, v99
	v_div_scale_f32 v100, vcc, 1.0, v97, 1.0
	v_mul_f32_e32 v101, v100, v99
	v_fma_f32 v102, -v96, v101, v100
	v_fmac_f32_e32 v101, v102, v99
	v_fma_f32 v96, -v96, v101, v100
	v_div_fmas_f32 v96, v96, v99, v101
	v_div_fixup_f32 v125, v96, v97, 1.0
	v_mul_f32_e32 v96, 0xbfb8aa3b, v109
	v_rndne_f32_e32 v97, v96
	v_sub_f32_e32 v99, v96, v97
	v_fma_f32 v96, v109, s54, -v96
	v_fmac_f32_e32 v96, 0xb2a5705f, v109
	v_add_f32_e32 v96, v99, v96
	v_exp_f32_e32 v96, v96
	v_cvt_i32_f32_e32 v97, v97
	v_ldexp_f32 v96, v96, v97
	s_nop 0
	s_nop 1
	v_mov_b32_e32 v99, v96
	v_pk_add_f32 v[96:97], v[98:99], 1.0 op_sel_hi:[1,0]
	s_nop 0
	v_div_scale_f32 v98, s[30:31], v96, v96, 1.0
	v_rcp_f32_e32 v99, v98
	s_nop 0
	v_fma_f32 v100, -v98, v99, 1.0
	v_fmac_f32_e32 v99, v100, v99
	v_div_scale_f32 v100, vcc, 1.0, v96, 1.0
	v_mul_f32_e32 v101, v100, v99
	v_fma_f32 v102, -v98, v101, v100
	v_fmac_f32_e32 v101, v102, v99
	v_fma_f32 v98, -v98, v101, v100
	v_div_fmas_f32 v98, v98, v99, v101
	v_div_fixup_f32 v108, v98, v96, 1.0
	v_div_scale_f32 v96, s[30:31], v97, v97, 1.0
	v_rcp_f32_e32 v98, v96
	s_nop 0
	v_fma_f32 v99, -v96, v98, 1.0
	v_fmac_f32_e32 v98, v99, v98
	v_div_scale_f32 v99, vcc, 1.0, v97, 1.0
	v_mul_f32_e32 v100, v99, v98
	v_fma_f32 v101, -v96, v100, v99
	v_fmac_f32_e32 v100, v101, v98
	v_fma_f32 v96, -v96, v100, v99
	v_div_fmas_f32 v96, v96, v98, v100
	v_div_fixup_f32 v109, v96, v97, 1.0
	v_mul_f32_e32 v96, 0xbfb8aa3b, v126
	v_rndne_f32_e32 v97, v96
	v_sub_f32_e32 v98, v96, v97
	v_fma_f32 v96, v126, s54, -v96
	v_fmac_f32_e32 v96, 0xb2a5705f, v126
	v_add_f32_e32 v96, v98, v96
	v_exp_f32_e32 v96, v96
	v_cvt_i32_f32_e32 v97, v97
	v_ldexp_f32 v96, v96, v97
	v_mul_f32_e32 v97, 0xbfb8aa3b, v110
	v_rndne_f32_e32 v98, v97
	v_sub_f32_e32 v99, v97, v98
	v_fma_f32 v97, v110, s54, -v97
	v_fmac_f32_e32 v97, 0xb2a5705f, v110
	v_add_f32_e32 v97, v99, v97
	v_exp_f32_e32 v97, v97
	v_cvt_i32_f32_e32 v98, v98
	v_ldexp_f32 v97, v97, v98
	s_nop 0
	s_nop 1
	s_nop 1
	v_mov_b32_e32 v98, v97
	v_mul_f32_e32 v97, 0xbfb8aa3b, v127
	v_rndne_f32_e32 v99, v97
	v_sub_f32_e32 v100, v97, v99
	v_fma_f32 v97, v127, s54, -v97
	v_fmac_f32_e32 v97, 0xb2a5705f, v127
	v_add_f32_e32 v97, v100, v97
	v_exp_f32_e32 v97, v97
	v_cvt_i32_f32_e32 v99, v99
	v_ldexp_f32 v97, v97, v99
	s_nop 0
	s_nop 1
	v_pk_add_f32 v[96:97], v[96:97], 1.0 op_sel_hi:[1,0]
	s_nop 0
	v_div_scale_f32 v99, s[30:31], v96, v96, 1.0
	v_rcp_f32_e32 v100, v99
	s_nop 0
	v_fma_f32 v101, -v99, v100, 1.0
	v_fmac_f32_e32 v100, v101, v100
	v_div_scale_f32 v101, vcc, 1.0, v96, 1.0
	v_mul_f32_e32 v102, v101, v100
	v_fma_f32 v103, -v99, v102, v101
	v_fmac_f32_e32 v102, v103, v100
	v_fma_f32 v99, -v99, v102, v101
	v_div_fmas_f32 v99, v99, v100, v102
	v_div_fixup_f32 v126, v99, v96, 1.0
	v_div_scale_f32 v96, s[30:31], v97, v97, 1.0
	v_rcp_f32_e32 v99, v96
	s_nop 0
	v_fma_f32 v100, -v96, v99, 1.0
	v_fmac_f32_e32 v99, v100, v99
	v_div_scale_f32 v100, vcc, 1.0, v97, 1.0
	v_mul_f32_e32 v101, v100, v99
	v_fma_f32 v102, -v96, v101, v100
	v_fmac_f32_e32 v101, v102, v99
	v_fma_f32 v96, -v96, v101, v100
	v_div_fmas_f32 v96, v96, v99, v101
	v_div_fixup_f32 v127, v96, v97, 1.0
	v_mul_f32_e32 v96, 0xbfb8aa3b, v111
	v_rndne_f32_e32 v97, v96
	v_sub_f32_e32 v99, v96, v97
	v_fma_f32 v96, v111, s54, -v96
	v_fmac_f32_e32 v96, 0xb2a5705f, v111
	v_add_f32_e32 v96, v99, v96
	v_exp_f32_e32 v96, v96
	v_cvt_i32_f32_e32 v97, v97
	v_ldexp_f32 v96, v96, v97
	s_nop 0
	s_nop 1
	v_mov_b32_e32 v99, v96
	v_pk_add_f32 v[96:97], v[98:99], 1.0 op_sel_hi:[1,0]
	s_nop 0
	v_div_scale_f32 v98, s[30:31], v96, v96, 1.0
	v_rcp_f32_e32 v99, v98
	s_nop 0
	v_fma_f32 v100, -v98, v99, 1.0
	v_fmac_f32_e32 v99, v100, v99
	v_div_scale_f32 v100, vcc, 1.0, v96, 1.0
	v_mul_f32_e32 v101, v100, v99
	v_fma_f32 v102, -v98, v101, v100
	v_fmac_f32_e32 v101, v102, v99
	v_fma_f32 v98, -v98, v101, v100
	v_div_fmas_f32 v98, v98, v99, v101
	v_div_fixup_f32 v110, v98, v96, 1.0
	v_div_scale_f32 v96, s[30:31], v97, v97, 1.0
	v_rcp_f32_e32 v98, v96
	s_nop 0
	v_fma_f32 v99, -v96, v98, 1.0
	v_fmac_f32_e32 v98, v99, v98
	v_div_scale_f32 v99, vcc, 1.0, v97, 1.0
	v_mul_f32_e32 v100, v99, v98
	v_fma_f32 v101, -v96, v100, v99
	v_fmac_f32_e32 v100, v101, v98
	v_fma_f32 v96, -v96, v100, v99
	v_div_fmas_f32 v96, v96, v98, v100
	v_div_fixup_f32 v111, v96, v97, 1.0

; DEVI void phase_gemm_in(const Params& p, int l, char* lds) {
;     ...
;       for (int mi = 0; mi < 2; ++mi) {
;         const int m = m0 + wm * 64 + mi * 32 + r32;
; #pragma unroll
;         for (int q = 0; q < 4; ++q) {
;           const int ci = q * 8 + hi * 4;
;           float x1[4], x2[4];
; #pragma unroll
;           for (int j = 0; j < 4; ++j) { x1[j] = acc[2 * cg2][mi][q * 4 + j]; x2[j] = acc[2 * cg2 + 1][mi][q * 4 + j]; }
;           if (mode == 1) {
; #pragma unroll
;             for (int j = 0; j < 4; ++j) { x1[j] *= 0.08838834764831845f; x2[j] *= 0.08838834764831845f; }
;           } else if (mode == 2) {
;             if (rr_of(m) < SEQ) {
;               const f32x4 cs = *(const f32x4*)(rope + (long)rr_of(m) * 64 + ci);
.LBB0_187:
	s_andn2_saveexec_b64 s[8:9], s[8:9]
	v_pk_mul_f32 v[124:125], v[124:125], s[96:97] op_sel_hi:[1,0]
	v_pk_mul_f32 v[108:109], v[108:109], s[96:97] op_sel_hi:[1,0]
	v_pk_mul_f32 v[126:127], v[126:127], s[96:97] op_sel_hi:[1,0]
	v_pk_mul_f32 v[110:111], v[110:111], s[96:97] op_sel_hi:[1,0]
	s_or_b64 exec, exec, s[8:9]
	v_cvt_pk_bf16_f32 v96, v124, v125
	v_cvt_pk_bf16_f32 v97, v126, v127
	v_cvt_pk_bf16_f32 v98, v108, v109
	v_cvt_pk_bf16_f32 v99, v110, v111
	ds_write2_b64 v225, v[96:97], v[98:99] offset1:8
	v_or_b32_e32 v96, 32, v139
	v_add_u32_e32 v97, 0xffffdf20, v139
	v_cmp_lt_i32_e32 vcc, s53, v96
	v_readlane_b32 s14, v252, 45
	v_readlane_b32 s15, v252, 46
	v_cndmask_b32_e32 v96, v96, v97, vcc
	v_ashrrev_i32_e32 v97, 31, v96
	v_cmp_gt_i32_e64 s[8:9], s95, v96
	v_lshlrev_b64 v[96:97], 8, v[96:97]
	v_lshl_add_u64 v[96:97], s[14:15], 0, v[96:97]
	s_and_saveexec_b64 s[14:15], s[10:11]
	s_xor_b64 s[14:15], exec, s[14:15]
	s_cbranch_execz .LBB0_199
	s_and_saveexec_b64 s[28:29], s[12:13]
	s_xor_b64 s[28:29], exec, s[28:29]
	s_cbranch_execz .LBB0_194
	v_mov_b32_e32 v103, v83
	v_mov_b32_e32 v102, v82
	v_mov_b32_e32 v99, v81
	v_mov_b32_e32 v98, v80
	v_mov_b32_e32 v105, v67
	v_mov_b32_e32 v104, v66
	v_mov_b32_e32 v101, v65
	v_mov_b32_e32 v100, v64
	s_and_saveexec_b64 s[30:31], s[2:3]
	s_cbranch_execz .LBB0_193
; DEVI float sigmf(float x) { return 1.f / (1.f + expf(-x)); }
; DEVI void phase_gemm_in(const Params& p, int l, char* lds) {
;     ...
;           } else if (mode == 3) {
; #pragma unroll
;             for (int j = 0; j < 4; ++j) { x1[j] = sigmf(x1[j]); x2[j] = sigmf(x2[j]); }
;           }
	v_mul_f32_e32 v98, 0xbfb8aa3b, v80
	v_rndne_f32_e32 v99, v98
	v_sub_f32_e32 v100, v98, v99
	v_fma_f32 v98, v80, s54, -v98
	v_fmac_f32_e32 v98, 0xb2a5705f, v80
	v_add_f32_e32 v98, v100, v98
	v_exp_f32_e32 v98, v98
	v_cvt_i32_f32_e32 v99, v99
	v_ldexp_f32 v98, v98, v99
	v_mul_f32_e32 v99, 0xbfb8aa3b, v64
	v_rndne_f32_e32 v100, v99
	v_sub_f32_e32 v101, v99, v100
	v_fma_f32 v99, v64, s54, -v99
	v_fmac_f32_e32 v99, 0xb2a5705f, v64
	v_add_f32_e32 v99, v101, v99
	v_exp_f32_e32 v99, v99
	v_cvt_i32_f32_e32 v100, v100
	v_ldexp_f32 v99, v99, v100
	s_nop 0
	s_nop 1
	s_nop 1
	v_mov_b32_e32 v100, v99
	v_mul_f32_e32 v99, 0xbfb8aa3b, v81
	v_rndne_f32_e32 v101, v99
	v_sub_f32_e32 v102, v99, v101
	v_fma_f32 v99, v81, s54, -v99
	v_fmac_f32_e32 v99, 0xb2a5705f, v81
	v_add_f32_e32 v99, v102, v99
	v_exp_f32_e32 v99, v99
	v_cvt_i32_f32_e32 v101, v101
	v_ldexp_f32 v99, v99, v101
	s_nop 0
	s_nop 1
	v_pk_add_f32 v[98:99], v[98:99], 1.0 op_sel_hi:[1,0]
	s_nop 0
	v_div_scale_f32 v101, s[42:43], v98, v98, 1.0
	v_rcp_f32_e32 v102, v101
	s_nop 0
	v_fma_f32 v103, -v101, v102, 1.0
	v_fmac_f32_e32 v102, v103, v102
	v_div_scale_f32 v103, vcc, 1.0, v98, 1.0
	v_mul_f32_e32 v104, v103, v102
	v_fma_f32 v105, -v101, v104, v103
	v_fmac_f32_e32 v104, v105, v102
	v_fma_f32 v101, -v101, v104, v103
	v_div_fmas_f32 v101, v101, v102, v104
	v_div_fixup_f32 v98, v101, v98, 1.0
	v_div_scale_f32 v101, s[42:43], v99, v99, 1.0
	v_rcp_f32_e32 v102, v101
	s_nop 0
	v_fma_f32 v103, -v101, v102, 1.0
	v_fmac_f32_e32 v102, v103, v102
	v_div_scale_f32 v103, vcc, 1.0, v99, 1.0
	v_mul_f32_e32 v104, v103, v102
	v_fma_f32 v105, -v101, v104, v103
	v_fmac_f32_e32 v104, v105, v102
	v_fma_f32 v101, -v101, v104, v103
	v_div_fmas_f32 v101, v101, v102, v104
	v_div_fixup_f32 v99, v101, v99, 1.0
	v_mul_f32_e32 v101, 0xbfb8aa3b, v65
	v_rndne_f32_e32 v102, v101
	v_sub_f32_e32 v103, v101, v102
	v_fma_f32 v101, v65, s54, -v101
	v_fmac_f32_e32 v101, 0xb2a5705f, v65
	v_add_f32_e32 v101, v103, v101
	v_exp_f32_e32 v101, v101
	v_cvt_i32_f32_e32 v102, v102
	v_ldexp_f32 v101, v101, v102
	s_nop 0
	s_nop 1
	v_pk_add_f32 v[100:101], v[100:101], 1.0 op_sel_hi:[1,0]
	s_nop 0
	v_div_scale_f32 v102, s[42:43], v100, v100, 1.0
	v_rcp_f32_e32 v103, v102
	s_nop 0
	v_fma_f32 v104, -v102, v103, 1.0
	v_fmac_f32_e32 v103, v104, v103
	v_div_scale_f32 v104, vcc, 1.0, v100, 1.0
	v_mul_f32_e32 v105, v104, v103
	v_fma_f32 v106, -v102, v105, v104
	v_fmac_f32_e32 v105, v106, v103
	v_fma_f32 v102, -v102, v105, v104
	v_div_fmas_f32 v102, v102, v103, v105
	v_div_fixup_f32 v100, v102, v100, 1.0
	v_div_scale_f32 v102, s[42:43], v101, v101, 1.0
	v_rcp_f32_e32 v103, v102
	s_nop 0
	v_fma_f32 v104, -v102, v103, 1.0
	v_fmac_f32_e32 v103, v104, v103
	v_div_scale_f32 v104, vcc, 1.0, v101, 1.0
	v_mul_f32_e32 v105, v104, v103
	v_fma_f32 v106, -v102, v105, v104
	v_fmac_f32_e32 v105, v106, v103
	v_fma_f32 v102, -v102, v105, v104
	v_div_fmas_f32 v102, v102, v103, v105
	v_div_fixup_f32 v101, v102, v101, 1.0
	v_mul_f32_e32 v102, 0xbfb8aa3b, v82
	v_rndne_f32_e32 v103, v102
	v_sub_f32_e32 v104, v102, v103
	v_fma_f32 v102, v82, s54, -v102
	v_fmac_f32_e32 v102, 0xb2a5705f, v82
	v_add_f32_e32 v102, v104, v102
	v_exp_f32_e32 v102, v102
	v_cvt_i32_f32_e32 v103, v103
	v_ldexp_f32 v102, v102, v103
	v_mul_f32_e32 v103, 0xbfb8aa3b, v66
	v_rndne_f32_e32 v104, v103
	v_sub_f32_e32 v105, v103, v104
	v_fma_f32 v103, v66, s54, -v103
	v_fmac_f32_e32 v103, 0xb2a5705f, v66
	v_add_f32_e32 v103, v105, v103
	v_exp_f32_e32 v103, v103
	v_cvt_i32_f32_e32 v104, v104
	v_ldexp_f32 v103, v103, v104
	s_nop 0
	s_nop 1
	s_nop 1
	v_mov_b32_e32 v104, v103
	v_mul_f32_e32 v103, 0xbfb8aa3b, v83
	v_rndne_f32_e32 v105, v103
	v_sub_f32_e32 v106, v103, v105
	v_fma_f32 v103, v83, s54, -v103
	v_fmac_f32_e32 v103, 0xb2a5705f, v83
	v_add_f32_e32 v103, v106, v103
	v_exp_f32_e32 v103, v103
	v_cvt_i32_f32_e32 v105, v105
	v_ldexp_f32 v103, v103, v105
	s_nop 0
	s_nop 1
	v_pk_add_f32 v[102:103], v[102:103], 1.0 op_sel_hi:[1,0]
	s_nop 0
	v_div_scale_f32 v105, s[42:43], v102, v102, 1.0
	v_rcp_f32_e32 v106, v105
	s_nop 0
	v_fma_f32 v107, -v105, v106, 1.0
	v_fmac_f32_e32 v106, v107, v106
	v_div_scale_f32 v107, vcc, 1.0, v102, 1.0
	v_mul_f32_e32 v108, v107, v106
	v_fma_f32 v109, -v105, v108, v107
	v_fmac_f32_e32 v108, v109, v106
	v_fma_f32 v105, -v105, v108, v107
	v_div_fmas_f32 v105, v105, v106, v108
	v_div_fixup_f32 v102, v105, v102, 1.0
	v_div_scale_f32 v105, s[42:43], v103, v103, 1.0
	v_rcp_f32_e32 v106, v105
	s_nop 0
	v_fma_f32 v107, -v105, v106, 1.0
	v_fmac_f32_e32 v106, v107, v106
	v_div_scale_f32 v107, vcc, 1.0, v103, 1.0
	v_mul_f32_e32 v108, v107, v106
	v_fma_f32 v109, -v105, v108, v107
	v_fmac_f32_e32 v108, v109, v106
	v_fma_f32 v105, -v105, v108, v107
	v_div_fmas_f32 v105, v105, v106, v108
	v_div_fixup_f32 v103, v105, v103, 1.0
	v_mul_f32_e32 v105, 0xbfb8aa3b, v67
	v_rndne_f32_e32 v106, v105
	v_sub_f32_e32 v107, v105, v106
	v_fma_f32 v105, v67, s54, -v105
	v_fmac_f32_e32 v105, 0xb2a5705f, v67
	v_add_f32_e32 v105, v107, v105
	v_exp_f32_e32 v105, v105
	v_cvt_i32_f32_e32 v106, v106
	v_ldexp_f32 v105, v105, v106
	s_nop 0
	s_nop 1
	v_pk_add_f32 v[104:105], v[104:105], 1.0 op_sel_hi:[1,0]
	s_nop 0
	v_div_scale_f32 v106, s[42:43], v104, v104, 1.0
	v_rcp_f32_e32 v107, v106
	s_nop 0
	v_fma_f32 v108, -v106, v107, 1.0
	v_fmac_f32_e32 v107, v108, v107
	v_div_scale_f32 v108, vcc, 1.0, v104, 1.0
	v_mul_f32_e32 v109, v108, v107
	v_fma_f32 v110, -v106, v109, v108
	v_fmac_f32_e32 v109, v110, v107
	v_fma_f32 v106, -v106, v109, v108
	v_div_fmas_f32 v106, v106, v107, v109
	v_div_fixup_f32 v104, v106, v104, 1.0
	v_div_scale_f32 v106, s[42:43], v105, v105, 1.0
	v_rcp_f32_e32 v107, v106
	s_nop 0
	v_fma_f32 v108, -v106, v107, 1.0
	v_fmac_f32_e32 v107, v108, v107
	v_div_scale_f32 v108, vcc, 1.0, v105, 1.0
	v_mul_f32_e32 v109, v108, v107
	v_fma_f32 v110, -v106, v109, v108
	v_fmac_f32_e32 v109, v110, v107
	v_fma_f32 v106, -v106, v109, v108
	v_div_fmas_f32 v106, v106, v107, v109
	v_div_fixup_f32 v105, v106, v105, 1.0

; DEVI float sigmf(float x) { return 1.f / (1.f + expf(-x)); }
; DEVI void lds_put4(char* wl, int RS, int row, int col, float a, float b, float c, float d) { u32x2 w = {cvtpk(a, b), cvtpk(c, d)}; *(u32x2*)(wl + row * RS + col * 2) = w; }
; DEVI void phase_gemm_in(const Params& p, int l, char* lds) {
;     ...
;           if (mode == 1) {
; #pragma unroll
;             for (int j = 0; j < 4; ++j) { x1[j] *= 0.08838834764831845f; x2[j] *= 0.08838834764831845f; }
;           } else if (mode == 2) {
;             if (rr_of(m) < SEQ) {
;               const f32x4 cs = *(const f32x4*)(rope + (long)rr_of(m) * 64 + ci);
;               const f32x4 sn = *(const f32x4*)(rope + (long)rr_of(m) * 64 + 32 + ci);
; #pragma unroll
;               for (int j = 0; j < 4; ++j) { const float a = x1[j], bb = x2[j]; x1[j] = a * cs[j] - bb * sn[j]; x2[j] = a * sn[j] + bb * cs[j]; }
;             }
;           } else if (mode == 3) {
; #pragma unroll
;             for (int j = 0; j < 4; ++j) { x1[j] = sigmf(x1[j]); x2[j] = sigmf(x2[j]); }
;           }
;           lds_put4(wl, 272, mi * 32 + r32, cg2 * 64 + ci, x1[0], x1[1], x1[2], x1[3]);
.LBB0_199:
	s_andn2_saveexec_b64 s[14:15], s[14:15]
	v_pk_mul_f32 v[98:99], v[80:81], s[96:97] op_sel_hi:[1,0]
	v_pk_mul_f32 v[100:101], v[64:65], s[96:97] op_sel_hi:[1,0]
	v_pk_mul_f32 v[102:103], v[82:83], s[96:97] op_sel_hi:[1,0]
	v_pk_mul_f32 v[104:105], v[66:67], s[96:97] op_sel_hi:[1,0]
	s_or_b64 exec, exec, s[14:15]
	v_cvt_pk_bf16_f32 v64, v98, v99
	v_cvt_pk_bf16_f32 v65, v102, v103
	v_cvt_pk_bf16_f32 v66, v100, v101
	v_cvt_pk_bf16_f32 v67, v104, v105
	v_add_u32_e32 v98, 0x2000, v130
	ds_write2_b64 v98, v[64:65], v[66:67] offset0:64 offset1:72
	s_and_saveexec_b64 s[14:15], s[10:11]
	s_xor_b64 s[14:15], exec, s[14:15]
	s_cbranch_execz .LBB0_211
	s_and_saveexec_b64 s[28:29], s[12:13]
	s_xor_b64 s[28:29], exec, s[28:29]
	s_cbranch_execz .LBB0_206
	v_mov_b32_e32 v81, v87
	v_mov_b32_e32 v80, v86
	v_mov_b32_e32 v65, v85
	v_mov_b32_e32 v64, v84
	v_mov_b32_e32 v83, v71
	v_mov_b32_e32 v82, v70
	v_mov_b32_e32 v67, v69
	v_mov_b32_e32 v66, v68
	s_and_saveexec_b64 s[30:31], s[2:3]
	s_cbranch_execz .LBB0_205
	v_mul_f32_e32 v64, 0xbfb8aa3b, v84
	v_rndne_f32_e32 v65, v64
	v_sub_f32_e32 v66, v64, v65
	v_fma_f32 v64, v84, s54, -v64
	v_fmac_f32_e32 v64, 0xb2a5705f, v84
	v_add_f32_e32 v64, v66, v64
	v_exp_f32_e32 v64, v64
	v_cvt_i32_f32_e32 v65, v65
	v_ldexp_f32 v64, v64, v65
	v_mul_f32_e32 v65, 0xbfb8aa3b, v68
	v_rndne_f32_e32 v66, v65
	v_sub_f32_e32 v67, v65, v66
	v_fma_f32 v65, v68, s54, -v65
	v_fmac_f32_e32 v65, 0xb2a5705f, v68
	v_add_f32_e32 v65, v67, v65
	v_exp_f32_e32 v65, v65
	v_cvt_i32_f32_e32 v66, v66
	v_ldexp_f32 v65, v65, v66
	s_nop 0
	s_nop 1
	s_nop 1
	v_mov_b32_e32 v66, v65
	v_mul_f32_e32 v65, 0xbfb8aa3b, v85
	v_rndne_f32_e32 v67, v65
	v_sub_f32_e32 v80, v65, v67
	v_fma_f32 v65, v85, s54, -v65
	v_fmac_f32_e32 v65, 0xb2a5705f, v85
	v_add_f32_e32 v65, v80, v65
	v_exp_f32_e32 v65, v65
	v_cvt_i32_f32_e32 v67, v67
	v_ldexp_f32 v65, v65, v67
	s_nop 0
	s_nop 1
	v_pk_add_f32 v[64:65], v[64:65], 1.0 op_sel_hi:[1,0]
	s_nop 0
	v_div_scale_f32 v67, s[42:43], v64, v64, 1.0
	v_rcp_f32_e32 v80, v67
	s_nop 0
	v_fma_f32 v81, -v67, v80, 1.0
	v_fmac_f32_e32 v80, v81, v80
	v_div_scale_f32 v81, vcc, 1.0, v64, 1.0
	v_mul_f32_e32 v82, v81, v80
	v_fma_f32 v83, -v67, v82, v81
	v_fmac_f32_e32 v82, v83, v80
	v_fma_f32 v67, -v67, v82, v81
	v_div_fmas_f32 v67, v67, v80, v82
	v_div_fixup_f32 v64, v67, v64, 1.0
	v_div_scale_f32 v67, s[42:43], v65, v65, 1.0
	v_rcp_f32_e32 v80, v67
	s_nop 0
	v_fma_f32 v81, -v67, v80, 1.0
	v_fmac_f32_e32 v80, v81, v80
	v_div_scale_f32 v81, vcc, 1.0, v65, 1.0
	v_mul_f32_e32 v82, v81, v80
	v_fma_f32 v83, -v67, v82, v81
	v_fmac_f32_e32 v82, v83, v80
	v_fma_f32 v67, -v67, v82, v81
	v_div_fmas_f32 v67, v67, v80, v82
	v_div_fixup_f32 v65, v67, v65, 1.0
	v_mul_f32_e32 v67, 0xbfb8aa3b, v69
	v_rndne_f32_e32 v80, v67
	v_sub_f32_e32 v81, v67, v80
	v_fma_f32 v67, v69, s54, -v67
	v_fmac_f32_e32 v67, 0xb2a5705f, v69
	v_add_f32_e32 v67, v81, v67
	v_exp_f32_e32 v67, v67
	v_cvt_i32_f32_e32 v80, v80
	v_ldexp_f32 v67, v67, v80
	s_nop 0
	s_nop 1
	v_pk_add_f32 v[66:67], v[66:67], 1.0 op_sel_hi:[1,0]
	s_nop 0
	v_div_scale_f32 v80, s[42:43], v66, v66, 1.0
	v_rcp_f32_e32 v81, v80
	s_nop 0
	v_fma_f32 v82, -v80, v81, 1.0
	v_fmac_f32_e32 v81, v82, v81
	v_div_scale_f32 v82, vcc, 1.0, v66, 1.0
	v_mul_f32_e32 v83, v82, v81
	v_fma_f32 v99, -v80, v83, v82
	v_fmac_f32_e32 v83, v99, v81
	v_fma_f32 v80, -v80, v83, v82
	v_div_fmas_f32 v80, v80, v81, v83
	v_div_fixup_f32 v66, v80, v66, 1.0
	v_div_scale_f32 v80, s[42:43], v67, v67, 1.0
	v_rcp_f32_e32 v81, v80
	s_nop 0
	v_fma_f32 v82, -v80, v81, 1.0
	v_fmac_f32_e32 v81, v82, v81
	v_div_scale_f32 v82, vcc, 1.0, v67, 1.0
	v_mul_f32_e32 v83, v82, v81
	v_fma_f32 v99, -v80, v83, v82
	v_fmac_f32_e32 v83, v99, v81
	v_fma_f32 v80, -v80, v83, v82
	v_div_fmas_f32 v80, v80, v81, v83
	v_div_fixup_f32 v67, v80, v67, 1.0
	v_mul_f32_e32 v80, 0xbfb8aa3b, v86
	v_rndne_f32_e32 v81, v80
	v_sub_f32_e32 v82, v80, v81
	v_fma_f32 v80, v86, s54, -v80
	v_fmac_f32_e32 v80, 0xb2a5705f, v86
	v_add_f32_e32 v80, v82, v80
	v_exp_f32_e32 v80, v80
	v_cvt_i32_f32_e32 v81, v81
	v_ldexp_f32 v80, v80, v81
	v_mul_f32_e32 v81, 0xbfb8aa3b, v70
	v_rndne_f32_e32 v82, v81
	v_sub_f32_e32 v83, v81, v82
	v_fma_f32 v81, v70, s54, -v81
	v_fmac_f32_e32 v81, 0xb2a5705f, v70
	v_add_f32_e32 v81, v83, v81
	v_exp_f32_e32 v81, v81
	v_cvt_i32_f32_e32 v82, v82
	v_ldexp_f32 v81, v81, v82
	s_nop 0
	s_nop 1
	s_nop 1
	v_mov_b32_e32 v82, v81
	v_mul_f32_e32 v81, 0xbfb8aa3b, v87
	v_rndne_f32_e32 v83, v81
	v_sub_f32_e32 v99, v81, v83
	v_fma_f32 v81, v87, s54, -v81
	v_fmac_f32_e32 v81, 0xb2a5705f, v87
	v_add_f32_e32 v81, v99, v81
	v_exp_f32_e32 v81, v81
	v_cvt_i32_f32_e32 v83, v83
	v_ldexp_f32 v81, v81, v83
	s_nop 0
	s_nop 1
	v_pk_add_f32 v[80:81], v[80:81], 1.0 op_sel_hi:[1,0]
	s_nop 0
	v_div_scale_f32 v83, s[42:43], v80, v80, 1.0
	v_rcp_f32_e32 v99, v83
	s_nop 0
	v_fma_f32 v100, -v83, v99, 1.0
	v_fmac_f32_e32 v99, v100, v99
	v_div_scale_f32 v100, vcc, 1.0, v80, 1.0
	v_mul_f32_e32 v101, v100, v99
	v_fma_f32 v102, -v83, v101, v100
	v_fmac_f32_e32 v101, v102, v99
	v_fma_f32 v83, -v83, v101, v100
	v_div_fmas_f32 v83, v83, v99, v101
	v_div_fixup_f32 v80, v83, v80, 1.0
	v_div_scale_f32 v83, s[42:43], v81, v81, 1.0
	v_rcp_f32_e32 v99, v83
	s_nop 0
	v_fma_f32 v100, -v83, v99, 1.0
	v_fmac_f32_e32 v99, v100, v99
	v_div_scale_f32 v100, vcc, 1.0, v81, 1.0
	v_mul_f32_e32 v101, v100, v99
	v_fma_f32 v102, -v83, v101, v100
	v_fmac_f32_e32 v101, v102, v99
	v_fma_f32 v83, -v83, v101, v100
	v_div_fmas_f32 v83, v83, v99, v101
	v_div_fixup_f32 v81, v83, v81, 1.0
	v_mul_f32_e32 v83, 0xbfb8aa3b, v71
	v_rndne_f32_e32 v99, v83
	v_sub_f32_e32 v100, v83, v99
	v_fma_f32 v83, v71, s54, -v83
	v_fmac_f32_e32 v83, 0xb2a5705f, v71
	v_add_f32_e32 v83, v100, v83
	v_exp_f32_e32 v83, v83
	v_cvt_i32_f32_e32 v99, v99
	v_ldexp_f32 v83, v83, v99
	s_nop 0
	s_nop 1
	v_pk_add_f32 v[82:83], v[82:83], 1.0 op_sel_hi:[1,0]
	s_nop 0
	v_div_scale_f32 v99, s[42:43], v82, v82, 1.0
	v_rcp_f32_e32 v100, v99
	s_nop 0
	v_fma_f32 v101, -v99, v100, 1.0
	v_fmac_f32_e32 v100, v101, v100
	v_div_scale_f32 v101, vcc, 1.0, v82, 1.0
	v_mul_f32_e32 v102, v101, v100
	v_fma_f32 v103, -v99, v102, v101
	v_fmac_f32_e32 v102, v103, v100
	v_fma_f32 v99, -v99, v102, v101
	v_div_fmas_f32 v99, v99, v100, v102
	v_div_fixup_f32 v82, v99, v82, 1.0
	v_div_scale_f32 v99, s[42:43], v83, v83, 1.0
	v_rcp_f32_e32 v100, v99
	s_nop 0
	v_fma_f32 v101, -v99, v100, 1.0
	v_fmac_f32_e32 v100, v101, v100
	v_div_scale_f32 v101, vcc, 1.0, v83, 1.0
	v_mul_f32_e32 v102, v101, v100
	v_fma_f32 v103, -v99, v102, v101
	v_fmac_f32_e32 v102, v103, v100
	v_fma_f32 v99, -v99, v102, v101
	v_div_fmas_f32 v99, v99, v100, v102
	v_div_fixup_f32 v83, v99, v83, 1.0

; DEVI float sigmf(float x) { return 1.f / (1.f + expf(-x)); }
; DEVI void lds_put4(char* wl, int RS, int row, int col, float a, float b, float c, float d) { u32x2 w = {cvtpk(a, b), cvtpk(c, d)}; *(u32x2*)(wl + row * RS + col * 2) = w; }
; DEVI void phase_gemm_in(const Params& p, int l, char* lds) {
;     ...
;           if (mode == 1) {
; #pragma unroll
;             for (int j = 0; j < 4; ++j) { x1[j] *= 0.08838834764831845f; x2[j] *= 0.08838834764831845f; }
;           } else if (mode == 2) {
;             if (rr_of(m) < SEQ) {
;               const f32x4 cs = *(const f32x4*)(rope + (long)rr_of(m) * 64 + ci);
;               const f32x4 sn = *(const f32x4*)(rope + (long)rr_of(m) * 64 + 32 + ci);
; #pragma unroll
;               for (int j = 0; j < 4; ++j) { const float a = x1[j], bb = x2[j]; x1[j] = a * cs[j] - bb * sn[j]; x2[j] = a * sn[j] + bb * cs[j]; }
;             }
;           } else if (mode == 3) {
; #pragma unroll
;             for (int j = 0; j < 4; ++j) { x1[j] = sigmf(x1[j]); x2[j] = sigmf(x2[j]); }
;           }
;           lds_put4(wl, 272, mi * 32 + r32, cg2 * 64 + ci, x1[0], x1[1], x1[2], x1[3]);
.LBB0_211:
	s_andn2_saveexec_b64 s[14:15], s[14:15]
	v_pk_mul_f32 v[64:65], v[84:85], s[96:97] op_sel_hi:[1,0]
	v_pk_mul_f32 v[66:67], v[68:69], s[96:97] op_sel_hi:[1,0]
	v_pk_mul_f32 v[80:81], v[86:87], s[96:97] op_sel_hi:[1,0]
	v_pk_mul_f32 v[82:83], v[70:71], s[96:97] op_sel_hi:[1,0]
	s_or_b64 exec, exec, s[14:15]
	v_cvt_pk_bf16_f32 v64, v64, v65
	v_cvt_pk_bf16_f32 v65, v80, v81
	v_cvt_pk_bf16_f32 v66, v66, v67
	v_cvt_pk_bf16_f32 v67, v82, v83
	v_add_u32_e32 v68, 0x2000, v223
	ds_write2_b64 v68, v[64:65], v[66:67] offset0:64 offset1:72
	s_and_saveexec_b64 s[14:15], s[10:11]
	s_xor_b64 s[14:15], exec, s[14:15]
	s_cbranch_execz .LBB0_223
	s_and_saveexec_b64 s[28:29], s[12:13]
	s_xor_b64 s[28:29], exec, s[28:29]
	s_cbranch_execz .LBB0_218
	v_mov_b32_e32 v69, v91
	v_mov_b32_e32 v68, v90
	v_mov_b32_e32 v65, v89
	v_mov_b32_e32 v64, v88
	v_mov_b32_e32 v71, v75
	v_mov_b32_e32 v70, v74
	v_mov_b32_e32 v67, v73
	v_mov_b32_e32 v66, v72
	s_and_saveexec_b64 s[30:31], s[2:3]
	s_cbranch_execz .LBB0_217
	v_mul_f32_e32 v64, 0xbfb8aa3b, v88
	v_rndne_f32_e32 v65, v64
	v_sub_f32_e32 v66, v64, v65
	v_fma_f32 v64, v88, s54, -v64
	v_fmac_f32_e32 v64, 0xb2a5705f, v88
	v_add_f32_e32 v64, v66, v64
	v_exp_f32_e32 v64, v64
	v_cvt_i32_f32_e32 v65, v65
	v_ldexp_f32 v64, v64, v65
	v_mul_f32_e32 v65, 0xbfb8aa3b, v72
	v_rndne_f32_e32 v66, v65
	v_sub_f32_e32 v67, v65, v66
	v_fma_f32 v65, v72, s54, -v65
	v_fmac_f32_e32 v65, 0xb2a5705f, v72
	v_add_f32_e32 v65, v67, v65
	v_exp_f32_e32 v65, v65
	v_cvt_i32_f32_e32 v66, v66
	v_ldexp_f32 v65, v65, v66
	s_nop 0
	s_nop 1
	s_nop 1
	v_mov_b32_e32 v66, v65
	v_mul_f32_e32 v65, 0xbfb8aa3b, v89
	v_rndne_f32_e32 v67, v65
	v_sub_f32_e32 v68, v65, v67
	v_fma_f32 v65, v89, s54, -v65
	v_fmac_f32_e32 v65, 0xb2a5705f, v89
	v_add_f32_e32 v65, v68, v65
	v_exp_f32_e32 v65, v65
	v_cvt_i32_f32_e32 v67, v67
	v_ldexp_f32 v65, v65, v67
	s_nop 0
	s_nop 1
	v_pk_add_f32 v[64:65], v[64:65], 1.0 op_sel_hi:[1,0]
	s_nop 0
	v_div_scale_f32 v67, s[42:43], v64, v64, 1.0
	v_rcp_f32_e32 v68, v67
	s_nop 0
	v_fma_f32 v69, -v67, v68, 1.0
	v_fmac_f32_e32 v68, v69, v68
	v_div_scale_f32 v69, vcc, 1.0, v64, 1.0
	v_mul_f32_e32 v70, v69, v68
	v_fma_f32 v71, -v67, v70, v69
	v_fmac_f32_e32 v70, v71, v68
	v_fma_f32 v67, -v67, v70, v69
	v_div_fmas_f32 v67, v67, v68, v70
	v_div_fixup_f32 v64, v67, v64, 1.0
	v_div_scale_f32 v67, s[42:43], v65, v65, 1.0
	v_rcp_f32_e32 v68, v67
	s_nop 0
	v_fma_f32 v69, -v67, v68, 1.0
	v_fmac_f32_e32 v68, v69, v68
	v_div_scale_f32 v69, vcc, 1.0, v65, 1.0
	v_mul_f32_e32 v70, v69, v68
	v_fma_f32 v71, -v67, v70, v69
	v_fmac_f32_e32 v70, v71, v68
	v_fma_f32 v67, -v67, v70, v69
	v_div_fmas_f32 v67, v67, v68, v70
	v_div_fixup_f32 v65, v67, v65, 1.0
	v_mul_f32_e32 v67, 0xbfb8aa3b, v73
	v_rndne_f32_e32 v68, v67
	v_sub_f32_e32 v69, v67, v68
	v_fma_f32 v67, v73, s54, -v67
	v_fmac_f32_e32 v67, 0xb2a5705f, v73
	v_add_f32_e32 v67, v69, v67
	v_exp_f32_e32 v67, v67
	v_cvt_i32_f32_e32 v68, v68
	v_ldexp_f32 v67, v67, v68
	s_nop 0
	s_nop 1
	v_pk_add_f32 v[66:67], v[66:67], 1.0 op_sel_hi:[1,0]
	s_nop 0
	v_div_scale_f32 v68, s[42:43], v66, v66, 1.0
	v_rcp_f32_e32 v69, v68
	s_nop 0
	v_fma_f32 v70, -v68, v69, 1.0
	v_fmac_f32_e32 v69, v70, v69
	v_div_scale_f32 v70, vcc, 1.0, v66, 1.0
	v_mul_f32_e32 v71, v70, v69
	v_fma_f32 v80, -v68, v71, v70
	v_fmac_f32_e32 v71, v80, v69
	v_fma_f32 v68, -v68, v71, v70
	v_div_fmas_f32 v68, v68, v69, v71
	v_div_fixup_f32 v66, v68, v66, 1.0
	v_div_scale_f32 v68, s[42:43], v67, v67, 1.0
	v_rcp_f32_e32 v69, v68
	s_nop 0
	v_fma_f32 v70, -v68, v69, 1.0
	v_fmac_f32_e32 v69, v70, v69
	v_div_scale_f32 v70, vcc, 1.0, v67, 1.0
	v_mul_f32_e32 v71, v70, v69
	v_fma_f32 v80, -v68, v71, v70
	v_fmac_f32_e32 v71, v80, v69
	v_fma_f32 v68, -v68, v71, v70
	v_div_fmas_f32 v68, v68, v69, v71
	v_div_fixup_f32 v67, v68, v67, 1.0
	v_mul_f32_e32 v68, 0xbfb8aa3b, v90
	v_rndne_f32_e32 v69, v68
	v_sub_f32_e32 v70, v68, v69
	v_fma_f32 v68, v90, s54, -v68
	v_fmac_f32_e32 v68, 0xb2a5705f, v90
	v_add_f32_e32 v68, v70, v68
	v_exp_f32_e32 v68, v68
	v_cvt_i32_f32_e32 v69, v69
	v_ldexp_f32 v68, v68, v69
	v_mul_f32_e32 v69, 0xbfb8aa3b, v74
	v_rndne_f32_e32 v70, v69
	v_sub_f32_e32 v71, v69, v70
	v_fma_f32 v69, v74, s54, -v69
	v_fmac_f32_e32 v69, 0xb2a5705f, v74
	v_add_f32_e32 v69, v71, v69
	v_exp_f32_e32 v69, v69
	v_cvt_i32_f32_e32 v70, v70
	v_ldexp_f32 v69, v69, v70
	s_nop 0
	s_nop 1
	s_nop 1
	v_mov_b32_e32 v70, v69
	v_mul_f32_e32 v69, 0xbfb8aa3b, v91
	v_rndne_f32_e32 v71, v69
	v_sub_f32_e32 v80, v69, v71
	v_fma_f32 v69, v91, s54, -v69
	v_fmac_f32_e32 v69, 0xb2a5705f, v91
	v_add_f32_e32 v69, v80, v69
	v_exp_f32_e32 v69, v69
	v_cvt_i32_f32_e32 v71, v71
	v_ldexp_f32 v69, v69, v71
	s_nop 0
	s_nop 1
	v_pk_add_f32 v[68:69], v[68:69], 1.0 op_sel_hi:[1,0]
	s_nop 0
	v_div_scale_f32 v71, s[42:43], v68, v68, 1.0
	v_rcp_f32_e32 v80, v71
	s_nop 0
	v_fma_f32 v81, -v71, v80, 1.0
	v_fmac_f32_e32 v80, v81, v80
	v_div_scale_f32 v81, vcc, 1.0, v68, 1.0
	v_mul_f32_e32 v82, v81, v80
	v_fma_f32 v83, -v71, v82, v81
	v_fmac_f32_e32 v82, v83, v80
	v_fma_f32 v71, -v71, v82, v81
	v_div_fmas_f32 v71, v71, v80, v82
	v_div_fixup_f32 v68, v71, v68, 1.0
	v_div_scale_f32 v71, s[42:43], v69, v69, 1.0
	v_rcp_f32_e32 v80, v71
	s_nop 0
	v_fma_f32 v81, -v71, v80, 1.0
	v_fmac_f32_e32 v80, v81, v80
	v_div_scale_f32 v81, vcc, 1.0, v69, 1.0
	v_mul_f32_e32 v82, v81, v80
	v_fma_f32 v83, -v71, v82, v81
	v_fmac_f32_e32 v82, v83, v80
	v_fma_f32 v71, -v71, v82, v81
	v_div_fmas_f32 v71, v71, v80, v82
	v_div_fixup_f32 v69, v71, v69, 1.0
	v_mul_f32_e32 v71, 0xbfb8aa3b, v75
	v_rndne_f32_e32 v80, v71
	v_sub_f32_e32 v81, v71, v80
	v_fma_f32 v71, v75, s54, -v71
	v_fmac_f32_e32 v71, 0xb2a5705f, v75
	v_add_f32_e32 v71, v81, v71
	v_exp_f32_e32 v71, v71
	v_cvt_i32_f32_e32 v80, v80
	v_ldexp_f32 v71, v71, v80
	s_nop 0
	s_nop 1
	v_pk_add_f32 v[70:71], v[70:71], 1.0 op_sel_hi:[1,0]
	s_nop 0
	v_div_scale_f32 v80, s[42:43], v70, v70, 1.0
	v_rcp_f32_e32 v81, v80
	s_nop 0
	v_fma_f32 v82, -v80, v81, 1.0
	v_fmac_f32_e32 v81, v82, v81
	v_div_scale_f32 v82, vcc, 1.0, v70, 1.0
	v_mul_f32_e32 v83, v82, v81
	v_fma_f32 v84, -v80, v83, v82
	v_fmac_f32_e32 v83, v84, v81
	v_fma_f32 v80, -v80, v83, v82
	v_div_fmas_f32 v80, v80, v81, v83
	v_div_fixup_f32 v70, v80, v70, 1.0
	v_div_scale_f32 v80, s[42:43], v71, v71, 1.0
	v_rcp_f32_e32 v81, v80
	s_nop 0
	v_fma_f32 v82, -v80, v81, 1.0
	v_fmac_f32_e32 v81, v82, v81
	v_div_scale_f32 v82, vcc, 1.0, v71, 1.0
	v_mul_f32_e32 v83, v82, v81
	v_fma_f32 v84, -v80, v83, v82
	v_fmac_f32_e32 v83, v84, v81
	v_fma_f32 v80, -v80, v83, v82
	v_div_fmas_f32 v80, v80, v81, v83
	v_div_fixup_f32 v71, v80, v71, 1.0

; #define SBAR() __builtin_amdgcn_sched_barrier(0)
; DEVI void lds_put4(char* wl, int RS, int row, int col, float a, float b, float c, float d) { u32x2 w = {cvtpk(a, b), cvtpk(c, d)}; *(u32x2*)(wl + row * RS + col * 2) = w; }
; DEVI float sigmf(float x) { return 1.f / (1.f + expf(-x)); }
; DEVI void phase_gemm_in(const Params& p, int l, char* lds) {
;     ...
;     for (int cg2 = 0; cg2 < 2; ++cg2) {
;       SBAR();
;       const int cb = n0 + wn * 128 + cg2 * 64;
;       int mode = 0;
;       if (cb < F_GK) mode = 1;
;       else if ((cb >= F_DQ && cb < F_DV) || cb == F_KR) mode = 2;
;       else if (cb >= F_GATE && cb < F_KR) mode = 3;
; #pragma unroll
;       for (int mi = 0; mi < 2; ++mi) {
;         const int m = m0 + wm * 64 + mi * 32 + r32;
; #pragma unroll
;         for (int q = 0; q < 4; ++q) {
;           const int ci = q * 8 + hi * 4;
;           float x1[4], x2[4];
; #pragma unroll
;           for (int j = 0; j < 4; ++j) { x1[j] = acc[2 * cg2][mi][q * 4 + j]; x2[j] = acc[2 * cg2 + 1][mi][q * 4 + j]; }
;           if (mode == 1) {
; #pragma unroll
;             for (int j = 0; j < 4; ++j) { x1[j] *= 0.08838834764831845f; x2[j] *= 0.08838834764831845f; }
;           } else if (mode == 2) {
;             if (rr_of(m) < SEQ) {
;               const f32x4 cs = *(const f32x4*)(rope + (long)rr_of(m) * 64 + ci);
;               const f32x4 sn = *(const f32x4*)(rope + (long)rr_of(m) * 64 + 32 + ci);
; #pragma unroll
;               for (int j = 0; j < 4; ++j) { const float a = x1[j], bb = x2[j]; x1[j] = a * cs[j] - bb * sn[j]; x2[j] = a * sn[j] + bb * cs[j]; }
;             }
;           } else if (mode == 3) {
; #pragma unroll
;             for (int j = 0; j < 4; ++j) { x1[j] = sigmf(x1[j]); x2[j] = sigmf(x2[j]); }
;           }
;           lds_put4(wl, 272, mi * 32 + r32, cg2 * 64 + ci, x1[0], x1[1], x1[2], x1[3]);
;           lds_put4(wl, 272, mi * 32 + r32, cg2 * 64 + 32 + ci, x2[0], x2[1], x2[2], x2[3]);
;         }
;       }
.LBB0_223:
	s_andn2_saveexec_b64 s[14:15], s[14:15]
	v_pk_mul_f32 v[64:65], v[88:89], s[96:97] op_sel_hi:[1,0]
	v_pk_mul_f32 v[66:67], v[72:73], s[96:97] op_sel_hi:[1,0]
	v_pk_mul_f32 v[68:69], v[90:91], s[96:97] op_sel_hi:[1,0]
	v_pk_mul_f32 v[70:71], v[74:75], s[96:97] op_sel_hi:[1,0]
	s_or_b64 exec, exec, s[14:15]
	v_cvt_pk_bf16_f32 v64, v64, v65
	v_cvt_pk_bf16_f32 v65, v68, v69
	v_cvt_pk_bf16_f32 v66, v66, v67
	v_cvt_pk_bf16_f32 v67, v70, v71
	v_add_u32_e32 v68, 0x2000, v224
	ds_write2_b64 v68, v[64:65], v[66:67] offset0:64 offset1:72
	s_and_saveexec_b64 s[14:15], s[10:11]
	s_xor_b64 s[10:11], exec, s[14:15]
	s_cbranch_execz .LBB0_235
	s_and_saveexec_b64 s[14:15], s[12:13]
	s_xor_b64 s[12:13], exec, s[14:15]
	s_cbranch_execz .LBB0_230
	s_and_saveexec_b64 s[14:15], s[2:3]
	s_cbranch_execz .LBB0_229
	v_mul_f32_e32 v64, 0xbfb8aa3b, v92
	v_rndne_f32_e32 v65, v64
	v_sub_f32_e32 v66, v64, v65
	v_fma_f32 v64, v92, s54, -v64
	v_fmac_f32_e32 v64, 0xb2a5705f, v92
	v_add_f32_e32 v64, v66, v64
	v_exp_f32_e32 v64, v64
	v_cvt_i32_f32_e32 v65, v65
	v_ldexp_f32 v64, v64, v65
	v_mul_f32_e32 v65, 0xbfb8aa3b, v76
	v_rndne_f32_e32 v66, v65
	v_sub_f32_e32 v67, v65, v66
	v_fma_f32 v65, v76, s54, -v65
	v_fmac_f32_e32 v65, 0xb2a5705f, v76
	v_add_f32_e32 v65, v67, v65
	v_exp_f32_e32 v65, v65
	v_cvt_i32_f32_e32 v66, v66
	v_ldexp_f32 v65, v65, v66
	s_nop 0
	s_nop 1
	s_nop 1
	v_mov_b32_e32 v66, v65
	v_mul_f32_e32 v65, 0xbfb8aa3b, v93
	v_rndne_f32_e32 v67, v65
	v_sub_f32_e32 v68, v65, v67
	v_fma_f32 v65, v93, s54, -v65
	v_fmac_f32_e32 v65, 0xb2a5705f, v93
	v_add_f32_e32 v65, v68, v65
	v_exp_f32_e32 v65, v65
	v_cvt_i32_f32_e32 v67, v67
	v_ldexp_f32 v65, v65, v67
	s_nop 0
	s_nop 1
	v_pk_add_f32 v[64:65], v[64:65], 1.0 op_sel_hi:[1,0]
	s_nop 0
	v_div_scale_f32 v67, s[2:3], v64, v64, 1.0
	v_rcp_f32_e32 v68, v67
	s_nop 0
	v_fma_f32 v69, -v67, v68, 1.0
	v_fmac_f32_e32 v68, v69, v68
	v_div_scale_f32 v69, vcc, 1.0, v64, 1.0
	v_mul_f32_e32 v70, v69, v68
	v_fma_f32 v71, -v67, v70, v69
	v_fmac_f32_e32 v70, v71, v68
	v_fma_f32 v67, -v67, v70, v69
	v_div_fmas_f32 v67, v67, v68, v70
	v_div_fixup_f32 v92, v67, v64, 1.0
	v_div_scale_f32 v64, s[2:3], v65, v65, 1.0
	v_rcp_f32_e32 v67, v64
	s_nop 0
	v_fma_f32 v68, -v64, v67, 1.0
	v_fmac_f32_e32 v67, v68, v67
	v_div_scale_f32 v68, vcc, 1.0, v65, 1.0
	v_mul_f32_e32 v69, v68, v67
	v_fma_f32 v70, -v64, v69, v68
	v_fmac_f32_e32 v69, v70, v67
	v_fma_f32 v64, -v64, v69, v68
	v_div_fmas_f32 v64, v64, v67, v69
	v_div_fixup_f32 v93, v64, v65, 1.0
	v_mul_f32_e32 v64, 0xbfb8aa3b, v77
	v_rndne_f32_e32 v65, v64
	v_sub_f32_e32 v67, v64, v65
	v_fma_f32 v64, v77, s54, -v64
	v_fmac_f32_e32 v64, 0xb2a5705f, v77
	v_add_f32_e32 v64, v67, v64
	v_exp_f32_e32 v64, v64
	v_cvt_i32_f32_e32 v65, v65
	v_ldexp_f32 v64, v64, v65
	s_nop 0
	s_nop 1
	v_mov_b32_e32 v67, v64
	v_pk_add_f32 v[64:65], v[66:67], 1.0 op_sel_hi:[1,0]
	s_nop 0
	v_div_scale_f32 v66, s[2:3], v64, v64, 1.0
	v_rcp_f32_e32 v67, v66
	s_nop 0
	v_fma_f32 v68, -v66, v67, 1.0
	v_fmac_f32_e32 v67, v68, v67
	v_div_scale_f32 v68, vcc, 1.0, v64, 1.0
	v_mul_f32_e32 v69, v68, v67
	v_fma_f32 v70, -v66, v69, v68
	v_fmac_f32_e32 v69, v70, v67
	v_fma_f32 v66, -v66, v69, v68
	v_div_fmas_f32 v66, v66, v67, v69
	v_div_fixup_f32 v76, v66, v64, 1.0
	v_div_scale_f32 v64, s[2:3], v65, v65, 1.0
	v_rcp_f32_e32 v66, v64
	s_nop 0
	v_fma_f32 v67, -v64, v66, 1.0
	v_fmac_f32_e32 v66, v67, v66
	v_div_scale_f32 v67, vcc, 1.0, v65, 1.0
	v_mul_f32_e32 v68, v67, v66
	v_fma_f32 v69, -v64, v68, v67
	v_fmac_f32_e32 v68, v69, v66
	v_fma_f32 v64, -v64, v68, v67
	v_div_fmas_f32 v64, v64, v66, v68
	v_div_fixup_f32 v77, v64, v65, 1.0
	v_mul_f32_e32 v64, 0xbfb8aa3b, v94
	v_rndne_f32_e32 v65, v64
	v_sub_f32_e32 v66, v64, v65
	v_fma_f32 v64, v94, s54, -v64
	v_fmac_f32_e32 v64, 0xb2a5705f, v94
	v_add_f32_e32 v64, v66, v64
	v_exp_f32_e32 v64, v64
	v_cvt_i32_f32_e32 v65, v65
	v_ldexp_f32 v64, v64, v65
	v_mul_f32_e32 v65, 0xbfb8aa3b, v78
	v_rndne_f32_e32 v66, v65
	v_sub_f32_e32 v67, v65, v66
	v_fma_f32 v65, v78, s54, -v65
	v_fmac_f32_e32 v65, 0xb2a5705f, v78
	v_add_f32_e32 v65, v67, v65
	v_exp_f32_e32 v65, v65
	v_cvt_i32_f32_e32 v66, v66
	v_ldexp_f32 v65, v65, v66
	s_nop 0
	s_nop 1
	s_nop 1
	v_mov_b32_e32 v66, v65
	v_mul_f32_e32 v65, 0xbfb8aa3b, v95
	v_rndne_f32_e32 v67, v65
	v_sub_f32_e32 v68, v65, v67
	v_fma_f32 v65, v95, s54, -v65
	v_fmac_f32_e32 v65, 0xb2a5705f, v95
	v_add_f32_e32 v65, v68, v65
	v_exp_f32_e32 v65, v65
	v_cvt_i32_f32_e32 v67, v67
	v_ldexp_f32 v65, v65, v67
	s_nop 0
	s_nop 1
	v_pk_add_f32 v[64:65], v[64:65], 1.0 op_sel_hi:[1,0]
	s_nop 0
	v_div_scale_f32 v67, s[2:3], v64, v64, 1.0
	v_rcp_f32_e32 v68, v67
	s_nop 0
	v_fma_f32 v69, -v67, v68, 1.0
	v_fmac_f32_e32 v68, v69, v68
	v_div_scale_f32 v69, vcc, 1.0, v64, 1.0
	v_mul_f32_e32 v70, v69, v68
	v_fma_f32 v71, -v67, v70, v69
	v_fmac_f32_e32 v70, v71, v68
	v_fma_f32 v67, -v67, v70, v69
	v_div_fmas_f32 v67, v67, v68, v70
	v_div_fixup_f32 v94, v67, v64, 1.0
	v_div_scale_f32 v64, s[2:3], v65, v65, 1.0
	v_rcp_f32_e32 v67, v64
	s_nop 0
	v_fma_f32 v68, -v64, v67, 1.0
	v_fmac_f32_e32 v67, v68, v67
	v_div_scale_f32 v68, vcc, 1.0, v65, 1.0
	v_mul_f32_e32 v69, v68, v67
	v_fma_f32 v70, -v64, v69, v68
	v_fmac_f32_e32 v69, v70, v67
	v_fma_f32 v64, -v64, v69, v68
	v_div_fmas_f32 v64, v64, v67, v69
	v_div_fixup_f32 v95, v64, v65, 1.0
	v_mul_f32_e32 v64, 0xbfb8aa3b, v79
	v_rndne_f32_e32 v65, v64
	v_sub_f32_e32 v67, v64, v65
	v_fma_f32 v64, v79, s54, -v64
	v_fmac_f32_e32 v64, 0xb2a5705f, v79
	v_add_f32_e32 v64, v67, v64
	v_exp_f32_e32 v64, v64
	v_cvt_i32_f32_e32 v65, v65
	v_ldexp_f32 v64, v64, v65
	s_nop 0
	s_nop 1
	v_mov_b32_e32 v67, v64
	v_pk_add_f32 v[64:65], v[66:67], 1.0 op_sel_hi:[1,0]
	s_nop 0
	v_div_scale_f32 v66, s[2:3], v64, v64, 1.0
	v_rcp_f32_e32 v67, v66
	s_nop 0
	v_fma_f32 v68, -v66, v67, 1.0
	v_fmac_f32_e32 v67, v68, v67
	v_div_scale_f32 v68, vcc, 1.0, v64, 1.0
	v_mul_f32_e32 v69, v68, v67
	v_fma_f32 v70, -v66, v69, v68
	v_fmac_f32_e32 v69, v70, v67
	v_fma_f32 v66, -v66, v69, v68
	v_div_fmas_f32 v66, v66, v67, v69
	v_div_fixup_f32 v78, v66, v64, 1.0
	v_div_scale_f32 v64, s[2:3], v65, v65, 1.0
	v_rcp_f32_e32 v66, v64
	s_nop 0
	v_fma_f32 v67, -v64, v66, 1.0
	v_fmac_f32_e32 v66, v67, v66
	v_div_scale_f32 v67, vcc, 1.0, v65, 1.0
	v_mul_f32_e32 v68, v67, v66
	v_fma_f32 v69, -v64, v68, v67
	v_fmac_f32_e32 v68, v69, v66
	v_fma_f32 v64, -v64, v68, v67
	v_div_fmas_f32 v64, v64, v66, v68
	v_div_fixup_f32 v79, v64, v65, 1.0

; DEVI float sigmf(float x) { return 1.f / (1.f + expf(-x)); }
; #define SBAR() __builtin_amdgcn_sched_barrier(0)
; DEVI void lds_put4(char* wl, int RS, int row, int col, float a, float b, float c, float d) { u32x2 w = {cvtpk(a, b), cvtpk(c, d)}; *(u32x2*)(wl + row * RS + col * 2) = w; }
; DEVI void phase_gemm_in(const Params& p, int l, char* lds) {
;     ...
;     for (int cg2 = 0; cg2 < 2; ++cg2) {
;       SBAR();
;       const int cb = n0 + wn * 128 + cg2 * 64;
;       int mode = 0;
;       if (cb < F_GK) mode = 1;
;       else if ((cb >= F_DQ && cb < F_DV) || cb == F_KR) mode = 2;
;       else if (cb >= F_GATE && cb < F_KR) mode = 3;
; #pragma unroll
;       for (int mi = 0; mi < 2; ++mi) {
;         const int m = m0 + wm * 64 + mi * 32 + r32;
; #pragma unroll
;         for (int q = 0; q < 4; ++q) {
;           const int ci = q * 8 + hi * 4;
;           float x1[4], x2[4];
; #pragma unroll
;           for (int j = 0; j < 4; ++j) { x1[j] = acc[2 * cg2][mi][q * 4 + j]; x2[j] = acc[2 * cg2 + 1][mi][q * 4 + j]; }
;           if (mode == 1) {
; #pragma unroll
;             for (int j = 0; j < 4; ++j) { x1[j] *= 0.08838834764831845f; x2[j] *= 0.08838834764831845f; }
;           } else if (mode == 2) {
;             if (rr_of(m) < SEQ) {
;               const f32x4 cs = *(const f32x4*)(rope + (long)rr_of(m) * 64 + ci);
;               const f32x4 sn = *(const f32x4*)(rope + (long)rr_of(m) * 64 + 32 + ci);
; #pragma unroll
;               for (int j = 0; j < 4; ++j) { const float a = x1[j], bb = x2[j]; x1[j] = a * cs[j] - bb * sn[j]; x2[j] = a * sn[j] + bb * cs[j]; }
;             }
;           } else if (mode == 3) {
; #pragma unroll
;             for (int j = 0; j < 4; ++j) { x1[j] = sigmf(x1[j]); x2[j] = sigmf(x2[j]); }
;           }
;           lds_put4(wl, 272, mi * 32 + r32, cg2 * 64 + ci, x1[0], x1[1], x1[2], x1[3]);
;           lds_put4(wl, 272, mi * 32 + r32, cg2 * 64 + 32 + ci, x2[0], x2[1], x2[2], x2[3]);
.LBB0_235:
	s_andn2_saveexec_b64 s[2:3], s[10:11]
	v_pk_mul_f32 v[92:93], v[92:93], s[96:97] op_sel_hi:[1,0]
	v_pk_mul_f32 v[76:77], v[76:77], s[96:97] op_sel_hi:[1,0]
	v_pk_mul_f32 v[94:95], v[94:95], s[96:97] op_sel_hi:[1,0]
	v_pk_mul_f32 v[78:79], v[78:79], s[96:97] op_sel_hi:[1,0]
	s_or_b64 exec, exec, s[2:3]
	v_cvt_pk_bf16_f32 v64, v92, v93
	v_cvt_pk_bf16_f32 v65, v94, v95
	v_cvt_pk_bf16_f32 v66, v76, v77
	v_cvt_pk_bf16_f32 v67, v78, v79
	v_add_u32_e32 v68, 0x2000, v225
	ds_write2_b64 v68, v[64:65], v[66:67] offset0:64 offset1:72
	v_or_b32_e32 v64, 64, v138
	s_movk_i32 s2, 0x200
	v_cmp_gt_i32_e64 s[14:15], s2, v64
	v_add_u32_e32 v64, 0xfffff440, v138
	s_movk_i32 s2, 0x7ff
	v_cmp_lt_u32_e64 s[12:13], s2, v64
	v_add_u32_e32 v64, 0xffffe6c0, v138
	s_movk_i32 s2, 0xc00
	v_cmp_gt_u32_e64 s[10:11], s2, v64
	s_and_saveexec_b64 s[2:3], s[14:15]
	s_xor_b64 s[2:3], exec, s[2:3]
	v_pk_mul_f32 v[64:65], v[48:49], s[96:97] op_sel_hi:[1,0]
	v_pk_mul_f32 v[66:67], v[32:33], s[96:97] op_sel_hi:[1,0]
	v_pk_mul_f32 v[68:69], v[50:51], s[96:97] op_sel_hi:[1,0]
	v_pk_mul_f32 v[70:71], v[34:35], s[96:97] op_sel_hi:[1,0]
	s_andn2_saveexec_b64 s[2:3], s[2:3]
	s_cbranch_execz .LBB0_249
	s_and_saveexec_b64 s[28:29], s[12:13]
	s_xor_b64 s[28:29], exec, s[28:29]
	s_cbranch_execz .LBB0_244
	v_mov_b32_e32 v69, v51
	v_mov_b32_e32 v68, v50
	v_mov_b32_e32 v65, v49
	v_mov_b32_e32 v64, v48
	v_mov_b32_e32 v71, v35
	v_mov_b32_e32 v70, v34
	v_mov_b32_e32 v67, v33
	v_mov_b32_e32 v66, v32
	s_and_saveexec_b64 s[30:31], s[10:11]
	s_cbranch_execz .LBB0_243
; DEVI float sigmf(float x) { return 1.f / (1.f + expf(-x)); }
; DEVI void phase_gemm_in(const Params& p, int l, char* lds) {
;     ...
;           } else if (mode == 3) {
; #pragma unroll
;             for (int j = 0; j < 4; ++j) { x1[j] = sigmf(x1[j]); x2[j] = sigmf(x2[j]); }
;           }
	v_mul_f32_e32 v64, 0xbfb8aa3b, v48
	v_rndne_f32_e32 v65, v64
	v_sub_f32_e32 v66, v64, v65
	v_fma_f32 v64, v48, s54, -v64
	v_fmac_f32_e32 v64, 0xb2a5705f, v48
	v_add_f32_e32 v64, v66, v64
	v_exp_f32_e32 v64, v64
	v_cvt_i32_f32_e32 v65, v65
	v_ldexp_f32 v64, v64, v65
	v_mul_f32_e32 v65, 0xbfb8aa3b, v32
	v_rndne_f32_e32 v66, v65
	v_sub_f32_e32 v67, v65, v66
	v_fma_f32 v65, v32, s54, -v65
	v_fmac_f32_e32 v65, 0xb2a5705f, v32
	v_add_f32_e32 v65, v67, v65
	v_exp_f32_e32 v65, v65
	v_cvt_i32_f32_e32 v66, v66
	v_ldexp_f32 v65, v65, v66
	s_nop 0
	s_nop 1
	s_nop 1
	v_mov_b32_e32 v66, v65
	v_mul_f32_e32 v65, 0xbfb8aa3b, v49
	v_rndne_f32_e32 v67, v65
	v_sub_f32_e32 v68, v65, v67
	v_fma_f32 v65, v49, s54, -v65
	v_fmac_f32_e32 v65, 0xb2a5705f, v49
	v_add_f32_e32 v65, v68, v65
	v_exp_f32_e32 v65, v65
	v_cvt_i32_f32_e32 v67, v67
	v_ldexp_f32 v65, v65, v67
	s_nop 0
	s_nop 1
	v_pk_add_f32 v[64:65], v[64:65], 1.0 op_sel_hi:[1,0]
	s_nop 0
	v_div_scale_f32 v67, s[42:43], v64, v64, 1.0
	v_rcp_f32_e32 v68, v67
	s_nop 0
	v_fma_f32 v69, -v67, v68, 1.0
	v_fmac_f32_e32 v68, v69, v68
	v_div_scale_f32 v69, vcc, 1.0, v64, 1.0
	v_mul_f32_e32 v70, v69, v68
	v_fma_f32 v71, -v67, v70, v69
	v_fmac_f32_e32 v70, v71, v68
	v_fma_f32 v67, -v67, v70, v69
	v_div_fmas_f32 v67, v67, v68, v70
	v_div_fixup_f32 v64, v67, v64, 1.0
	v_div_scale_f32 v67, s[42:43], v65, v65, 1.0
	v_rcp_f32_e32 v68, v67
	s_nop 0
	v_fma_f32 v69, -v67, v68, 1.0
	v_fmac_f32_e32 v68, v69, v68
	v_div_scale_f32 v69, vcc, 1.0, v65, 1.0
	v_mul_f32_e32 v70, v69, v68
	v_fma_f32 v71, -v67, v70, v69
	v_fmac_f32_e32 v70, v71, v68
	v_fma_f32 v67, -v67, v70, v69
	v_div_fmas_f32 v67, v67, v68, v70
	v_div_fixup_f32 v65, v67, v65, 1.0
	v_mul_f32_e32 v67, 0xbfb8aa3b, v33
	v_rndne_f32_e32 v68, v67
	v_sub_f32_e32 v69, v67, v68
	v_fma_f32 v67, v33, s54, -v67
	v_fmac_f32_e32 v67, 0xb2a5705f, v33
	v_add_f32_e32 v67, v69, v67
	v_exp_f32_e32 v67, v67
	v_cvt_i32_f32_e32 v68, v68
	v_ldexp_f32 v67, v67, v68
	s_nop 0
	s_nop 1
	v_pk_add_f32 v[66:67], v[66:67], 1.0 op_sel_hi:[1,0]
	s_nop 0
	v_div_scale_f32 v68, s[42:43], v66, v66, 1.0
	v_rcp_f32_e32 v69, v68
	s_nop 0
	v_fma_f32 v70, -v68, v69, 1.0
	v_fmac_f32_e32 v69, v70, v69
	v_div_scale_f32 v70, vcc, 1.0, v66, 1.0
	v_mul_f32_e32 v71, v70, v69
	v_fma_f32 v72, -v68, v71, v70
	v_fmac_f32_e32 v71, v72, v69
	v_fma_f32 v68, -v68, v71, v70
	v_div_fmas_f32 v68, v68, v69, v71
	v_div_fixup_f32 v66, v68, v66, 1.0
	v_div_scale_f32 v68, s[42:43], v67, v67, 1.0
	v_rcp_f32_e32 v69, v68
	s_nop 0
	v_fma_f32 v70, -v68, v69, 1.0
	v_fmac_f32_e32 v69, v70, v69
	v_div_scale_f32 v70, vcc, 1.0, v67, 1.0
	v_mul_f32_e32 v71, v70, v69
	v_fma_f32 v72, -v68, v71, v70
	v_fmac_f32_e32 v71, v72, v69
	v_fma_f32 v68, -v68, v71, v70
	v_div_fmas_f32 v68, v68, v69, v71
	v_div_fixup_f32 v67, v68, v67, 1.0
	v_mul_f32_e32 v68, 0xbfb8aa3b, v50
	v_rndne_f32_e32 v69, v68
	v_sub_f32_e32 v70, v68, v69
	v_fma_f32 v68, v50, s54, -v68
	v_fmac_f32_e32 v68, 0xb2a5705f, v50
	v_add_f32_e32 v68, v70, v68
	v_exp_f32_e32 v68, v68
	v_cvt_i32_f32_e32 v69, v69
	v_ldexp_f32 v68, v68, v69
	v_mul_f32_e32 v69, 0xbfb8aa3b, v34
	v_rndne_f32_e32 v70, v69
	v_sub_f32_e32 v71, v69, v70
	v_fma_f32 v69, v34, s54, -v69
	v_fmac_f32_e32 v69, 0xb2a5705f, v34
	v_add_f32_e32 v69, v71, v69
	v_exp_f32_e32 v69, v69
	v_cvt_i32_f32_e32 v70, v70
	v_ldexp_f32 v69, v69, v70
	s_nop 0
	s_nop 1
	s_nop 1
	v_mov_b32_e32 v70, v69
	v_mul_f32_e32 v69, 0xbfb8aa3b, v51
	v_rndne_f32_e32 v71, v69
	v_sub_f32_e32 v72, v69, v71
	v_fma_f32 v69, v51, s54, -v69
	v_fmac_f32_e32 v69, 0xb2a5705f, v51
	v_add_f32_e32 v69, v72, v69
	v_exp_f32_e32 v69, v69
	v_cvt_i32_f32_e32 v71, v71
	v_ldexp_f32 v69, v69, v71
	s_nop 0
	s_nop 1
	v_pk_add_f32 v[68:69], v[68:69], 1.0 op_sel_hi:[1,0]
	s_nop 0
	v_div_scale_f32 v71, s[42:43], v68, v68, 1.0
	v_rcp_f32_e32 v72, v71
	s_nop 0
	v_fma_f32 v73, -v71, v72, 1.0
	v_fmac_f32_e32 v72, v73, v72
	v_div_scale_f32 v73, vcc, 1.0, v68, 1.0
	v_mul_f32_e32 v74, v73, v72
	v_fma_f32 v75, -v71, v74, v73
	v_fmac_f32_e32 v74, v75, v72
	v_fma_f32 v71, -v71, v74, v73
	v_div_fmas_f32 v71, v71, v72, v74
	v_div_fixup_f32 v68, v71, v68, 1.0
	v_div_scale_f32 v71, s[42:43], v69, v69, 1.0
	v_rcp_f32_e32 v72, v71
	s_nop 0
	v_fma_f32 v73, -v71, v72, 1.0
	v_fmac_f32_e32 v72, v73, v72
	v_div_scale_f32 v73, vcc, 1.0, v69, 1.0
	v_mul_f32_e32 v74, v73, v72
	v_fma_f32 v75, -v71, v74, v73
	v_fmac_f32_e32 v74, v75, v72
	v_fma_f32 v71, -v71, v74, v73
	v_div_fmas_f32 v71, v71, v72, v74
	v_div_fixup_f32 v69, v71, v69, 1.0
	v_mul_f32_e32 v71, 0xbfb8aa3b, v35
	v_rndne_f32_e32 v72, v71
	v_sub_f32_e32 v73, v71, v72
	v_fma_f32 v71, v35, s54, -v71
	v_fmac_f32_e32 v71, 0xb2a5705f, v35
	v_add_f32_e32 v71, v73, v71
	v_exp_f32_e32 v71, v71
	v_cvt_i32_f32_e32 v72, v72
	v_ldexp_f32 v71, v71, v72
	s_nop 0
	s_nop 1
	v_pk_add_f32 v[70:71], v[70:71], 1.0 op_sel_hi:[1,0]
	s_nop 0
	v_div_scale_f32 v72, s[42:43], v70, v70, 1.0
	v_rcp_f32_e32 v73, v72
	s_nop 0
	v_fma_f32 v74, -v72, v73, 1.0
	v_fmac_f32_e32 v73, v74, v73
	v_div_scale_f32 v74, vcc, 1.0, v70, 1.0
	v_mul_f32_e32 v75, v74, v73
	v_fma_f32 v76, -v72, v75, v74
	v_fmac_f32_e32 v75, v76, v73
	v_fma_f32 v72, -v72, v75, v74
	v_div_fmas_f32 v72, v72, v73, v75
	v_div_fixup_f32 v70, v72, v70, 1.0
	v_div_scale_f32 v72, s[42:43], v71, v71, 1.0
	v_rcp_f32_e32 v73, v72
	s_nop 0
	v_fma_f32 v74, -v72, v73, 1.0
	v_fmac_f32_e32 v73, v74, v73
	v_div_scale_f32 v74, vcc, 1.0, v71, 1.0
	v_mul_f32_e32 v75, v74, v73
	v_fma_f32 v76, -v72, v75, v74
	v_fmac_f32_e32 v75, v76, v73
	v_fma_f32 v72, -v72, v75, v74
	v_div_fmas_f32 v72, v72, v73, v75
	v_div_fixup_f32 v71, v72, v71, 1.0

; DEVI void lds_put4(char* wl, int RS, int row, int col, float a, float b, float c, float d) { u32x2 w = {cvtpk(a, b), cvtpk(c, d)}; *(u32x2*)(wl + row * RS + col * 2) = w; }
; DEVI float sigmf(float x) { return 1.f / (1.f + expf(-x)); }
; DEVI void phase_gemm_in(const Params& p, int l, char* lds) {
;     ...
;           } else if (mode == 3) {
; #pragma unroll
;             for (int j = 0; j < 4; ++j) { x1[j] = sigmf(x1[j]); x2[j] = sigmf(x2[j]); }
;           }
;           lds_put4(wl, 272, mi * 32 + r32, cg2 * 64 + ci, x1[0], x1[1], x1[2], x1[3]);
;           lds_put4(wl, 272, mi * 32 + r32, cg2 * 64 + 32 + ci, x2[0], x2[1], x2[2], x2[3]);
.LBB0_249:
	s_or_b64 exec, exec, s[2:3]
	v_cvt_pk_bf16_f32 v32, v64, v65
	v_cvt_pk_bf16_f32 v33, v68, v69
	v_cvt_pk_bf16_f32 v34, v66, v67
	v_cvt_pk_bf16_f32 v35, v70, v71
	ds_write2_b64 v130, v[32:33], v[34:35] offset0:16 offset1:24
	s_and_saveexec_b64 s[2:3], s[14:15]
	s_xor_b64 s[2:3], exec, s[2:3]
	v_pk_mul_f32 v[32:33], v[52:53], s[96:97] op_sel_hi:[1,0]
	v_pk_mul_f32 v[34:35], v[36:37], s[96:97] op_sel_hi:[1,0]
	v_pk_mul_f32 v[48:49], v[54:55], s[96:97] op_sel_hi:[1,0]
	v_pk_mul_f32 v[50:51], v[38:39], s[96:97] op_sel_hi:[1,0]
	s_andn2_saveexec_b64 s[2:3], s[2:3]
	s_cbranch_execz .LBB0_261
	s_and_saveexec_b64 s[28:29], s[12:13]
	s_xor_b64 s[28:29], exec, s[28:29]
	s_cbranch_execz .LBB0_256
	v_mov_b32_e32 v49, v55
	v_mov_b32_e32 v48, v54
	v_mov_b32_e32 v33, v53
	v_mov_b32_e32 v32, v52
	v_mov_b32_e32 v51, v39
	v_mov_b32_e32 v50, v38
	v_mov_b32_e32 v35, v37
	v_mov_b32_e32 v34, v36
	s_and_saveexec_b64 s[30:31], s[10:11]
	s_cbranch_execz .LBB0_255
	v_mul_f32_e32 v32, 0xbfb8aa3b, v52
	v_rndne_f32_e32 v33, v32
	v_sub_f32_e32 v34, v32, v33
	v_fma_f32 v32, v52, s54, -v32
	v_fmac_f32_e32 v32, 0xb2a5705f, v52
	v_add_f32_e32 v32, v34, v32
	v_exp_f32_e32 v32, v32
	v_cvt_i32_f32_e32 v33, v33
	v_ldexp_f32 v32, v32, v33
	v_mul_f32_e32 v33, 0xbfb8aa3b, v36
	v_rndne_f32_e32 v34, v33
	v_sub_f32_e32 v35, v33, v34
	v_fma_f32 v33, v36, s54, -v33
	v_fmac_f32_e32 v33, 0xb2a5705f, v36
	v_add_f32_e32 v33, v35, v33
	v_exp_f32_e32 v33, v33
	v_cvt_i32_f32_e32 v34, v34
	v_ldexp_f32 v33, v33, v34
	s_nop 0
	s_nop 1
	s_nop 1
	v_mov_b32_e32 v34, v33
	v_mul_f32_e32 v33, 0xbfb8aa3b, v53
	v_rndne_f32_e32 v35, v33
	v_sub_f32_e32 v48, v33, v35
	v_fma_f32 v33, v53, s54, -v33
	v_fmac_f32_e32 v33, 0xb2a5705f, v53
	v_add_f32_e32 v33, v48, v33
	v_exp_f32_e32 v33, v33
	v_cvt_i32_f32_e32 v35, v35
	v_ldexp_f32 v33, v33, v35
	s_nop 0
	s_nop 1
	v_pk_add_f32 v[32:33], v[32:33], 1.0 op_sel_hi:[1,0]
	s_nop 0
	v_div_scale_f32 v35, s[42:43], v32, v32, 1.0
	v_rcp_f32_e32 v48, v35
	s_nop 0
	v_fma_f32 v49, -v35, v48, 1.0
	v_fmac_f32_e32 v48, v49, v48
	v_div_scale_f32 v49, vcc, 1.0, v32, 1.0
	v_mul_f32_e32 v50, v49, v48
	v_fma_f32 v51, -v35, v50, v49
	v_fmac_f32_e32 v50, v51, v48
	v_fma_f32 v35, -v35, v50, v49
	v_div_fmas_f32 v35, v35, v48, v50
	v_div_fixup_f32 v32, v35, v32, 1.0
	v_div_scale_f32 v35, s[42:43], v33, v33, 1.0
	v_rcp_f32_e32 v48, v35
	s_nop 0
	v_fma_f32 v49, -v35, v48, 1.0
	v_fmac_f32_e32 v48, v49, v48
	v_div_scale_f32 v49, vcc, 1.0, v33, 1.0
	v_mul_f32_e32 v50, v49, v48
	v_fma_f32 v51, -v35, v50, v49
	v_fmac_f32_e32 v50, v51, v48
	v_fma_f32 v35, -v35, v50, v49
	v_div_fmas_f32 v35, v35, v48, v50
	v_div_fixup_f32 v33, v35, v33, 1.0
	v_mul_f32_e32 v35, 0xbfb8aa3b, v37
	v_rndne_f32_e32 v48, v35
	v_sub_f32_e32 v49, v35, v48
	v_fma_f32 v35, v37, s54, -v35
	v_fmac_f32_e32 v35, 0xb2a5705f, v37
	v_add_f32_e32 v35, v49, v35
	v_exp_f32_e32 v35, v35
	v_cvt_i32_f32_e32 v48, v48
	v_ldexp_f32 v35, v35, v48
	s_nop 0
	s_nop 1
	v_pk_add_f32 v[34:35], v[34:35], 1.0 op_sel_hi:[1,0]
	s_nop 0
	v_div_scale_f32 v48, s[42:43], v34, v34, 1.0
	v_rcp_f32_e32 v49, v48
	s_nop 0
	v_fma_f32 v50, -v48, v49, 1.0
	v_fmac_f32_e32 v49, v50, v49
	v_div_scale_f32 v50, vcc, 1.0, v34, 1.0
	v_mul_f32_e32 v51, v50, v49
	v_fma_f32 v64, -v48, v51, v50
	v_fmac_f32_e32 v51, v64, v49
	v_fma_f32 v48, -v48, v51, v50
	v_div_fmas_f32 v48, v48, v49, v51
	v_div_fixup_f32 v34, v48, v34, 1.0
	v_div_scale_f32 v48, s[42:43], v35, v35, 1.0
	v_rcp_f32_e32 v49, v48
	s_nop 0
	v_fma_f32 v50, -v48, v49, 1.0
	v_fmac_f32_e32 v49, v50, v49
	v_div_scale_f32 v50, vcc, 1.0, v35, 1.0
	v_mul_f32_e32 v51, v50, v49
	v_fma_f32 v64, -v48, v51, v50
	v_fmac_f32_e32 v51, v64, v49
	v_fma_f32 v48, -v48, v51, v50
	v_div_fmas_f32 v48, v48, v49, v51
	v_div_fixup_f32 v35, v48, v35, 1.0
	v_mul_f32_e32 v48, 0xbfb8aa3b, v54
	v_rndne_f32_e32 v49, v48
	v_sub_f32_e32 v50, v48, v49
	v_fma_f32 v48, v54, s54, -v48
	v_fmac_f32_e32 v48, 0xb2a5705f, v54
	v_add_f32_e32 v48, v50, v48
	v_exp_f32_e32 v48, v48
	v_cvt_i32_f32_e32 v49, v49
	v_ldexp_f32 v48, v48, v49
	v_mul_f32_e32 v49, 0xbfb8aa3b, v38
	v_rndne_f32_e32 v50, v49
	v_sub_f32_e32 v51, v49, v50
	v_fma_f32 v49, v38, s54, -v49
	v_fmac_f32_e32 v49, 0xb2a5705f, v38
	v_add_f32_e32 v49, v51, v49
	v_exp_f32_e32 v49, v49
	v_cvt_i32_f32_e32 v50, v50
	v_ldexp_f32 v49, v49, v50
	s_nop 0
	s_nop 1
	s_nop 1
	v_mov_b32_e32 v50, v49
	v_mul_f32_e32 v49, 0xbfb8aa3b, v55
	v_rndne_f32_e32 v51, v49
	v_sub_f32_e32 v64, v49, v51
	v_fma_f32 v49, v55, s54, -v49
	v_fmac_f32_e32 v49, 0xb2a5705f, v55
	v_add_f32_e32 v49, v64, v49
	v_exp_f32_e32 v49, v49
	v_cvt_i32_f32_e32 v51, v51
	v_ldexp_f32 v49, v49, v51
	s_nop 0
	s_nop 1
	v_pk_add_f32 v[48:49], v[48:49], 1.0 op_sel_hi:[1,0]
	s_nop 0
	v_div_scale_f32 v51, s[42:43], v48, v48, 1.0
	v_rcp_f32_e32 v64, v51
	s_nop 0
	v_fma_f32 v65, -v51, v64, 1.0
	v_fmac_f32_e32 v64, v65, v64
	v_div_scale_f32 v65, vcc, 1.0, v48, 1.0
	v_mul_f32_e32 v66, v65, v64
	v_fma_f32 v67, -v51, v66, v65
	v_fmac_f32_e32 v66, v67, v64
	v_fma_f32 v51, -v51, v66, v65
	v_div_fmas_f32 v51, v51, v64, v66
	v_div_fixup_f32 v48, v51, v48, 1.0
	v_div_scale_f32 v51, s[42:43], v49, v49, 1.0
	v_rcp_f32_e32 v64, v51
	s_nop 0
	v_fma_f32 v65, -v51, v64, 1.0
	v_fmac_f32_e32 v64, v65, v64
	v_div_scale_f32 v65, vcc, 1.0, v49, 1.0
	v_mul_f32_e32 v66, v65, v64
	v_fma_f32 v67, -v51, v66, v65
	v_fmac_f32_e32 v66, v67, v64
	v_fma_f32 v51, -v51, v66, v65
	v_div_fmas_f32 v51, v51, v64, v66
	v_div_fixup_f32 v49, v51, v49, 1.0
	v_mul_f32_e32 v51, 0xbfb8aa3b, v39
	v_rndne_f32_e32 v64, v51
	v_sub_f32_e32 v65, v51, v64
	v_fma_f32 v51, v39, s54, -v51
	v_fmac_f32_e32 v51, 0xb2a5705f, v39
	v_add_f32_e32 v51, v65, v51
	v_exp_f32_e32 v51, v51
	v_cvt_i32_f32_e32 v64, v64
	v_ldexp_f32 v51, v51, v64
	s_nop 0
	s_nop 1
	v_pk_add_f32 v[50:51], v[50:51], 1.0 op_sel_hi:[1,0]
	s_nop 0
	v_div_scale_f32 v64, s[42:43], v50, v50, 1.0
	v_rcp_f32_e32 v65, v64
	s_nop 0
	v_fma_f32 v66, -v64, v65, 1.0
	v_fmac_f32_e32 v65, v66, v65
	v_div_scale_f32 v66, vcc, 1.0, v50, 1.0
	v_mul_f32_e32 v67, v66, v65
	v_fma_f32 v68, -v64, v67, v66
	v_fmac_f32_e32 v67, v68, v65
	v_fma_f32 v64, -v64, v67, v66
	v_div_fmas_f32 v64, v64, v65, v67
	v_div_fixup_f32 v50, v64, v50, 1.0
	v_div_scale_f32 v64, s[42:43], v51, v51, 1.0
	v_rcp_f32_e32 v65, v64
	s_nop 0
	v_fma_f32 v66, -v64, v65, 1.0
	v_fmac_f32_e32 v65, v66, v65
	v_div_scale_f32 v66, vcc, 1.0, v51, 1.0
	v_mul_f32_e32 v67, v66, v65
	v_fma_f32 v68, -v64, v67, v66
	v_fmac_f32_e32 v67, v68, v65
	v_fma_f32 v64, -v64, v67, v66
	v_div_fmas_f32 v64, v64, v65, v67
	v_div_fixup_f32 v51, v64, v51, 1.0

; DEVI void lds_put4(char* wl, int RS, int row, int col, float a, float b, float c, float d) { u32x2 w = {cvtpk(a, b), cvtpk(c, d)}; *(u32x2*)(wl + row * RS + col * 2) = w; }
; DEVI float sigmf(float x) { return 1.f / (1.f + expf(-x)); }
; DEVI void phase_gemm_in(const Params& p, int l, char* lds) {
;     ...
;           } else if (mode == 3) {
; #pragma unroll
;             for (int j = 0; j < 4; ++j) { x1[j] = sigmf(x1[j]); x2[j] = sigmf(x2[j]); }
;           }
;           lds_put4(wl, 272, mi * 32 + r32, cg2 * 64 + ci, x1[0], x1[1], x1[2], x1[3]);
;           lds_put4(wl, 272, mi * 32 + r32, cg2 * 64 + 32 + ci, x2[0], x2[1], x2[2], x2[3]);
.LBB0_261:
	s_or_b64 exec, exec, s[2:3]
	v_cvt_pk_bf16_f32 v32, v32, v33
	v_cvt_pk_bf16_f32 v33, v48, v49
	v_cvt_pk_bf16_f32 v34, v34, v35
	v_cvt_pk_bf16_f32 v35, v50, v51
	ds_write2_b64 v130, v[32:33], v[34:35] offset0:18 offset1:26
	s_and_saveexec_b64 s[2:3], s[14:15]
	s_xor_b64 s[2:3], exec, s[2:3]
	v_pk_mul_f32 v[32:33], v[56:57], s[96:97] op_sel_hi:[1,0]
	v_pk_mul_f32 v[34:35], v[40:41], s[96:97] op_sel_hi:[1,0]
	v_pk_mul_f32 v[36:37], v[58:59], s[96:97] op_sel_hi:[1,0]
	v_pk_mul_f32 v[38:39], v[42:43], s[96:97] op_sel_hi:[1,0]
	s_andn2_saveexec_b64 s[2:3], s[2:3]
	s_cbranch_execz .LBB0_273
	s_and_saveexec_b64 s[28:29], s[12:13]
	s_xor_b64 s[28:29], exec, s[28:29]
	s_cbranch_execz .LBB0_268
	v_mov_b32_e32 v37, v59
	v_mov_b32_e32 v36, v58
	v_mov_b32_e32 v33, v57
	v_mov_b32_e32 v32, v56
	v_mov_b32_e32 v39, v43
	v_mov_b32_e32 v38, v42
	v_mov_b32_e32 v35, v41
	v_mov_b32_e32 v34, v40
	s_and_saveexec_b64 s[30:31], s[10:11]
	s_cbranch_execz .LBB0_267
	v_mul_f32_e32 v32, 0xbfb8aa3b, v56
	v_rndne_f32_e32 v33, v32
	v_sub_f32_e32 v34, v32, v33
	v_fma_f32 v32, v56, s54, -v32
	v_fmac_f32_e32 v32, 0xb2a5705f, v56
	v_add_f32_e32 v32, v34, v32
	v_exp_f32_e32 v32, v32
	v_cvt_i32_f32_e32 v33, v33
	v_ldexp_f32 v32, v32, v33
	v_mul_f32_e32 v33, 0xbfb8aa3b, v40
	v_rndne_f32_e32 v34, v33
	v_sub_f32_e32 v35, v33, v34
	v_fma_f32 v33, v40, s54, -v33
	v_fmac_f32_e32 v33, 0xb2a5705f, v40
	v_add_f32_e32 v33, v35, v33
	v_exp_f32_e32 v33, v33
	v_cvt_i32_f32_e32 v34, v34
	v_ldexp_f32 v33, v33, v34
	s_nop 0
	s_nop 1
	s_nop 1
	v_mov_b32_e32 v34, v33
	v_mul_f32_e32 v33, 0xbfb8aa3b, v57
	v_rndne_f32_e32 v35, v33
	v_sub_f32_e32 v36, v33, v35
	v_fma_f32 v33, v57, s54, -v33
	v_fmac_f32_e32 v33, 0xb2a5705f, v57
	v_add_f32_e32 v33, v36, v33
	v_exp_f32_e32 v33, v33
	v_cvt_i32_f32_e32 v35, v35
	v_ldexp_f32 v33, v33, v35
	s_nop 0
	s_nop 1
	v_pk_add_f32 v[32:33], v[32:33], 1.0 op_sel_hi:[1,0]
	s_nop 0
	v_div_scale_f32 v35, s[42:43], v32, v32, 1.0
	v_rcp_f32_e32 v36, v35
	s_nop 0
	v_fma_f32 v37, -v35, v36, 1.0
	v_fmac_f32_e32 v36, v37, v36
	v_div_scale_f32 v37, vcc, 1.0, v32, 1.0
	v_mul_f32_e32 v38, v37, v36
	v_fma_f32 v39, -v35, v38, v37
	v_fmac_f32_e32 v38, v39, v36
	v_fma_f32 v35, -v35, v38, v37
	v_div_fmas_f32 v35, v35, v36, v38
	v_div_fixup_f32 v32, v35, v32, 1.0
	v_div_scale_f32 v35, s[42:43], v33, v33, 1.0
	v_rcp_f32_e32 v36, v35
	s_nop 0
	v_fma_f32 v37, -v35, v36, 1.0
	v_fmac_f32_e32 v36, v37, v36
	v_div_scale_f32 v37, vcc, 1.0, v33, 1.0
	v_mul_f32_e32 v38, v37, v36
	v_fma_f32 v39, -v35, v38, v37
	v_fmac_f32_e32 v38, v39, v36
	v_fma_f32 v35, -v35, v38, v37
	v_div_fmas_f32 v35, v35, v36, v38
	v_div_fixup_f32 v33, v35, v33, 1.0
	v_mul_f32_e32 v35, 0xbfb8aa3b, v41
	v_rndne_f32_e32 v36, v35
	v_sub_f32_e32 v37, v35, v36
	v_fma_f32 v35, v41, s54, -v35
	v_fmac_f32_e32 v35, 0xb2a5705f, v41
	v_add_f32_e32 v35, v37, v35
	v_exp_f32_e32 v35, v35
	v_cvt_i32_f32_e32 v36, v36
	v_ldexp_f32 v35, v35, v36
	s_nop 0
	s_nop 1
	v_pk_add_f32 v[34:35], v[34:35], 1.0 op_sel_hi:[1,0]
	s_nop 0
	v_div_scale_f32 v36, s[42:43], v34, v34, 1.0
	v_rcp_f32_e32 v37, v36
	s_nop 0
	v_fma_f32 v38, -v36, v37, 1.0
	v_fmac_f32_e32 v37, v38, v37
	v_div_scale_f32 v38, vcc, 1.0, v34, 1.0
	v_mul_f32_e32 v39, v38, v37
	v_fma_f32 v48, -v36, v39, v38
	v_fmac_f32_e32 v39, v48, v37
	v_fma_f32 v36, -v36, v39, v38
	v_div_fmas_f32 v36, v36, v37, v39
	v_div_fixup_f32 v34, v36, v34, 1.0
	v_div_scale_f32 v36, s[42:43], v35, v35, 1.0
	v_rcp_f32_e32 v37, v36
	s_nop 0
	v_fma_f32 v38, -v36, v37, 1.0
	v_fmac_f32_e32 v37, v38, v37
	v_div_scale_f32 v38, vcc, 1.0, v35, 1.0
	v_mul_f32_e32 v39, v38, v37
	v_fma_f32 v48, -v36, v39, v38
	v_fmac_f32_e32 v39, v48, v37
	v_fma_f32 v36, -v36, v39, v38
	v_div_fmas_f32 v36, v36, v37, v39
	v_div_fixup_f32 v35, v36, v35, 1.0
	v_mul_f32_e32 v36, 0xbfb8aa3b, v58
	v_rndne_f32_e32 v37, v36
	v_sub_f32_e32 v38, v36, v37
	v_fma_f32 v36, v58, s54, -v36
	v_fmac_f32_e32 v36, 0xb2a5705f, v58
	v_add_f32_e32 v36, v38, v36
	v_exp_f32_e32 v36, v36
	v_cvt_i32_f32_e32 v37, v37
	v_ldexp_f32 v36, v36, v37
	v_mul_f32_e32 v37, 0xbfb8aa3b, v42
	v_rndne_f32_e32 v38, v37
	v_sub_f32_e32 v39, v37, v38
	v_fma_f32 v37, v42, s54, -v37
	v_fmac_f32_e32 v37, 0xb2a5705f, v42
	v_add_f32_e32 v37, v39, v37
	v_exp_f32_e32 v37, v37
	v_cvt_i32_f32_e32 v38, v38
	v_ldexp_f32 v37, v37, v38
	s_nop 0
	s_nop 1
	s_nop 1
	v_mov_b32_e32 v38, v37
	v_mul_f32_e32 v37, 0xbfb8aa3b, v59
	v_rndne_f32_e32 v39, v37
	v_sub_f32_e32 v48, v37, v39
	v_fma_f32 v37, v59, s54, -v37
	v_fmac_f32_e32 v37, 0xb2a5705f, v59
	v_add_f32_e32 v37, v48, v37
	v_exp_f32_e32 v37, v37
	v_cvt_i32_f32_e32 v39, v39
	v_ldexp_f32 v37, v37, v39
	s_nop 0
	s_nop 1
	v_pk_add_f32 v[36:37], v[36:37], 1.0 op_sel_hi:[1,0]
	s_nop 0
	v_div_scale_f32 v39, s[42:43], v36, v36, 1.0
	v_rcp_f32_e32 v48, v39
	s_nop 0
	v_fma_f32 v49, -v39, v48, 1.0
	v_fmac_f32_e32 v48, v49, v48
	v_div_scale_f32 v49, vcc, 1.0, v36, 1.0
	v_mul_f32_e32 v50, v49, v48
	v_fma_f32 v51, -v39, v50, v49
	v_fmac_f32_e32 v50, v51, v48
	v_fma_f32 v39, -v39, v50, v49
	v_div_fmas_f32 v39, v39, v48, v50
	v_div_fixup_f32 v36, v39, v36, 1.0
	v_div_scale_f32 v39, s[42:43], v37, v37, 1.0
	v_rcp_f32_e32 v48, v39
	s_nop 0
	v_fma_f32 v49, -v39, v48, 1.0
	v_fmac_f32_e32 v48, v49, v48
	v_div_scale_f32 v49, vcc, 1.0, v37, 1.0
	v_mul_f32_e32 v50, v49, v48
	v_fma_f32 v51, -v39, v50, v49
	v_fmac_f32_e32 v50, v51, v48
	v_fma_f32 v39, -v39, v50, v49
	v_div_fmas_f32 v39, v39, v48, v50
	v_div_fixup_f32 v37, v39, v37, 1.0
	v_mul_f32_e32 v39, 0xbfb8aa3b, v43
	v_rndne_f32_e32 v48, v39
	v_sub_f32_e32 v49, v39, v48
	v_fma_f32 v39, v43, s54, -v39
	v_fmac_f32_e32 v39, 0xb2a5705f, v43
	v_add_f32_e32 v39, v49, v39
	v_exp_f32_e32 v39, v39
	v_cvt_i32_f32_e32 v48, v48
	v_ldexp_f32 v39, v39, v48
	s_nop 0
	s_nop 1
	v_pk_add_f32 v[38:39], v[38:39], 1.0 op_sel_hi:[1,0]
	s_nop 0
	v_div_scale_f32 v48, s[42:43], v38, v38, 1.0
	v_rcp_f32_e32 v49, v48
	s_nop 0
	v_fma_f32 v50, -v48, v49, 1.0
	v_fmac_f32_e32 v49, v50, v49
	v_div_scale_f32 v50, vcc, 1.0, v38, 1.0
	v_mul_f32_e32 v51, v50, v49
	v_fma_f32 v52, -v48, v51, v50
	v_fmac_f32_e32 v51, v52, v49
	v_fma_f32 v48, -v48, v51, v50
	v_div_fmas_f32 v48, v48, v49, v51
	v_div_fixup_f32 v38, v48, v38, 1.0
	v_div_scale_f32 v48, s[42:43], v39, v39, 1.0
	v_rcp_f32_e32 v49, v48
	s_nop 0
	v_fma_f32 v50, -v48, v49, 1.0
	v_fmac_f32_e32 v49, v50, v49
	v_div_scale_f32 v50, vcc, 1.0, v39, 1.0
	v_mul_f32_e32 v51, v50, v49
	v_fma_f32 v52, -v48, v51, v50
	v_fmac_f32_e32 v51, v52, v49
	v_fma_f32 v48, -v48, v51, v50
	v_div_fmas_f32 v48, v48, v49, v51
	v_div_fixup_f32 v39, v48, v39, 1.0

; DEVI void lds_put4(char* wl, int RS, int row, int col, float a, float b, float c, float d) { u32x2 w = {cvtpk(a, b), cvtpk(c, d)}; *(u32x2*)(wl + row * RS + col * 2) = w; }
; DEVI float sigmf(float x) { return 1.f / (1.f + expf(-x)); }
; DEVI void phase_gemm_in(const Params& p, int l, char* lds) {
;     ...
;           } else if (mode == 3) {
; #pragma unroll
;             for (int j = 0; j < 4; ++j) { x1[j] = sigmf(x1[j]); x2[j] = sigmf(x2[j]); }
;           }
;           lds_put4(wl, 272, mi * 32 + r32, cg2 * 64 + ci, x1[0], x1[1], x1[2], x1[3]);
;           lds_put4(wl, 272, mi * 32 + r32, cg2 * 64 + 32 + ci, x2[0], x2[1], x2[2], x2[3]);
.LBB0_273:
	s_or_b64 exec, exec, s[2:3]
	v_cvt_pk_bf16_f32 v32, v32, v33
	v_cvt_pk_bf16_f32 v33, v36, v37
	v_cvt_pk_bf16_f32 v34, v34, v35
	v_cvt_pk_bf16_f32 v35, v38, v39
	ds_write2_b64 v130, v[32:33], v[34:35] offset0:20 offset1:28
	s_and_saveexec_b64 s[2:3], s[14:15]
	s_xor_b64 s[2:3], exec, s[2:3]
	v_pk_mul_f32 v[60:61], v[60:61], s[96:97] op_sel_hi:[1,0]
	v_pk_mul_f32 v[44:45], v[44:45], s[96:97] op_sel_hi:[1,0]
	v_pk_mul_f32 v[62:63], v[62:63], s[96:97] op_sel_hi:[1,0]
	v_pk_mul_f32 v[46:47], v[46:47], s[96:97] op_sel_hi:[1,0]
	s_andn2_saveexec_b64 s[2:3], s[2:3]
	s_cbranch_execz .LBB0_285
	s_and_saveexec_b64 s[28:29], s[12:13]
	s_xor_b64 s[28:29], exec, s[28:29]
	s_cbranch_execz .LBB0_280
	s_and_saveexec_b64 s[30:31], s[10:11]
	s_cbranch_execz .LBB0_279
	v_mul_f32_e32 v32, 0xbfb8aa3b, v60
	v_rndne_f32_e32 v33, v32
	v_sub_f32_e32 v34, v32, v33
	v_fma_f32 v32, v60, s54, -v32
	v_fmac_f32_e32 v32, 0xb2a5705f, v60
	v_add_f32_e32 v32, v34, v32
	v_exp_f32_e32 v32, v32
	v_cvt_i32_f32_e32 v33, v33
	v_ldexp_f32 v32, v32, v33
	v_mul_f32_e32 v33, 0xbfb8aa3b, v44
	v_rndne_f32_e32 v34, v33
	v_sub_f32_e32 v35, v33, v34
	v_fma_f32 v33, v44, s54, -v33
	v_fmac_f32_e32 v33, 0xb2a5705f, v44
	v_add_f32_e32 v33, v35, v33
	v_exp_f32_e32 v33, v33
	v_cvt_i32_f32_e32 v34, v34
	v_ldexp_f32 v33, v33, v34
	s_nop 0
	s_nop 1
	s_nop 1
	v_mov_b32_e32 v34, v33
	v_mul_f32_e32 v33, 0xbfb8aa3b, v61
	v_rndne_f32_e32 v35, v33
	v_sub_f32_e32 v36, v33, v35
	v_fma_f32 v33, v61, s54, -v33
	v_fmac_f32_e32 v33, 0xb2a5705f, v61
	v_add_f32_e32 v33, v36, v33
	v_exp_f32_e32 v33, v33
	v_cvt_i32_f32_e32 v35, v35
	v_ldexp_f32 v33, v33, v35
	s_nop 0
	s_nop 1
	v_pk_add_f32 v[32:33], v[32:33], 1.0 op_sel_hi:[1,0]
	s_nop 0
	v_div_scale_f32 v35, s[42:43], v32, v32, 1.0
	v_rcp_f32_e32 v36, v35
	s_nop 0
	v_fma_f32 v37, -v35, v36, 1.0
	v_fmac_f32_e32 v36, v37, v36
	v_div_scale_f32 v37, vcc, 1.0, v32, 1.0
	v_mul_f32_e32 v38, v37, v36
	v_fma_f32 v39, -v35, v38, v37
	v_fmac_f32_e32 v38, v39, v36
	v_fma_f32 v35, -v35, v38, v37
	v_div_fmas_f32 v35, v35, v36, v38
	v_div_fixup_f32 v60, v35, v32, 1.0
	v_div_scale_f32 v32, s[42:43], v33, v33, 1.0
	v_rcp_f32_e32 v35, v32
	s_nop 0
	v_fma_f32 v36, -v32, v35, 1.0
	v_fmac_f32_e32 v35, v36, v35
	v_div_scale_f32 v36, vcc, 1.0, v33, 1.0
	v_mul_f32_e32 v37, v36, v35
	v_fma_f32 v38, -v32, v37, v36
	v_fmac_f32_e32 v37, v38, v35
	v_fma_f32 v32, -v32, v37, v36
	v_div_fmas_f32 v32, v32, v35, v37
	v_div_fixup_f32 v61, v32, v33, 1.0
	v_mul_f32_e32 v32, 0xbfb8aa3b, v45
	v_rndne_f32_e32 v33, v32
	v_sub_f32_e32 v35, v32, v33
	v_fma_f32 v32, v45, s54, -v32
	v_fmac_f32_e32 v32, 0xb2a5705f, v45
	v_add_f32_e32 v32, v35, v32
	v_exp_f32_e32 v32, v32
	v_cvt_i32_f32_e32 v33, v33
	v_ldexp_f32 v32, v32, v33
	s_nop 0
	s_nop 1
	v_mov_b32_e32 v35, v32
	v_pk_add_f32 v[32:33], v[34:35], 1.0 op_sel_hi:[1,0]
	s_nop 0
	v_div_scale_f32 v34, s[42:43], v32, v32, 1.0
	v_rcp_f32_e32 v35, v34
	s_nop 0
	v_fma_f32 v36, -v34, v35, 1.0
	v_fmac_f32_e32 v35, v36, v35
	v_div_scale_f32 v36, vcc, 1.0, v32, 1.0
	v_mul_f32_e32 v37, v36, v35
	v_fma_f32 v38, -v34, v37, v36
	v_fmac_f32_e32 v37, v38, v35
	v_fma_f32 v34, -v34, v37, v36
	v_div_fmas_f32 v34, v34, v35, v37
	v_div_fixup_f32 v44, v34, v32, 1.0
	v_div_scale_f32 v32, s[42:43], v33, v33, 1.0
	v_rcp_f32_e32 v34, v32
	s_nop 0
	v_fma_f32 v35, -v32, v34, 1.0
	v_fmac_f32_e32 v34, v35, v34
	v_div_scale_f32 v35, vcc, 1.0, v33, 1.0
	v_mul_f32_e32 v36, v35, v34
	v_fma_f32 v37, -v32, v36, v35
	v_fmac_f32_e32 v36, v37, v34
	v_fma_f32 v32, -v32, v36, v35
	v_div_fmas_f32 v32, v32, v34, v36
	v_div_fixup_f32 v45, v32, v33, 1.0
	v_mul_f32_e32 v32, 0xbfb8aa3b, v62
	v_rndne_f32_e32 v33, v32
	v_sub_f32_e32 v34, v32, v33
	v_fma_f32 v32, v62, s54, -v32
	v_fmac_f32_e32 v32, 0xb2a5705f, v62
	v_add_f32_e32 v32, v34, v32
	v_exp_f32_e32 v32, v32
	v_cvt_i32_f32_e32 v33, v33
	v_ldexp_f32 v32, v32, v33
	v_mul_f32_e32 v33, 0xbfb8aa3b, v46
	v_rndne_f32_e32 v34, v33
	v_sub_f32_e32 v35, v33, v34
	v_fma_f32 v33, v46, s54, -v33
	v_fmac_f32_e32 v33, 0xb2a5705f, v46
	v_add_f32_e32 v33, v35, v33
	v_exp_f32_e32 v33, v33
	v_cvt_i32_f32_e32 v34, v34
	v_ldexp_f32 v33, v33, v34
	s_nop 0
	s_nop 1
	s_nop 1
	v_mov_b32_e32 v34, v33
	v_mul_f32_e32 v33, 0xbfb8aa3b, v63
	v_rndne_f32_e32 v35, v33
	v_sub_f32_e32 v36, v33, v35
	v_fma_f32 v33, v63, s54, -v33
	v_fmac_f32_e32 v33, 0xb2a5705f, v63
	v_add_f32_e32 v33, v36, v33
	v_exp_f32_e32 v33, v33
	v_cvt_i32_f32_e32 v35, v35
	v_ldexp_f32 v33, v33, v35
	s_nop 0
	s_nop 1
	v_pk_add_f32 v[32:33], v[32:33], 1.0 op_sel_hi:[1,0]
	s_nop 0
	v_div_scale_f32 v35, s[42:43], v32, v32, 1.0
	v_rcp_f32_e32 v36, v35
	s_nop 0
	v_fma_f32 v37, -v35, v36, 1.0
	v_fmac_f32_e32 v36, v37, v36
	v_div_scale_f32 v37, vcc, 1.0, v32, 1.0
	v_mul_f32_e32 v38, v37, v36
	v_fma_f32 v39, -v35, v38, v37
	v_fmac_f32_e32 v38, v39, v36
	v_fma_f32 v35, -v35, v38, v37
	v_div_fmas_f32 v35, v35, v36, v38
	v_div_fixup_f32 v62, v35, v32, 1.0
	v_div_scale_f32 v32, s[42:43], v33, v33, 1.0
	v_rcp_f32_e32 v35, v32
	s_nop 0
	v_fma_f32 v36, -v32, v35, 1.0
	v_fmac_f32_e32 v35, v36, v35
	v_div_scale_f32 v36, vcc, 1.0, v33, 1.0
	v_mul_f32_e32 v37, v36, v35
	v_fma_f32 v38, -v32, v37, v36
	v_fmac_f32_e32 v37, v38, v35
	v_fma_f32 v32, -v32, v37, v36
	v_div_fmas_f32 v32, v32, v35, v37
	v_div_fixup_f32 v63, v32, v33, 1.0
	v_mul_f32_e32 v32, 0xbfb8aa3b, v47
	v_rndne_f32_e32 v33, v32
	v_sub_f32_e32 v35, v32, v33
	v_fma_f32 v32, v47, s54, -v32
	v_fmac_f32_e32 v32, 0xb2a5705f, v47
	v_add_f32_e32 v32, v35, v32
	v_exp_f32_e32 v32, v32
	v_cvt_i32_f32_e32 v33, v33
	v_ldexp_f32 v32, v32, v33
	s_nop 0
	s_nop 1
	v_mov_b32_e32 v35, v32
	v_pk_add_f32 v[32:33], v[34:35], 1.0 op_sel_hi:[1,0]
	s_nop 0
	v_div_scale_f32 v34, s[42:43], v32, v32, 1.0
	v_rcp_f32_e32 v35, v34
	s_nop 0
	v_fma_f32 v36, -v34, v35, 1.0
	v_fmac_f32_e32 v35, v36, v35
	v_div_scale_f32 v36, vcc, 1.0, v32, 1.0
	v_mul_f32_e32 v37, v36, v35
	v_fma_f32 v38, -v34, v37, v36
	v_fmac_f32_e32 v37, v38, v35
	v_fma_f32 v34, -v34, v37, v36
	v_div_fmas_f32 v34, v34, v35, v37
	v_div_fixup_f32 v46, v34, v32, 1.0
	v_div_scale_f32 v32, s[42:43], v33, v33, 1.0
	v_rcp_f32_e32 v34, v32
	s_nop 0
	v_fma_f32 v35, -v32, v34, 1.0
	v_fmac_f32_e32 v34, v35, v34
	v_div_scale_f32 v35, vcc, 1.0, v33, 1.0
	v_mul_f32_e32 v36, v35, v34
	v_fma_f32 v37, -v32, v36, v35
	v_fmac_f32_e32 v36, v37, v34
	v_fma_f32 v32, -v32, v36, v35
	v_div_fmas_f32 v32, v32, v34, v36
	v_div_fixup_f32 v47, v32, v33, 1.0

; DEVI void lds_put4(char* wl, int RS, int row, int col, float a, float b, float c, float d) { u32x2 w = {cvtpk(a, b), cvtpk(c, d)}; *(u32x2*)(wl + row * RS + col * 2) = w; }
; DEVI float sigmf(float x) { return 1.f / (1.f + expf(-x)); }
; DEVI void phase_gemm_in(const Params& p, int l, char* lds) {
;     ...
;           } else if (mode == 3) {
; #pragma unroll
;             for (int j = 0; j < 4; ++j) { x1[j] = sigmf(x1[j]); x2[j] = sigmf(x2[j]); }
;           }
;           lds_put4(wl, 272, mi * 32 + r32, cg2 * 64 + ci, x1[0], x1[1], x1[2], x1[3]);
;           lds_put4(wl, 272, mi * 32 + r32, cg2 * 64 + 32 + ci, x2[0], x2[1], x2[2], x2[3]);
.LBB0_285:
	s_or_b64 exec, exec, s[2:3]
	v_cvt_pk_bf16_f32 v32, v60, v61
	v_cvt_pk_bf16_f32 v33, v62, v63
	v_cvt_pk_bf16_f32 v34, v44, v45
	v_cvt_pk_bf16_f32 v35, v46, v47
	ds_write2_b64 v130, v[32:33], v[34:35] offset0:22 offset1:30
	s_and_saveexec_b64 s[2:3], s[14:15]
	s_xor_b64 s[2:3], exec, s[2:3]
	v_pk_mul_f32 v[32:33], v[16:17], s[96:97] op_sel_hi:[1,0]
	v_pk_mul_f32 v[34:35], v[0:1], s[96:97] op_sel_hi:[1,0]
	v_pk_mul_f32 v[36:37], v[18:19], s[96:97] op_sel_hi:[1,0]
	v_pk_mul_f32 v[38:39], v[2:3], s[96:97] op_sel_hi:[1,0]
	s_andn2_saveexec_b64 s[2:3], s[2:3]
	s_cbranch_execz .LBB0_297
	s_and_saveexec_b64 s[6:7], s[12:13]
	s_xor_b64 s[6:7], exec, s[6:7]
	s_cbranch_execz .LBB0_292
	v_mov_b32_e32 v37, v19
	v_mov_b32_e32 v36, v18
	v_mov_b32_e32 v33, v17
	v_mov_b32_e32 v32, v16
	v_mov_b32_e32 v39, v3
	v_mov_b32_e32 v38, v2
	v_mov_b32_e32 v35, v1
	v_mov_b32_e32 v34, v0
	s_and_saveexec_b64 s[28:29], s[10:11]
	s_cbranch_execz .LBB0_291
	v_mul_f32_e32 v32, 0xbfb8aa3b, v16
	v_rndne_f32_e32 v33, v32
	v_sub_f32_e32 v34, v32, v33
	v_fma_f32 v32, v16, s54, -v32
	v_fmac_f32_e32 v32, 0xb2a5705f, v16
	v_add_f32_e32 v32, v34, v32
	v_exp_f32_e32 v32, v32
	v_cvt_i32_f32_e32 v33, v33
	v_ldexp_f32 v32, v32, v33
	v_mul_f32_e32 v33, 0xbfb8aa3b, v0
	v_rndne_f32_e32 v34, v33
	v_sub_f32_e32 v35, v33, v34
	v_fma_f32 v33, v0, s54, -v33
	v_fmac_f32_e32 v33, 0xb2a5705f, v0
	v_add_f32_e32 v33, v35, v33
	v_exp_f32_e32 v33, v33
	v_cvt_i32_f32_e32 v34, v34
	v_ldexp_f32 v33, v33, v34
	s_nop 0
	s_nop 1
	s_nop 1
	v_mov_b32_e32 v34, v33
	v_mul_f32_e32 v33, 0xbfb8aa3b, v17
	v_rndne_f32_e32 v35, v33
	v_sub_f32_e32 v36, v33, v35
	v_fma_f32 v33, v17, s54, -v33
	v_fmac_f32_e32 v33, 0xb2a5705f, v17
	v_add_f32_e32 v33, v36, v33
	v_exp_f32_e32 v33, v33
	v_cvt_i32_f32_e32 v35, v35
	v_ldexp_f32 v33, v33, v35
	s_nop 0
	s_nop 1
	v_pk_add_f32 v[32:33], v[32:33], 1.0 op_sel_hi:[1,0]
	s_nop 0
	v_div_scale_f32 v35, s[30:31], v32, v32, 1.0
	v_rcp_f32_e32 v36, v35
	s_nop 0
	v_fma_f32 v37, -v35, v36, 1.0
	v_fmac_f32_e32 v36, v37, v36
	v_div_scale_f32 v37, vcc, 1.0, v32, 1.0
	v_mul_f32_e32 v38, v37, v36
	v_fma_f32 v39, -v35, v38, v37
	v_fmac_f32_e32 v38, v39, v36
	v_fma_f32 v35, -v35, v38, v37
	v_div_fmas_f32 v35, v35, v36, v38
	v_div_fixup_f32 v32, v35, v32, 1.0
	v_div_scale_f32 v35, s[30:31], v33, v33, 1.0
	v_rcp_f32_e32 v36, v35
	s_nop 0
	v_fma_f32 v37, -v35, v36, 1.0
	v_fmac_f32_e32 v36, v37, v36
	v_div_scale_f32 v37, vcc, 1.0, v33, 1.0
	v_mul_f32_e32 v38, v37, v36
	v_fma_f32 v39, -v35, v38, v37
	v_fmac_f32_e32 v38, v39, v36
	v_fma_f32 v35, -v35, v38, v37
	v_div_fmas_f32 v35, v35, v36, v38
	v_div_fixup_f32 v33, v35, v33, 1.0
	v_mul_f32_e32 v35, 0xbfb8aa3b, v1
	v_rndne_f32_e32 v36, v35
	v_sub_f32_e32 v37, v35, v36
	v_fma_f32 v35, v1, s54, -v35
	v_fmac_f32_e32 v35, 0xb2a5705f, v1
	v_add_f32_e32 v35, v37, v35
	v_exp_f32_e32 v35, v35
	v_cvt_i32_f32_e32 v36, v36
	v_ldexp_f32 v35, v35, v36
	s_nop 0
	s_nop 1
	v_pk_add_f32 v[34:35], v[34:35], 1.0 op_sel_hi:[1,0]
	s_nop 0
	v_div_scale_f32 v36, s[30:31], v34, v34, 1.0
	v_rcp_f32_e32 v37, v36
	s_nop 0
	v_fma_f32 v38, -v36, v37, 1.0
	v_fmac_f32_e32 v37, v38, v37
	v_div_scale_f32 v38, vcc, 1.0, v34, 1.0
	v_mul_f32_e32 v39, v38, v37
	v_fma_f32 v40, -v36, v39, v38
	v_fmac_f32_e32 v39, v40, v37
	v_fma_f32 v36, -v36, v39, v38
	v_div_fmas_f32 v36, v36, v37, v39
	v_div_fixup_f32 v34, v36, v34, 1.0
	v_div_scale_f32 v36, s[30:31], v35, v35, 1.0
	v_rcp_f32_e32 v37, v36
	s_nop 0
	v_fma_f32 v38, -v36, v37, 1.0
	v_fmac_f32_e32 v37, v38, v37
	v_div_scale_f32 v38, vcc, 1.0, v35, 1.0
	v_mul_f32_e32 v39, v38, v37
	v_fma_f32 v40, -v36, v39, v38
	v_fmac_f32_e32 v39, v40, v37
	v_fma_f32 v36, -v36, v39, v38
	v_div_fmas_f32 v36, v36, v37, v39
	v_div_fixup_f32 v35, v36, v35, 1.0
	v_mul_f32_e32 v36, 0xbfb8aa3b, v18
	v_rndne_f32_e32 v37, v36
	v_sub_f32_e32 v38, v36, v37
	v_fma_f32 v36, v18, s54, -v36
	v_fmac_f32_e32 v36, 0xb2a5705f, v18
	v_add_f32_e32 v36, v38, v36
	v_exp_f32_e32 v36, v36
	v_cvt_i32_f32_e32 v37, v37
	v_ldexp_f32 v36, v36, v37
	v_mul_f32_e32 v37, 0xbfb8aa3b, v2
	v_rndne_f32_e32 v38, v37
	v_sub_f32_e32 v39, v37, v38
	v_fma_f32 v37, v2, s54, -v37
	v_fmac_f32_e32 v37, 0xb2a5705f, v2
	v_add_f32_e32 v37, v39, v37
	v_exp_f32_e32 v37, v37
	v_cvt_i32_f32_e32 v38, v38
	v_ldexp_f32 v37, v37, v38
	s_nop 0
	s_nop 1
	s_nop 1
	v_mov_b32_e32 v38, v37
	v_mul_f32_e32 v37, 0xbfb8aa3b, v19
	v_rndne_f32_e32 v39, v37
	v_sub_f32_e32 v40, v37, v39
	v_fma_f32 v37, v19, s54, -v37
	v_fmac_f32_e32 v37, 0xb2a5705f, v19
	v_add_f32_e32 v37, v40, v37
	v_exp_f32_e32 v37, v37
	v_cvt_i32_f32_e32 v39, v39
	v_ldexp_f32 v37, v37, v39
	s_nop 0
	s_nop 1
	v_pk_add_f32 v[36:37], v[36:37], 1.0 op_sel_hi:[1,0]
	s_nop 0
	v_div_scale_f32 v39, s[30:31], v36, v36, 1.0
	v_rcp_f32_e32 v40, v39
	s_nop 0
	v_fma_f32 v41, -v39, v40, 1.0
	v_fmac_f32_e32 v40, v41, v40
	v_div_scale_f32 v41, vcc, 1.0, v36, 1.0
	v_mul_f32_e32 v42, v41, v40
	v_fma_f32 v43, -v39, v42, v41
	v_fmac_f32_e32 v42, v43, v40
	v_fma_f32 v39, -v39, v42, v41
	v_div_fmas_f32 v39, v39, v40, v42
	v_div_fixup_f32 v36, v39, v36, 1.0
	v_div_scale_f32 v39, s[30:31], v37, v37, 1.0
	v_rcp_f32_e32 v40, v39
	s_nop 0
	v_fma_f32 v41, -v39, v40, 1.0
	v_fmac_f32_e32 v40, v41, v40
	v_div_scale_f32 v41, vcc, 1.0, v37, 1.0
	v_mul_f32_e32 v42, v41, v40
	v_fma_f32 v43, -v39, v42, v41
	v_fmac_f32_e32 v42, v43, v40
	v_fma_f32 v39, -v39, v42, v41
	v_div_fmas_f32 v39, v39, v40, v42
	v_div_fixup_f32 v37, v39, v37, 1.0
	v_mul_f32_e32 v39, 0xbfb8aa3b, v3
	v_rndne_f32_e32 v40, v39
	v_sub_f32_e32 v41, v39, v40
	v_fma_f32 v39, v3, s54, -v39
	v_fmac_f32_e32 v39, 0xb2a5705f, v3
	v_add_f32_e32 v39, v41, v39
	v_exp_f32_e32 v39, v39
	v_cvt_i32_f32_e32 v40, v40
	v_ldexp_f32 v39, v39, v40
	s_nop 0
	s_nop 1
	v_pk_add_f32 v[38:39], v[38:39], 1.0 op_sel_hi:[1,0]
	s_nop 0
	v_div_scale_f32 v40, s[30:31], v38, v38, 1.0
	v_rcp_f32_e32 v41, v40
	s_nop 0
	v_fma_f32 v42, -v40, v41, 1.0
	v_fmac_f32_e32 v41, v42, v41
	v_div_scale_f32 v42, vcc, 1.0, v38, 1.0
	v_mul_f32_e32 v43, v42, v41
	v_fma_f32 v44, -v40, v43, v42
	v_fmac_f32_e32 v43, v44, v41
	v_fma_f32 v40, -v40, v43, v42
	v_div_fmas_f32 v40, v40, v41, v43
	v_div_fixup_f32 v38, v40, v38, 1.0
	v_div_scale_f32 v40, s[30:31], v39, v39, 1.0
	v_rcp_f32_e32 v41, v40
	s_nop 0
	v_fma_f32 v42, -v40, v41, 1.0
	v_fmac_f32_e32 v41, v42, v41
	v_div_scale_f32 v42, vcc, 1.0, v39, 1.0
	v_mul_f32_e32 v43, v42, v41
	v_fma_f32 v44, -v40, v43, v42
	v_fmac_f32_e32 v43, v44, v41
	v_fma_f32 v40, -v40, v43, v42
	v_div_fmas_f32 v40, v40, v41, v43
	v_div_fixup_f32 v39, v40, v39, 1.0

; DEVI void lds_put4(char* wl, int RS, int row, int col, float a, float b, float c, float d) { u32x2 w = {cvtpk(a, b), cvtpk(c, d)}; *(u32x2*)(wl + row * RS + col * 2) = w; }
; DEVI float sigmf(float x) { return 1.f / (1.f + expf(-x)); }
; DEVI void phase_gemm_in(const Params& p, int l, char* lds) {
;     ...
;           } else if (mode == 3) {
; #pragma unroll
;             for (int j = 0; j < 4; ++j) { x1[j] = sigmf(x1[j]); x2[j] = sigmf(x2[j]); }
;           }
;           lds_put4(wl, 272, mi * 32 + r32, cg2 * 64 + ci, x1[0], x1[1], x1[2], x1[3]);
;           lds_put4(wl, 272, mi * 32 + r32, cg2 * 64 + 32 + ci, x2[0], x2[1], x2[2], x2[3]);
.LBB0_297:
	s_or_b64 exec, exec, s[2:3]
	v_cvt_pk_bf16_f32 v0, v32, v33
	v_cvt_pk_bf16_f32 v1, v36, v37
	v_cvt_pk_bf16_f32 v2, v34, v35
	v_cvt_pk_bf16_f32 v3, v38, v39
	ds_write2_b64 v98, v[0:1], v[2:3] offset0:80 offset1:88
	s_and_saveexec_b64 s[2:3], s[14:15]
	s_xor_b64 s[2:3], exec, s[2:3]
	v_pk_mul_f32 v[0:1], v[20:21], s[96:97] op_sel_hi:[1,0]
	v_pk_mul_f32 v[2:3], v[4:5], s[96:97] op_sel_hi:[1,0]
	v_pk_mul_f32 v[16:17], v[22:23], s[96:97] op_sel_hi:[1,0]
	v_pk_mul_f32 v[18:19], v[6:7], s[96:97] op_sel_hi:[1,0]
	s_andn2_saveexec_b64 s[2:3], s[2:3]
	s_cbranch_execz .LBB0_309
	s_and_saveexec_b64 s[6:7], s[12:13]
	s_xor_b64 s[6:7], exec, s[6:7]
	s_cbranch_execz .LBB0_304
	v_mov_b32_e32 v17, v23
	v_mov_b32_e32 v16, v22
	v_mov_b32_e32 v1, v21
	v_mov_b32_e32 v0, v20
	v_mov_b32_e32 v19, v7
	v_mov_b32_e32 v18, v6
	v_mov_b32_e32 v3, v5
	v_mov_b32_e32 v2, v4
	s_and_saveexec_b64 s[28:29], s[10:11]
	s_cbranch_execz .LBB0_303
	v_mul_f32_e32 v0, 0xbfb8aa3b, v20
	v_rndne_f32_e32 v1, v0
	v_sub_f32_e32 v2, v0, v1
	v_fma_f32 v0, v20, s54, -v0
	v_fmac_f32_e32 v0, 0xb2a5705f, v20
	v_add_f32_e32 v0, v2, v0
	v_exp_f32_e32 v0, v0
	v_cvt_i32_f32_e32 v1, v1
	v_ldexp_f32 v0, v0, v1
	v_mul_f32_e32 v1, 0xbfb8aa3b, v4
	v_rndne_f32_e32 v2, v1
	v_sub_f32_e32 v3, v1, v2
	v_fma_f32 v1, v4, s54, -v1
	v_fmac_f32_e32 v1, 0xb2a5705f, v4
	v_add_f32_e32 v1, v3, v1
	v_exp_f32_e32 v1, v1
	v_cvt_i32_f32_e32 v2, v2
	v_ldexp_f32 v1, v1, v2
	s_nop 0
	s_nop 1
	s_nop 1
	v_mov_b32_e32 v2, v1
	v_mul_f32_e32 v1, 0xbfb8aa3b, v21
	v_rndne_f32_e32 v3, v1
	v_sub_f32_e32 v16, v1, v3
	v_fma_f32 v1, v21, s54, -v1
	v_fmac_f32_e32 v1, 0xb2a5705f, v21
	v_add_f32_e32 v1, v16, v1
	v_exp_f32_e32 v1, v1
	v_cvt_i32_f32_e32 v3, v3
	v_ldexp_f32 v1, v1, v3
	s_nop 0
	s_nop 1
	v_pk_add_f32 v[0:1], v[0:1], 1.0 op_sel_hi:[1,0]
	s_nop 0
	v_div_scale_f32 v3, s[30:31], v0, v0, 1.0
	v_rcp_f32_e32 v16, v3
	s_nop 0
	v_fma_f32 v17, -v3, v16, 1.0
	v_fmac_f32_e32 v16, v17, v16
	v_div_scale_f32 v17, vcc, 1.0, v0, 1.0
	v_mul_f32_e32 v18, v17, v16
	v_fma_f32 v19, -v3, v18, v17
	v_fmac_f32_e32 v18, v19, v16
	v_fma_f32 v3, -v3, v18, v17
	v_div_fmas_f32 v3, v3, v16, v18
	v_div_fixup_f32 v0, v3, v0, 1.0
	v_div_scale_f32 v3, s[30:31], v1, v1, 1.0
	v_rcp_f32_e32 v16, v3
	s_nop 0
	v_fma_f32 v17, -v3, v16, 1.0
	v_fmac_f32_e32 v16, v17, v16
	v_div_scale_f32 v17, vcc, 1.0, v1, 1.0
	v_mul_f32_e32 v18, v17, v16
	v_fma_f32 v19, -v3, v18, v17
	v_fmac_f32_e32 v18, v19, v16
	v_fma_f32 v3, -v3, v18, v17
	v_div_fmas_f32 v3, v3, v16, v18
	v_div_fixup_f32 v1, v3, v1, 1.0
	v_mul_f32_e32 v3, 0xbfb8aa3b, v5
	v_rndne_f32_e32 v16, v3
	v_sub_f32_e32 v17, v3, v16
	v_fma_f32 v3, v5, s54, -v3
	v_fmac_f32_e32 v3, 0xb2a5705f, v5
	v_add_f32_e32 v3, v17, v3
	v_exp_f32_e32 v3, v3
	v_cvt_i32_f32_e32 v16, v16
	v_ldexp_f32 v3, v3, v16
	s_nop 0
	s_nop 1
	v_pk_add_f32 v[2:3], v[2:3], 1.0 op_sel_hi:[1,0]
	s_nop 0
	v_div_scale_f32 v16, s[30:31], v2, v2, 1.0
	v_rcp_f32_e32 v17, v16
	s_nop 0
	v_fma_f32 v18, -v16, v17, 1.0
	v_fmac_f32_e32 v17, v18, v17
	v_div_scale_f32 v18, vcc, 1.0, v2, 1.0
	v_mul_f32_e32 v19, v18, v17
	v_fma_f32 v32, -v16, v19, v18
	v_fmac_f32_e32 v19, v32, v17
	v_fma_f32 v16, -v16, v19, v18
	v_div_fmas_f32 v16, v16, v17, v19
	v_div_fixup_f32 v2, v16, v2, 1.0
	v_div_scale_f32 v16, s[30:31], v3, v3, 1.0
	v_rcp_f32_e32 v17, v16
	s_nop 0
	v_fma_f32 v18, -v16, v17, 1.0
	v_fmac_f32_e32 v17, v18, v17
	v_div_scale_f32 v18, vcc, 1.0, v3, 1.0
	v_mul_f32_e32 v19, v18, v17
	v_fma_f32 v32, -v16, v19, v18
	v_fmac_f32_e32 v19, v32, v17
	v_fma_f32 v16, -v16, v19, v18
	v_div_fmas_f32 v16, v16, v17, v19
	v_div_fixup_f32 v3, v16, v3, 1.0
	v_mul_f32_e32 v16, 0xbfb8aa3b, v22
	v_rndne_f32_e32 v17, v16
	v_sub_f32_e32 v18, v16, v17
	v_fma_f32 v16, v22, s54, -v16
	v_fmac_f32_e32 v16, 0xb2a5705f, v22
	v_add_f32_e32 v16, v18, v16
	v_exp_f32_e32 v16, v16
	v_cvt_i32_f32_e32 v17, v17
	v_ldexp_f32 v16, v16, v17
	v_mul_f32_e32 v17, 0xbfb8aa3b, v6
	v_rndne_f32_e32 v18, v17
	v_sub_f32_e32 v19, v17, v18
	v_fma_f32 v17, v6, s54, -v17
	v_fmac_f32_e32 v17, 0xb2a5705f, v6
	v_add_f32_e32 v17, v19, v17
	v_exp_f32_e32 v17, v17
	v_cvt_i32_f32_e32 v18, v18
	v_ldexp_f32 v17, v17, v18
	s_nop 0
	s_nop 1
	s_nop 1
	v_mov_b32_e32 v18, v17
	v_mul_f32_e32 v17, 0xbfb8aa3b, v23
	v_rndne_f32_e32 v19, v17
	v_sub_f32_e32 v32, v17, v19
	v_fma_f32 v17, v23, s54, -v17
	v_fmac_f32_e32 v17, 0xb2a5705f, v23
	v_add_f32_e32 v17, v32, v17
	v_exp_f32_e32 v17, v17
	v_cvt_i32_f32_e32 v19, v19
	v_ldexp_f32 v17, v17, v19
	s_nop 0
	s_nop 1
	v_pk_add_f32 v[16:17], v[16:17], 1.0 op_sel_hi:[1,0]
	s_nop 0
	v_div_scale_f32 v19, s[30:31], v16, v16, 1.0
	v_rcp_f32_e32 v32, v19
	s_nop 0
	v_fma_f32 v33, -v19, v32, 1.0
	v_fmac_f32_e32 v32, v33, v32
	v_div_scale_f32 v33, vcc, 1.0, v16, 1.0
	v_mul_f32_e32 v34, v33, v32
	v_fma_f32 v35, -v19, v34, v33
	v_fmac_f32_e32 v34, v35, v32
	v_fma_f32 v19, -v19, v34, v33
	v_div_fmas_f32 v19, v19, v32, v34
	v_div_fixup_f32 v16, v19, v16, 1.0
	v_div_scale_f32 v19, s[30:31], v17, v17, 1.0
	v_rcp_f32_e32 v32, v19
	s_nop 0
	v_fma_f32 v33, -v19, v32, 1.0
	v_fmac_f32_e32 v32, v33, v32
	v_div_scale_f32 v33, vcc, 1.0, v17, 1.0
	v_mul_f32_e32 v34, v33, v32
	v_fma_f32 v35, -v19, v34, v33
	v_fmac_f32_e32 v34, v35, v32
	v_fma_f32 v19, -v19, v34, v33
	v_div_fmas_f32 v19, v19, v32, v34
	v_div_fixup_f32 v17, v19, v17, 1.0
	v_mul_f32_e32 v19, 0xbfb8aa3b, v7
	v_rndne_f32_e32 v32, v19
	v_sub_f32_e32 v33, v19, v32
	v_fma_f32 v19, v7, s54, -v19
	v_fmac_f32_e32 v19, 0xb2a5705f, v7
	v_add_f32_e32 v19, v33, v19
	v_exp_f32_e32 v19, v19
	v_cvt_i32_f32_e32 v32, v32
	v_ldexp_f32 v19, v19, v32
	s_nop 0
	s_nop 1
	v_pk_add_f32 v[18:19], v[18:19], 1.0 op_sel_hi:[1,0]
	s_nop 0
	v_div_scale_f32 v32, s[30:31], v18, v18, 1.0
	v_rcp_f32_e32 v33, v32
	s_nop 0
	v_fma_f32 v34, -v32, v33, 1.0
	v_fmac_f32_e32 v33, v34, v33
	v_div_scale_f32 v34, vcc, 1.0, v18, 1.0
	v_mul_f32_e32 v35, v34, v33
	v_fma_f32 v36, -v32, v35, v34
	v_fmac_f32_e32 v35, v36, v33
	v_fma_f32 v32, -v32, v35, v34
	v_div_fmas_f32 v32, v32, v33, v35
	v_div_fixup_f32 v18, v32, v18, 1.0
	v_div_scale_f32 v32, s[30:31], v19, v19, 1.0
	v_rcp_f32_e32 v33, v32
	s_nop 0
	v_fma_f32 v34, -v32, v33, 1.0
	v_fmac_f32_e32 v33, v34, v33
	v_div_scale_f32 v34, vcc, 1.0, v19, 1.0
	v_mul_f32_e32 v35, v34, v33
	v_fma_f32 v36, -v32, v35, v34
	v_fmac_f32_e32 v35, v36, v33
	v_fma_f32 v32, -v32, v35, v34
	v_div_fmas_f32 v32, v32, v33, v35
	v_div_fixup_f32 v19, v32, v19, 1.0

; DEVI void lds_put4(char* wl, int RS, int row, int col, float a, float b, float c, float d) { u32x2 w = {cvtpk(a, b), cvtpk(c, d)}; *(u32x2*)(wl + row * RS + col * 2) = w; }
; DEVI float sigmf(float x) { return 1.f / (1.f + expf(-x)); }
; DEVI void phase_gemm_in(const Params& p, int l, char* lds) {
;     ...
;           } else if (mode == 3) {
; #pragma unroll
;             for (int j = 0; j < 4; ++j) { x1[j] = sigmf(x1[j]); x2[j] = sigmf(x2[j]); }
;           }
;           lds_put4(wl, 272, mi * 32 + r32, cg2 * 64 + ci, x1[0], x1[1], x1[2], x1[3]);
;           lds_put4(wl, 272, mi * 32 + r32, cg2 * 64 + 32 + ci, x2[0], x2[1], x2[2], x2[3]);
.LBB0_309:
	s_or_b64 exec, exec, s[2:3]
	v_cvt_pk_bf16_f32 v0, v0, v1
	v_cvt_pk_bf16_f32 v1, v16, v17
	v_cvt_pk_bf16_f32 v2, v2, v3
	v_cvt_pk_bf16_f32 v3, v18, v19
	ds_write2_b64 v98, v[0:1], v[2:3] offset0:82 offset1:90
	s_and_saveexec_b64 s[2:3], s[14:15]
	s_xor_b64 s[2:3], exec, s[2:3]
	v_pk_mul_f32 v[0:1], v[24:25], s[96:97] op_sel_hi:[1,0]
	v_pk_mul_f32 v[2:3], v[8:9], s[96:97] op_sel_hi:[1,0]
	v_pk_mul_f32 v[4:5], v[26:27], s[96:97] op_sel_hi:[1,0]
	v_pk_mul_f32 v[6:7], v[10:11], s[96:97] op_sel_hi:[1,0]
	s_andn2_saveexec_b64 s[2:3], s[2:3]
	s_cbranch_execz .LBB0_321
	s_and_saveexec_b64 s[6:7], s[12:13]
	s_xor_b64 s[6:7], exec, s[6:7]
	s_cbranch_execz .LBB0_316
	v_mov_b32_e32 v5, v27
	v_mov_b32_e32 v4, v26
	v_mov_b32_e32 v1, v25
	v_mov_b32_e32 v0, v24
	v_mov_b32_e32 v7, v11
	v_mov_b32_e32 v6, v10
	v_mov_b32_e32 v3, v9
	v_mov_b32_e32 v2, v8
	s_and_saveexec_b64 s[28:29], s[10:11]
	s_cbranch_execz .LBB0_315
	v_mul_f32_e32 v0, 0xbfb8aa3b, v24
	v_rndne_f32_e32 v1, v0
	v_sub_f32_e32 v2, v0, v1
	v_fma_f32 v0, v24, s54, -v0
	v_fmac_f32_e32 v0, 0xb2a5705f, v24
	v_add_f32_e32 v0, v2, v0
	v_exp_f32_e32 v0, v0
	v_cvt_i32_f32_e32 v1, v1
	v_ldexp_f32 v0, v0, v1
	v_mul_f32_e32 v1, 0xbfb8aa3b, v8
	v_rndne_f32_e32 v2, v1
	v_sub_f32_e32 v3, v1, v2
	v_fma_f32 v1, v8, s54, -v1
	v_fmac_f32_e32 v1, 0xb2a5705f, v8
	v_add_f32_e32 v1, v3, v1
	v_exp_f32_e32 v1, v1
	v_cvt_i32_f32_e32 v2, v2
	v_ldexp_f32 v1, v1, v2
	s_nop 0
	s_nop 1
	s_nop 1
	v_mov_b32_e32 v2, v1
	v_mul_f32_e32 v1, 0xbfb8aa3b, v25
	v_rndne_f32_e32 v3, v1
	v_sub_f32_e32 v4, v1, v3
	v_fma_f32 v1, v25, s54, -v1
	v_fmac_f32_e32 v1, 0xb2a5705f, v25
	v_add_f32_e32 v1, v4, v1
	v_exp_f32_e32 v1, v1
	v_cvt_i32_f32_e32 v3, v3
	v_ldexp_f32 v1, v1, v3
	s_nop 0
	s_nop 1
	v_pk_add_f32 v[0:1], v[0:1], 1.0 op_sel_hi:[1,0]
	s_nop 0
	v_div_scale_f32 v3, s[30:31], v0, v0, 1.0
	v_rcp_f32_e32 v4, v3
	s_nop 0
	v_fma_f32 v5, -v3, v4, 1.0
	v_fmac_f32_e32 v4, v5, v4
	v_div_scale_f32 v5, vcc, 1.0, v0, 1.0
	v_mul_f32_e32 v6, v5, v4
	v_fma_f32 v7, -v3, v6, v5
	v_fmac_f32_e32 v6, v7, v4
	v_fma_f32 v3, -v3, v6, v5
	v_div_fmas_f32 v3, v3, v4, v6
	v_div_fixup_f32 v0, v3, v0, 1.0
	v_div_scale_f32 v3, s[30:31], v1, v1, 1.0
	v_rcp_f32_e32 v4, v3
	s_nop 0
	v_fma_f32 v5, -v3, v4, 1.0
	v_fmac_f32_e32 v4, v5, v4
	v_div_scale_f32 v5, vcc, 1.0, v1, 1.0
	v_mul_f32_e32 v6, v5, v4
	v_fma_f32 v7, -v3, v6, v5
	v_fmac_f32_e32 v6, v7, v4
	v_fma_f32 v3, -v3, v6, v5
	v_div_fmas_f32 v3, v3, v4, v6
	v_div_fixup_f32 v1, v3, v1, 1.0
	v_mul_f32_e32 v3, 0xbfb8aa3b, v9
	v_rndne_f32_e32 v4, v3
	v_sub_f32_e32 v5, v3, v4
	v_fma_f32 v3, v9, s54, -v3
	v_fmac_f32_e32 v3, 0xb2a5705f, v9
	v_add_f32_e32 v3, v5, v3
	v_exp_f32_e32 v3, v3
	v_cvt_i32_f32_e32 v4, v4
	v_ldexp_f32 v3, v3, v4
	s_nop 0
	s_nop 1
	v_pk_add_f32 v[2:3], v[2:3], 1.0 op_sel_hi:[1,0]
	s_nop 0
	v_div_scale_f32 v4, s[30:31], v2, v2, 1.0
	v_rcp_f32_e32 v5, v4
	s_nop 0
	v_fma_f32 v6, -v4, v5, 1.0
	v_fmac_f32_e32 v5, v6, v5
	v_div_scale_f32 v6, vcc, 1.0, v2, 1.0
	v_mul_f32_e32 v7, v6, v5
	v_fma_f32 v16, -v4, v7, v6
	v_fmac_f32_e32 v7, v16, v5
	v_fma_f32 v4, -v4, v7, v6
	v_div_fmas_f32 v4, v4, v5, v7
	v_div_fixup_f32 v2, v4, v2, 1.0
	v_div_scale_f32 v4, s[30:31], v3, v3, 1.0
	v_rcp_f32_e32 v5, v4
	s_nop 0
	v_fma_f32 v6, -v4, v5, 1.0
	v_fmac_f32_e32 v5, v6, v5
	v_div_scale_f32 v6, vcc, 1.0, v3, 1.0
	v_mul_f32_e32 v7, v6, v5
	v_fma_f32 v16, -v4, v7, v6
	v_fmac_f32_e32 v7, v16, v5
	v_fma_f32 v4, -v4, v7, v6
	v_div_fmas_f32 v4, v4, v5, v7
	v_div_fixup_f32 v3, v4, v3, 1.0
	v_mul_f32_e32 v4, 0xbfb8aa3b, v26
	v_rndne_f32_e32 v5, v4
	v_sub_f32_e32 v6, v4, v5
	v_fma_f32 v4, v26, s54, -v4
	v_fmac_f32_e32 v4, 0xb2a5705f, v26
	v_add_f32_e32 v4, v6, v4
	v_exp_f32_e32 v4, v4
	v_cvt_i32_f32_e32 v5, v5
	v_ldexp_f32 v4, v4, v5
	v_mul_f32_e32 v5, 0xbfb8aa3b, v10
	v_rndne_f32_e32 v6, v5
	v_sub_f32_e32 v7, v5, v6
	v_fma_f32 v5, v10, s54, -v5
	v_fmac_f32_e32 v5, 0xb2a5705f, v10
	v_add_f32_e32 v5, v7, v5
	v_exp_f32_e32 v5, v5
	v_cvt_i32_f32_e32 v6, v6
	v_ldexp_f32 v5, v5, v6
	s_nop 0
	s_nop 1
	s_nop 1
	v_mov_b32_e32 v6, v5
	v_mul_f32_e32 v5, 0xbfb8aa3b, v27
	v_rndne_f32_e32 v7, v5
	v_sub_f32_e32 v16, v5, v7
	v_fma_f32 v5, v27, s54, -v5
	v_fmac_f32_e32 v5, 0xb2a5705f, v27
	v_add_f32_e32 v5, v16, v5
	v_exp_f32_e32 v5, v5
	v_cvt_i32_f32_e32 v7, v7
	v_ldexp_f32 v5, v5, v7
	s_nop 0
	s_nop 1
	v_pk_add_f32 v[4:5], v[4:5], 1.0 op_sel_hi:[1,0]
	s_nop 0
	v_div_scale_f32 v7, s[30:31], v4, v4, 1.0
	v_rcp_f32_e32 v16, v7
	s_nop 0
	v_fma_f32 v17, -v7, v16, 1.0
	v_fmac_f32_e32 v16, v17, v16
	v_div_scale_f32 v17, vcc, 1.0, v4, 1.0
	v_mul_f32_e32 v18, v17, v16
	v_fma_f32 v19, -v7, v18, v17
	v_fmac_f32_e32 v18, v19, v16
	v_fma_f32 v7, -v7, v18, v17
	v_div_fmas_f32 v7, v7, v16, v18
	v_div_fixup_f32 v4, v7, v4, 1.0
	v_div_scale_f32 v7, s[30:31], v5, v5, 1.0
	v_rcp_f32_e32 v16, v7
	s_nop 0
	v_fma_f32 v17, -v7, v16, 1.0
	v_fmac_f32_e32 v16, v17, v16
	v_div_scale_f32 v17, vcc, 1.0, v5, 1.0
	v_mul_f32_e32 v18, v17, v16
	v_fma_f32 v19, -v7, v18, v17
	v_fmac_f32_e32 v18, v19, v16
	v_fma_f32 v7, -v7, v18, v17
	v_div_fmas_f32 v7, v7, v16, v18
	v_div_fixup_f32 v5, v7, v5, 1.0
	v_mul_f32_e32 v7, 0xbfb8aa3b, v11
	v_rndne_f32_e32 v16, v7
	v_sub_f32_e32 v17, v7, v16
	v_fma_f32 v7, v11, s54, -v7
	v_fmac_f32_e32 v7, 0xb2a5705f, v11
	v_add_f32_e32 v7, v17, v7
	v_exp_f32_e32 v7, v7
	v_cvt_i32_f32_e32 v16, v16
	v_ldexp_f32 v7, v7, v16
	s_nop 0
	s_nop 1
	v_pk_add_f32 v[6:7], v[6:7], 1.0 op_sel_hi:[1,0]
	s_nop 0
	v_div_scale_f32 v16, s[30:31], v6, v6, 1.0
	v_rcp_f32_e32 v17, v16
	s_nop 0
	v_fma_f32 v18, -v16, v17, 1.0
	v_fmac_f32_e32 v17, v18, v17
	v_div_scale_f32 v18, vcc, 1.0, v6, 1.0
	v_mul_f32_e32 v19, v18, v17
	v_fma_f32 v20, -v16, v19, v18
	v_fmac_f32_e32 v19, v20, v17
	v_fma_f32 v16, -v16, v19, v18
	v_div_fmas_f32 v16, v16, v17, v19
	v_div_fixup_f32 v6, v16, v6, 1.0
	v_div_scale_f32 v16, s[30:31], v7, v7, 1.0
	v_rcp_f32_e32 v17, v16
	s_nop 0
	v_fma_f32 v18, -v16, v17, 1.0
	v_fmac_f32_e32 v17, v18, v17
	v_div_scale_f32 v18, vcc, 1.0, v7, 1.0
	v_mul_f32_e32 v19, v18, v17
	v_fma_f32 v20, -v16, v19, v18
	v_fmac_f32_e32 v19, v20, v17
	v_fma_f32 v16, -v16, v19, v18
	v_div_fmas_f32 v16, v16, v17, v19
	v_div_fixup_f32 v7, v16, v7, 1.0

; DEVI void lds_put4(char* wl, int RS, int row, int col, float a, float b, float c, float d) { u32x2 w = {cvtpk(a, b), cvtpk(c, d)}; *(u32x2*)(wl + row * RS + col * 2) = w; }
; DEVI float sigmf(float x) { return 1.f / (1.f + expf(-x)); }
; DEVI void phase_gemm_in(const Params& p, int l, char* lds) {
;     ...
;           } else if (mode == 3) {
; #pragma unroll
;             for (int j = 0; j < 4; ++j) { x1[j] = sigmf(x1[j]); x2[j] = sigmf(x2[j]); }
;           }
;           lds_put4(wl, 272, mi * 32 + r32, cg2 * 64 + ci, x1[0], x1[1], x1[2], x1[3]);
;           lds_put4(wl, 272, mi * 32 + r32, cg2 * 64 + 32 + ci, x2[0], x2[1], x2[2], x2[3]);
.LBB0_321:
	s_or_b64 exec, exec, s[2:3]
	v_cvt_pk_bf16_f32 v0, v0, v1
	v_cvt_pk_bf16_f32 v1, v4, v5
	v_cvt_pk_bf16_f32 v2, v2, v3
	v_cvt_pk_bf16_f32 v3, v6, v7
	ds_write2_b64 v98, v[0:1], v[2:3] offset0:84 offset1:92
	s_and_saveexec_b64 s[2:3], s[14:15]
	s_xor_b64 s[2:3], exec, s[2:3]
	v_pk_mul_f32 v[28:29], v[28:29], s[96:97] op_sel_hi:[1,0]
	v_pk_mul_f32 v[12:13], v[12:13], s[96:97] op_sel_hi:[1,0]
	v_pk_mul_f32 v[30:31], v[30:31], s[96:97] op_sel_hi:[1,0]
	v_pk_mul_f32 v[14:15], v[14:15], s[96:97] op_sel_hi:[1,0]
	s_andn2_saveexec_b64 s[2:3], s[2:3]
	s_cbranch_execz .LBB0_333
	s_and_saveexec_b64 s[6:7], s[12:13]
	s_xor_b64 s[6:7], exec, s[6:7]
	s_cbranch_execz .LBB0_328
	s_and_saveexec_b64 s[12:13], s[10:11]
	s_cbranch_execz .LBB0_327
	v_mul_f32_e32 v0, 0xbfb8aa3b, v28
	v_rndne_f32_e32 v1, v0
	v_sub_f32_e32 v2, v0, v1
	v_fma_f32 v0, v28, s54, -v0
	v_fmac_f32_e32 v0, 0xb2a5705f, v28
	v_add_f32_e32 v0, v2, v0
	v_exp_f32_e32 v0, v0
	v_cvt_i32_f32_e32 v1, v1
	v_ldexp_f32 v0, v0, v1
	v_mul_f32_e32 v1, 0xbfb8aa3b, v12
	v_rndne_f32_e32 v2, v1
	v_sub_f32_e32 v3, v1, v2
	v_fma_f32 v1, v12, s54, -v1
	v_fmac_f32_e32 v1, 0xb2a5705f, v12
	v_add_f32_e32 v1, v3, v1
	v_exp_f32_e32 v1, v1
	v_cvt_i32_f32_e32 v2, v2
	v_ldexp_f32 v1, v1, v2
	s_nop 0
	s_nop 1
	s_nop 1
	v_mov_b32_e32 v2, v1
	v_mul_f32_e32 v1, 0xbfb8aa3b, v29
	v_rndne_f32_e32 v3, v1
	v_sub_f32_e32 v4, v1, v3
	v_fma_f32 v1, v29, s54, -v1
	v_fmac_f32_e32 v1, 0xb2a5705f, v29
	v_add_f32_e32 v1, v4, v1
	v_exp_f32_e32 v1, v1
	v_cvt_i32_f32_e32 v3, v3
	v_ldexp_f32 v1, v1, v3
	s_nop 0
	s_nop 1
	v_pk_add_f32 v[0:1], v[0:1], 1.0 op_sel_hi:[1,0]
	s_nop 0
	v_div_scale_f32 v3, s[10:11], v0, v0, 1.0
	v_rcp_f32_e32 v4, v3
	s_nop 0
	v_fma_f32 v5, -v3, v4, 1.0
	v_fmac_f32_e32 v4, v5, v4
	v_div_scale_f32 v5, vcc, 1.0, v0, 1.0
	v_mul_f32_e32 v6, v5, v4
	v_fma_f32 v7, -v3, v6, v5
	v_fmac_f32_e32 v6, v7, v4
	v_fma_f32 v3, -v3, v6, v5
	v_div_fmas_f32 v3, v3, v4, v6
	v_div_fixup_f32 v28, v3, v0, 1.0
	v_div_scale_f32 v0, s[10:11], v1, v1, 1.0
	v_rcp_f32_e32 v3, v0
	s_nop 0
	v_fma_f32 v4, -v0, v3, 1.0
	v_fmac_f32_e32 v3, v4, v3
	v_div_scale_f32 v4, vcc, 1.0, v1, 1.0
	v_mul_f32_e32 v5, v4, v3
	v_fma_f32 v6, -v0, v5, v4
	v_fmac_f32_e32 v5, v6, v3
	v_fma_f32 v0, -v0, v5, v4
	v_div_fmas_f32 v0, v0, v3, v5
	v_div_fixup_f32 v29, v0, v1, 1.0
	v_mul_f32_e32 v0, 0xbfb8aa3b, v13
	v_rndne_f32_e32 v1, v0
	v_sub_f32_e32 v3, v0, v1
	v_fma_f32 v0, v13, s54, -v0
	v_fmac_f32_e32 v0, 0xb2a5705f, v13
	v_add_f32_e32 v0, v3, v0
	v_exp_f32_e32 v0, v0
	v_cvt_i32_f32_e32 v1, v1
	v_ldexp_f32 v0, v0, v1
	s_nop 0
	s_nop 1
	v_mov_b32_e32 v3, v0
	v_pk_add_f32 v[0:1], v[2:3], 1.0 op_sel_hi:[1,0]
	s_nop 0
	v_div_scale_f32 v2, s[10:11], v0, v0, 1.0
	v_rcp_f32_e32 v3, v2
	s_nop 0
	v_fma_f32 v4, -v2, v3, 1.0
	v_fmac_f32_e32 v3, v4, v3
	v_div_scale_f32 v4, vcc, 1.0, v0, 1.0
	v_mul_f32_e32 v5, v4, v3
	v_fma_f32 v6, -v2, v5, v4
	v_fmac_f32_e32 v5, v6, v3
	v_fma_f32 v2, -v2, v5, v4
	v_div_fmas_f32 v2, v2, v3, v5
	v_div_fixup_f32 v12, v2, v0, 1.0
	v_div_scale_f32 v0, s[10:11], v1, v1, 1.0
	v_rcp_f32_e32 v2, v0
	s_nop 0
	v_fma_f32 v3, -v0, v2, 1.0
	v_fmac_f32_e32 v2, v3, v2
	v_div_scale_f32 v3, vcc, 1.0, v1, 1.0
	v_mul_f32_e32 v4, v3, v2
	v_fma_f32 v5, -v0, v4, v3
	v_fmac_f32_e32 v4, v5, v2
	v_fma_f32 v0, -v0, v4, v3
	v_div_fmas_f32 v0, v0, v2, v4
	v_div_fixup_f32 v13, v0, v1, 1.0
	v_mul_f32_e32 v0, 0xbfb8aa3b, v30
	v_rndne_f32_e32 v1, v0
	v_sub_f32_e32 v2, v0, v1
	v_fma_f32 v0, v30, s54, -v0
	v_fmac_f32_e32 v0, 0xb2a5705f, v30
	v_add_f32_e32 v0, v2, v0
	v_exp_f32_e32 v0, v0
	v_cvt_i32_f32_e32 v1, v1
	v_ldexp_f32 v0, v0, v1
	v_mul_f32_e32 v1, 0xbfb8aa3b, v14
	v_rndne_f32_e32 v2, v1
	v_sub_f32_e32 v3, v1, v2
	v_fma_f32 v1, v14, s54, -v1
	v_fmac_f32_e32 v1, 0xb2a5705f, v14
	v_add_f32_e32 v1, v3, v1
	v_exp_f32_e32 v1, v1
	v_cvt_i32_f32_e32 v2, v2
	v_ldexp_f32 v1, v1, v2
	s_nop 0
	s_nop 1
	s_nop 1
	v_mov_b32_e32 v2, v1
	v_mul_f32_e32 v1, 0xbfb8aa3b, v31
	v_rndne_f32_e32 v3, v1
	v_sub_f32_e32 v4, v1, v3
	v_fma_f32 v1, v31, s54, -v1
	v_fmac_f32_e32 v1, 0xb2a5705f, v31
	v_add_f32_e32 v1, v4, v1
	v_exp_f32_e32 v1, v1
	v_cvt_i32_f32_e32 v3, v3
	v_ldexp_f32 v1, v1, v3
	s_nop 0
	s_nop 1
	v_pk_add_f32 v[0:1], v[0:1], 1.0 op_sel_hi:[1,0]
	s_nop 0
	v_div_scale_f32 v3, s[10:11], v0, v0, 1.0
	v_rcp_f32_e32 v4, v3
	s_nop 0
	v_fma_f32 v5, -v3, v4, 1.0
	v_fmac_f32_e32 v4, v5, v4
	v_div_scale_f32 v5, vcc, 1.0, v0, 1.0
	v_mul_f32_e32 v6, v5, v4
	v_fma_f32 v7, -v3, v6, v5
	v_fmac_f32_e32 v6, v7, v4
	v_fma_f32 v3, -v3, v6, v5
	v_div_fmas_f32 v3, v3, v4, v6
	v_div_fixup_f32 v30, v3, v0, 1.0
	v_div_scale_f32 v0, s[10:11], v1, v1, 1.0
	v_rcp_f32_e32 v3, v0
	s_nop 0
	v_fma_f32 v4, -v0, v3, 1.0
	v_fmac_f32_e32 v3, v4, v3
	v_div_scale_f32 v4, vcc, 1.0, v1, 1.0
	v_mul_f32_e32 v5, v4, v3
	v_fma_f32 v6, -v0, v5, v4
	v_fmac_f32_e32 v5, v6, v3
	v_fma_f32 v0, -v0, v5, v4
	v_div_fmas_f32 v0, v0, v3, v5
	v_div_fixup_f32 v31, v0, v1, 1.0
	v_mul_f32_e32 v0, 0xbfb8aa3b, v15
	v_rndne_f32_e32 v1, v0
	v_sub_f32_e32 v3, v0, v1
	v_fma_f32 v0, v15, s54, -v0
	v_fmac_f32_e32 v0, 0xb2a5705f, v15
	v_add_f32_e32 v0, v3, v0
	v_exp_f32_e32 v0, v0
	v_cvt_i32_f32_e32 v1, v1
	v_ldexp_f32 v0, v0, v1
	s_nop 0
	s_nop 1
	v_mov_b32_e32 v3, v0
	v_pk_add_f32 v[0:1], v[2:3], 1.0 op_sel_hi:[1,0]
	s_nop 0
	v_div_scale_f32 v2, s[10:11], v0, v0, 1.0
	v_rcp_f32_e32 v3, v2
	s_nop 0
	v_fma_f32 v4, -v2, v3, 1.0
	v_fmac_f32_e32 v3, v4, v3
	v_div_scale_f32 v4, vcc, 1.0, v0, 1.0
	v_mul_f32_e32 v5, v4, v3
	v_fma_f32 v6, -v2, v5, v4
	v_fmac_f32_e32 v5, v6, v3
	v_fma_f32 v2, -v2, v5, v4
	v_div_fmas_f32 v2, v2, v3, v5
	v_div_fixup_f32 v14, v2, v0, 1.0
	v_div_scale_f32 v0, s[10:11], v1, v1, 1.0
	v_rcp_f32_e32 v2, v0
	s_nop 0
	v_fma_f32 v3, -v0, v2, 1.0
	v_fmac_f32_e32 v2, v3, v2
	v_div_scale_f32 v3, vcc, 1.0, v1, 1.0
	v_mul_f32_e32 v4, v3, v2
	v_fma_f32 v5, -v0, v4, v3
	v_fmac_f32_e32 v4, v5, v2
	v_fma_f32 v0, -v0, v4, v3
	v_div_fmas_f32 v0, v0, v2, v4
	v_div_fixup_f32 v15, v0, v1, 1.0

; DEVI void lds_put4(char* wl, int RS, int row, int col, float a, float b, float c, float d) { u32x2 w = {cvtpk(a, b), cvtpk(c, d)}; *(u32x2*)(wl + row * RS + col * 2) = w; }
; DEVI float siluf(float x) { return x / (1.f + expf(-x)); }
; DEVI void phase_gemm_f1(const Params& p, int l, char* lds) {
;     ...
; #pragma unroll
;     for (int cg2 = 0; cg2 < 2; ++cg2) {
; #pragma unroll
;       for (int mi = 0; mi < 2; ++mi) {
; #pragma unroll
;         for (int q = 0; q < 4; ++q) {
;           float h[4];
; #pragma unroll
;           for (int j = 0; j < 4; ++j) h[j] = siluf(acc[2 * cg2][mi][q * 4 + j]) * acc[2 * cg2 + 1][mi][q * 4 + j];
;           lds_put4(wl, 144, mi * 32 + r32, cg2 * 32 + q * 8 + hi * 4, h[0], h[1], h[2], h[3]);
;         }
.LBB0_603:
	s_waitcnt vmcnt(7)
	v_mul_f32_e32 v128, 0xbfb8aa3b, v112
	v_rndne_f32_e32 v129, v128
	v_sub_f32_e32 v130, v128, v129
	v_fma_f32 v128, v112, s54, -v128
	v_fmac_f32_e32 v128, 0xb2a5705f, v112
	v_add_f32_e32 v128, v130, v128
	v_exp_f32_e32 v128, v128
	v_cvt_i32_f32_e32 v129, v129
	v_ldexp_f32 v128, v128, v129
	v_mul_f32_e32 v129, 0xbfb8aa3b, v113
	v_rndne_f32_e32 v130, v129
	v_sub_f32_e32 v131, v129, v130
	v_fma_f32 v129, v113, s54, -v129
	v_fmac_f32_e32 v129, 0xb2a5705f, v113
	v_add_f32_e32 v129, v131, v129
	v_exp_f32_e32 v129, v129
	v_cvt_i32_f32_e32 v130, v130
	v_ldexp_f32 v129, v129, v130
	s_nop 0
	s_nop 1
	s_nop 1
	v_pk_add_f32 v[128:129], v[128:129], 1.0 op_sel_hi:[1,0]
	s_nop 0
	v_div_scale_f32 v130, s[10:11], v129, v129, v113
	v_rcp_f32_e32 v131, v130
	s_waitcnt vmcnt(5)
	v_fma_f32 v132, -v130, v131, 1.0
	v_fmac_f32_e32 v131, v132, v131
	v_div_scale_f32 v132, vcc, v113, v129, v113
	v_mul_f32_e32 v133, v132, v131
	v_fma_f32 v134, -v130, v133, v132
	v_fmac_f32_e32 v133, v134, v131
	v_fma_f32 v130, -v130, v133, v132
	v_div_fmas_f32 v130, v130, v131, v133
	v_div_fixup_f32 v113, v130, v129, v113
	v_div_scale_f32 v129, s[10:11], v128, v128, v112
	v_rcp_f32_e32 v130, v129
	s_nop 0
	v_fma_f32 v131, -v129, v130, 1.0
	v_fmac_f32_e32 v130, v131, v130
	v_div_scale_f32 v131, vcc, v112, v128, v112
	v_mul_f32_e32 v132, v131, v130
	v_fma_f32 v133, -v129, v132, v131
	v_fmac_f32_e32 v132, v133, v130
	v_fma_f32 v129, -v129, v132, v131
	v_div_fmas_f32 v129, v129, v130, v132
	v_div_fixup_f32 v112, v129, v128, v112
	v_pk_mul_f32 v[96:97], v[96:97], v[112:113]
	v_mul_f32_e32 v112, 0xbfb8aa3b, v114
	v_rndne_f32_e32 v113, v112
	v_sub_f32_e32 v128, v112, v113
	v_fma_f32 v112, v114, s54, -v112
	v_fmac_f32_e32 v112, 0xb2a5705f, v114
	v_add_f32_e32 v112, v128, v112
	v_exp_f32_e32 v112, v112
	v_cvt_i32_f32_e32 v113, v113
	v_cvt_pk_bf16_f32 v96, v96, v97
	v_ldexp_f32 v112, v112, v113
	v_mul_f32_e32 v113, 0xbfb8aa3b, v115
	v_rndne_f32_e32 v128, v113
	v_sub_f32_e32 v129, v113, v128
	v_fma_f32 v113, v115, s54, -v113
	v_fmac_f32_e32 v113, 0xb2a5705f, v115
	v_add_f32_e32 v113, v129, v113
	v_exp_f32_e32 v113, v113
	v_cvt_i32_f32_e32 v128, v128
	v_ldexp_f32 v113, v113, v128
	s_nop 0
	s_nop 1
	s_nop 1
	v_pk_add_f32 v[112:113], v[112:113], 1.0 op_sel_hi:[1,0]
	s_nop 0
	v_div_scale_f32 v128, s[10:11], v113, v113, v115
	v_rcp_f32_e32 v129, v128
	s_nop 0
	v_fma_f32 v130, -v128, v129, 1.0
	v_fmac_f32_e32 v129, v130, v129
	v_div_scale_f32 v130, vcc, v115, v113, v115
	v_mul_f32_e32 v131, v130, v129
	v_fma_f32 v132, -v128, v131, v130
	v_fmac_f32_e32 v131, v132, v129
	v_fma_f32 v128, -v128, v131, v130
	v_div_fmas_f32 v128, v128, v129, v131
	v_div_fixup_f32 v113, v128, v113, v115
	v_div_scale_f32 v115, s[10:11], v112, v112, v114
	v_rcp_f32_e32 v128, v115
	s_nop 0
	v_fma_f32 v129, -v115, v128, 1.0
	v_fmac_f32_e32 v128, v129, v128
	v_div_scale_f32 v129, vcc, v114, v112, v114
	v_mul_f32_e32 v130, v129, v128
	v_fma_f32 v131, -v115, v130, v129
	v_fmac_f32_e32 v130, v131, v128
	v_fma_f32 v115, -v115, v130, v129
	v_div_fmas_f32 v115, v115, v128, v130
	v_div_fixup_f32 v112, v115, v112, v114
	v_pk_mul_f32 v[98:99], v[98:99], v[112:113]
	v_cvt_pk_bf16_f32 v97, v98, v99
	v_mul_f32_e32 v98, 0xbfb8aa3b, v116
	v_rndne_f32_e32 v99, v98
	v_sub_f32_e32 v112, v98, v99
	v_fma_f32 v98, v116, s54, -v98
	v_fmac_f32_e32 v98, 0xb2a5705f, v116
	v_add_f32_e32 v98, v112, v98
	v_exp_f32_e32 v98, v98
	v_cvt_i32_f32_e32 v99, v99
	v_ldexp_f32 v98, v98, v99
	v_mul_f32_e32 v99, 0xbfb8aa3b, v117
	v_rndne_f32_e32 v112, v99
	v_sub_f32_e32 v113, v99, v112
	v_fma_f32 v99, v117, s54, -v99
	v_fmac_f32_e32 v99, 0xb2a5705f, v117
	v_add_f32_e32 v99, v113, v99
	v_exp_f32_e32 v99, v99
	v_cvt_i32_f32_e32 v112, v112
	v_ldexp_f32 v99, v99, v112
	s_nop 0
	s_nop 1
	s_nop 1
	v_pk_add_f32 v[98:99], v[98:99], 1.0 op_sel_hi:[1,0]
	s_nop 0
	v_div_scale_f32 v112, s[10:11], v99, v99, v117
	v_rcp_f32_e32 v113, v112
	s_nop 0
	v_fma_f32 v114, -v112, v113, 1.0
	v_fmac_f32_e32 v113, v114, v113
	v_div_scale_f32 v114, vcc, v117, v99, v117
	v_mul_f32_e32 v115, v114, v113
	v_fma_f32 v128, -v112, v115, v114
	v_fmac_f32_e32 v115, v128, v113
	v_fma_f32 v112, -v112, v115, v114
	v_div_fmas_f32 v112, v112, v113, v115
	v_div_fixup_f32 v99, v112, v99, v117
	v_div_scale_f32 v112, s[10:11], v98, v98, v116
	v_rcp_f32_e32 v113, v112
	s_nop 0
	v_fma_f32 v114, -v112, v113, 1.0
	v_fmac_f32_e32 v113, v114, v113
	v_div_scale_f32 v114, vcc, v116, v98, v116
	v_mul_f32_e32 v115, v114, v113
	v_fma_f32 v117, -v112, v115, v114
	v_fmac_f32_e32 v115, v117, v113
	v_fma_f32 v112, -v112, v115, v114
	v_div_fmas_f32 v112, v112, v113, v115
	v_div_fixup_f32 v98, v112, v98, v116
	v_pk_mul_f32 v[98:99], v[100:101], v[98:99]
	v_mul_f32_e32 v100, 0xbfb8aa3b, v118
	v_rndne_f32_e32 v101, v100
	v_sub_f32_e32 v112, v100, v101
	v_fma_f32 v100, v118, s54, -v100
	v_fmac_f32_e32 v100, 0xb2a5705f, v118
	v_add_f32_e32 v100, v112, v100
	v_exp_f32_e32 v100, v100
	v_cvt_i32_f32_e32 v101, v101
	v_cvt_pk_bf16_f32 v98, v98, v99
	v_ldexp_f32 v100, v100, v101
	v_mul_f32_e32 v101, 0xbfb8aa3b, v119
	v_rndne_f32_e32 v112, v101
	v_sub_f32_e32 v113, v101, v112
	v_fma_f32 v101, v119, s54, -v101
	v_fmac_f32_e32 v101, 0xb2a5705f, v119
	v_add_f32_e32 v101, v113, v101
	v_exp_f32_e32 v101, v101
	v_cvt_i32_f32_e32 v112, v112
	v_ldexp_f32 v101, v101, v112
	s_nop 0
	s_nop 1
	s_nop 1
	v_pk_add_f32 v[100:101], v[100:101], 1.0 op_sel_hi:[1,0]
	s_nop 0
	v_div_scale_f32 v112, s[10:11], v101, v101, v119
	v_rcp_f32_e32 v113, v112
	s_nop 0
	v_fma_f32 v114, -v112, v113, 1.0
	v_fmac_f32_e32 v113, v114, v113
	v_div_scale_f32 v114, vcc, v119, v101, v119
	v_mul_f32_e32 v115, v114, v113
	v_fma_f32 v116, -v112, v115, v114
; DEVI void lds_put4(char* wl, int RS, int row, int col, float a, float b, float c, float d) { u32x2 w = {cvtpk(a, b), cvtpk(c, d)}; *(u32x2*)(wl + row * RS + col * 2) = w; }
; DEVI float siluf(float x) { return x / (1.f + expf(-x)); }
; DEVI void phase_gemm_f1(const Params& p, int l, char* lds) {
;     ...
; #pragma unroll
;     for (int cg2 = 0; cg2 < 2; ++cg2) {
; #pragma unroll
;       for (int mi = 0; mi < 2; ++mi) {
; #pragma unroll
;         for (int q = 0; q < 4; ++q) {
;           float h[4];
; #pragma unroll
;           for (int j = 0; j < 4; ++j) h[j] = siluf(acc[2 * cg2][mi][q * 4 + j]) * acc[2 * cg2 + 1][mi][q * 4 + j];
;           lds_put4(wl, 144, mi * 32 + r32, cg2 * 32 + q * 8 + hi * 4, h[0], h[1], h[2], h[3]);
;         }
	v_fmac_f32_e32 v115, v116, v113
	v_fma_f32 v112, -v112, v115, v114
	v_div_fmas_f32 v112, v112, v113, v115
	v_div_fixup_f32 v101, v112, v101, v119
	v_div_scale_f32 v112, s[10:11], v100, v100, v118
	v_rcp_f32_e32 v113, v112
	s_nop 0
	v_fma_f32 v114, -v112, v113, 1.0
	v_fmac_f32_e32 v113, v114, v113
	v_div_scale_f32 v114, vcc, v118, v100, v118
	v_mul_f32_e32 v115, v114, v113
	v_fma_f32 v116, -v112, v115, v114
	v_fmac_f32_e32 v115, v116, v113
	v_fma_f32 v112, -v112, v115, v114
	v_div_fmas_f32 v112, v112, v113, v115
	v_div_fixup_f32 v100, v112, v100, v118
	v_pk_mul_f32 v[100:101], v[102:103], v[100:101]
	v_cvt_pk_bf16_f32 v99, v100, v101
	ds_write2_b64 v225, v[96:97], v[98:99] offset1:2
	v_mul_f32_e32 v96, 0xbfb8aa3b, v120
	v_rndne_f32_e32 v97, v96
	v_sub_f32_e32 v98, v96, v97
	v_fma_f32 v96, v120, s54, -v96
	v_fmac_f32_e32 v96, 0xb2a5705f, v120
	v_add_f32_e32 v96, v98, v96
	v_exp_f32_e32 v96, v96
	v_cvt_i32_f32_e32 v97, v97
	v_ldexp_f32 v96, v96, v97
	v_mul_f32_e32 v97, 0xbfb8aa3b, v121
	v_rndne_f32_e32 v98, v97
	v_sub_f32_e32 v99, v97, v98
	v_fma_f32 v97, v121, s54, -v97
	v_fmac_f32_e32 v97, 0xb2a5705f, v121
	v_add_f32_e32 v97, v99, v97
	v_exp_f32_e32 v97, v97
	v_cvt_i32_f32_e32 v98, v98
	v_ldexp_f32 v97, v97, v98
	s_nop 0
	s_nop 1
	s_nop 1
	v_pk_add_f32 v[96:97], v[96:97], 1.0 op_sel_hi:[1,0]
	s_nop 0
	v_div_scale_f32 v98, s[10:11], v97, v97, v121
	v_rcp_f32_e32 v99, v98
	s_nop 0
	v_fma_f32 v100, -v98, v99, 1.0
	v_fmac_f32_e32 v99, v100, v99
	v_div_scale_f32 v100, vcc, v121, v97, v121
	v_mul_f32_e32 v101, v100, v99
	v_fma_f32 v102, -v98, v101, v100
	v_fmac_f32_e32 v101, v102, v99
	v_fma_f32 v98, -v98, v101, v100
	v_div_fmas_f32 v98, v98, v99, v101
	v_div_fixup_f32 v97, v98, v97, v121
	v_div_scale_f32 v98, s[10:11], v96, v96, v120
	v_rcp_f32_e32 v99, v98
	s_nop 0
	v_fma_f32 v100, -v98, v99, 1.0
	v_fmac_f32_e32 v99, v100, v99
	v_div_scale_f32 v100, vcc, v120, v96, v120
	v_mul_f32_e32 v101, v100, v99
	v_fma_f32 v102, -v98, v101, v100
	v_fmac_f32_e32 v101, v102, v99
	v_fma_f32 v98, -v98, v101, v100
	v_div_fmas_f32 v98, v98, v99, v101
	v_div_fixup_f32 v96, v98, v96, v120
	v_mul_f32_e32 v98, 0xbfb8aa3b, v122
	v_rndne_f32_e32 v99, v98
	v_sub_f32_e32 v100, v98, v99
	v_fma_f32 v98, v122, s54, -v98
	v_fmac_f32_e32 v98, 0xb2a5705f, v122
	v_add_f32_e32 v98, v100, v98
	v_exp_f32_e32 v98, v98
	v_cvt_i32_f32_e32 v99, v99
	v_pk_mul_f32 v[96:97], v[104:105], v[96:97]
	v_ldexp_f32 v98, v98, v99
	v_mul_f32_e32 v99, 0xbfb8aa3b, v123
	v_rndne_f32_e32 v100, v99
	v_sub_f32_e32 v101, v99, v100
	v_fma_f32 v99, v123, s54, -v99
	v_fmac_f32_e32 v99, 0xb2a5705f, v123
	v_add_f32_e32 v99, v101, v99
	v_exp_f32_e32 v99, v99
	v_cvt_i32_f32_e32 v100, v100
	v_cvt_pk_bf16_f32 v96, v96, v97
	v_ldexp_f32 v99, v99, v100
	s_nop 1
	s_nop 1
	v_pk_add_f32 v[98:99], v[98:99], 1.0 op_sel_hi:[1,0]
	s_nop 0
	v_div_scale_f32 v100, s[10:11], v99, v99, v123
	v_rcp_f32_e32 v101, v100
	s_nop 0
	v_fma_f32 v102, -v100, v101, 1.0
	v_fmac_f32_e32 v101, v102, v101
	v_div_scale_f32 v102, vcc, v123, v99, v123
	v_mul_f32_e32 v103, v102, v101
	v_fma_f32 v104, -v100, v103, v102
	v_fmac_f32_e32 v103, v104, v101
	v_fma_f32 v100, -v100, v103, v102
	v_div_fmas_f32 v100, v100, v101, v103
	v_div_fixup_f32 v99, v100, v99, v123
	v_div_scale_f32 v100, s[10:11], v98, v98, v122
	v_rcp_f32_e32 v101, v100
	s_nop 0
	v_fma_f32 v102, -v100, v101, 1.0
	v_fmac_f32_e32 v101, v102, v101
	v_div_scale_f32 v102, vcc, v122, v98, v122
	v_mul_f32_e32 v103, v102, v101
	v_fma_f32 v104, -v100, v103, v102
	v_fmac_f32_e32 v103, v104, v101
	v_fma_f32 v100, -v100, v103, v102
	v_div_fmas_f32 v100, v100, v101, v103
	v_div_fixup_f32 v98, v100, v98, v122
	v_pk_mul_f32 v[98:99], v[106:107], v[98:99]
	v_cvt_pk_bf16_f32 v97, v98, v99
	v_mul_f32_e32 v98, 0xbfb8aa3b, v124
	v_rndne_f32_e32 v99, v98
	v_sub_f32_e32 v100, v98, v99
	v_fma_f32 v98, v124, s54, -v98
	v_fmac_f32_e32 v98, 0xb2a5705f, v124
	v_add_f32_e32 v98, v100, v98
	v_exp_f32_e32 v98, v98
	v_cvt_i32_f32_e32 v99, v99
	v_ldexp_f32 v98, v98, v99
	v_mul_f32_e32 v99, 0xbfb8aa3b, v125
	v_rndne_f32_e32 v100, v99
	v_sub_f32_e32 v101, v99, v100
	v_fma_f32 v99, v125, s54, -v99
	v_fmac_f32_e32 v99, 0xb2a5705f, v125
	v_add_f32_e32 v99, v101, v99
	v_exp_f32_e32 v99, v99
	v_cvt_i32_f32_e32 v100, v100
	v_ldexp_f32 v99, v99, v100
	s_nop 0
	s_nop 1
	s_nop 1
	v_pk_add_f32 v[98:99], v[98:99], 1.0 op_sel_hi:[1,0]
	s_nop 0
	v_div_scale_f32 v100, s[10:11], v99, v99, v125
	v_rcp_f32_e32 v101, v100
	s_nop 0
	v_fma_f32 v102, -v100, v101, 1.0
	v_fmac_f32_e32 v101, v102, v101
	v_div_scale_f32 v102, vcc, v125, v99, v125
	v_mul_f32_e32 v103, v102, v101
	v_fma_f32 v104, -v100, v103, v102
	v_fmac_f32_e32 v103, v104, v101
	v_fma_f32 v100, -v100, v103, v102
	v_div_fmas_f32 v100, v100, v101, v103
	v_div_fixup_f32 v99, v100, v99, v125
	v_div_scale_f32 v100, s[10:11], v98, v98, v124
	v_rcp_f32_e32 v101, v100
	s_nop 0
	v_fma_f32 v102, -v100, v101, 1.0
	v_fmac_f32_e32 v101, v102, v101
	v_div_scale_f32 v102, vcc, v124, v98, v124
	v_mul_f32_e32 v103, v102, v101
	v_fma_f32 v104, -v100, v103, v102
	v_fmac_f32_e32 v103, v104, v101
	v_fma_f32 v100, -v100, v103, v102
	v_div_fmas_f32 v100, v100, v101, v103
	v_div_fixup_f32 v98, v100, v98, v124
	v_mul_f32_e32 v100, 0xbfb8aa3b, v126
	v_rndne_f32_e32 v101, v100
	v_sub_f32_e32 v102, v100, v101
	v_fma_f32 v100, v126, s54, -v100
	v_fmac_f32_e32 v100, 0xb2a5705f, v126
	v_add_f32_e32 v100, v102, v100
	v_exp_f32_e32 v100, v100
	v_cvt_i32_f32_e32 v101, v101
	v_pk_mul_f32 v[98:99], v[108:109], v[98:99]
	v_ldexp_f32 v100, v100, v101
	v_mul_f32_e32 v101, 0xbfb8aa3b, v127
	v_rndne_f32_e32 v102, v101
	v_sub_f32_e32 v103, v101, v102
	v_fma_f32 v101, v127, s54, -v101
	v_fmac_f32_e32 v101, 0xb2a5705f, v127
; DEVI void lds_put4(char* wl, int RS, int row, int col, float a, float b, float c, float d) { u32x2 w = {cvtpk(a, b), cvtpk(c, d)}; *(u32x2*)(wl + row * RS + col * 2) = w; }
; DEVI float siluf(float x) { return x / (1.f + expf(-x)); }
; DEVI void phase_gemm_f1(const Params& p, int l, char* lds) {
;     ...
; #pragma unroll
;     for (int cg2 = 0; cg2 < 2; ++cg2) {
; #pragma unroll
;       for (int mi = 0; mi < 2; ++mi) {
; #pragma unroll
;         for (int q = 0; q < 4; ++q) {
;           float h[4];
; #pragma unroll
;           for (int j = 0; j < 4; ++j) h[j] = siluf(acc[2 * cg2][mi][q * 4 + j]) * acc[2 * cg2 + 1][mi][q * 4 + j];
;           lds_put4(wl, 144, mi * 32 + r32, cg2 * 32 + q * 8 + hi * 4, h[0], h[1], h[2], h[3]);
;         }
	v_add_f32_e32 v101, v103, v101
	v_exp_f32_e32 v101, v101
	v_cvt_i32_f32_e32 v102, v102
	v_cvt_pk_bf16_f32 v98, v98, v99
	v_ldexp_f32 v101, v101, v102
	s_nop 1
	s_nop 1
	v_pk_add_f32 v[100:101], v[100:101], 1.0 op_sel_hi:[1,0]
	s_nop 0
	v_div_scale_f32 v102, s[10:11], v101, v101, v127
	v_rcp_f32_e32 v103, v102
	s_nop 0
	v_fma_f32 v104, -v102, v103, 1.0
	v_fmac_f32_e32 v103, v104, v103
	v_div_scale_f32 v104, vcc, v127, v101, v127
	v_mul_f32_e32 v105, v104, v103
	v_fma_f32 v106, -v102, v105, v104
	v_fmac_f32_e32 v105, v106, v103
	v_fma_f32 v102, -v102, v105, v104
	v_div_fmas_f32 v102, v102, v103, v105
	v_div_fixup_f32 v101, v102, v101, v127
	v_div_scale_f32 v102, s[10:11], v100, v100, v126
	v_rcp_f32_e32 v103, v102
	s_nop 0
	v_fma_f32 v104, -v102, v103, 1.0
	v_fmac_f32_e32 v103, v104, v103
	v_div_scale_f32 v104, vcc, v126, v100, v126
	v_mul_f32_e32 v105, v104, v103
	v_fma_f32 v106, -v102, v105, v104
	v_fmac_f32_e32 v105, v106, v103
	v_fma_f32 v102, -v102, v105, v104
	v_div_fmas_f32 v102, v102, v103, v105
	v_div_fixup_f32 v100, v102, v100, v126
	v_pk_mul_f32 v[100:101], v[110:111], v[100:101]
	v_cvt_pk_bf16_f32 v99, v100, v101
	ds_write2_b64 v225, v[96:97], v[98:99] offset0:4 offset1:6
	v_mul_f32_e32 v96, 0xbfb8aa3b, v80
	v_rndne_f32_e32 v97, v96
	v_sub_f32_e32 v98, v96, v97
	v_fma_f32 v96, v80, s54, -v96
	v_fmac_f32_e32 v96, 0xb2a5705f, v80
	v_add_f32_e32 v96, v98, v96
	v_exp_f32_e32 v96, v96
	v_cvt_i32_f32_e32 v97, v97
	v_ldexp_f32 v96, v96, v97
	v_mul_f32_e32 v97, 0xbfb8aa3b, v81
	v_rndne_f32_e32 v98, v97
	v_sub_f32_e32 v99, v97, v98
	v_fma_f32 v97, v81, s54, -v97
	v_fmac_f32_e32 v97, 0xb2a5705f, v81
	v_add_f32_e32 v97, v99, v97
	v_exp_f32_e32 v97, v97
	v_cvt_i32_f32_e32 v98, v98
	v_ldexp_f32 v97, v97, v98
	s_nop 0
	s_nop 1
	s_nop 1
	v_pk_add_f32 v[96:97], v[96:97], 1.0 op_sel_hi:[1,0]
	s_nop 0
	v_div_scale_f32 v98, s[10:11], v97, v97, v81
	v_rcp_f32_e32 v99, v98
	s_nop 0
	v_fma_f32 v100, -v98, v99, 1.0
	v_fmac_f32_e32 v99, v100, v99
	v_div_scale_f32 v100, vcc, v81, v97, v81
	v_mul_f32_e32 v101, v100, v99
	v_fma_f32 v102, -v98, v101, v100
	v_fmac_f32_e32 v101, v102, v99
	v_fma_f32 v98, -v98, v101, v100
	v_div_fmas_f32 v98, v98, v99, v101
	v_div_fixup_f32 v81, v98, v97, v81
	v_div_scale_f32 v97, s[10:11], v96, v96, v80
	v_rcp_f32_e32 v98, v97
	s_nop 0
	v_fma_f32 v99, -v97, v98, 1.0
	v_fmac_f32_e32 v98, v99, v98
	v_div_scale_f32 v99, vcc, v80, v96, v80
	v_mul_f32_e32 v100, v99, v98
	v_fma_f32 v101, -v97, v100, v99
	v_fmac_f32_e32 v100, v101, v98
	v_fma_f32 v97, -v97, v100, v99
	v_div_fmas_f32 v97, v97, v98, v100
	v_div_fixup_f32 v80, v97, v96, v80
	v_pk_mul_f32 v[64:65], v[64:65], v[80:81]
	v_mul_f32_e32 v80, 0xbfb8aa3b, v82
	v_rndne_f32_e32 v81, v80
	v_sub_f32_e32 v96, v80, v81
	v_fma_f32 v80, v82, s54, -v80
	v_fmac_f32_e32 v80, 0xb2a5705f, v82
	v_add_f32_e32 v80, v96, v80
	v_exp_f32_e32 v80, v80
	v_cvt_i32_f32_e32 v81, v81
	v_cvt_pk_bf16_f32 v64, v64, v65
	v_ldexp_f32 v80, v80, v81
	v_mul_f32_e32 v81, 0xbfb8aa3b, v83
	v_rndne_f32_e32 v96, v81
	v_sub_f32_e32 v97, v81, v96
	v_fma_f32 v81, v83, s54, -v81
	v_fmac_f32_e32 v81, 0xb2a5705f, v83
	v_add_f32_e32 v81, v97, v81
	v_exp_f32_e32 v81, v81
	v_cvt_i32_f32_e32 v96, v96
	v_ldexp_f32 v81, v81, v96
	s_nop 0
	s_nop 1
	s_nop 1
	v_pk_add_f32 v[80:81], v[80:81], 1.0 op_sel_hi:[1,0]
	s_nop 0
	v_div_scale_f32 v96, s[10:11], v81, v81, v83
	v_rcp_f32_e32 v97, v96
	s_nop 0
	v_fma_f32 v98, -v96, v97, 1.0
	v_fmac_f32_e32 v97, v98, v97
	v_div_scale_f32 v98, vcc, v83, v81, v83
	v_mul_f32_e32 v99, v98, v97
	v_fma_f32 v100, -v96, v99, v98
	v_fmac_f32_e32 v99, v100, v97
	v_fma_f32 v96, -v96, v99, v98
	v_div_fmas_f32 v96, v96, v97, v99
	v_div_fixup_f32 v81, v96, v81, v83
	v_div_scale_f32 v83, s[10:11], v80, v80, v82
	v_rcp_f32_e32 v96, v83
	s_nop 0
	v_fma_f32 v97, -v83, v96, 1.0
	v_fmac_f32_e32 v96, v97, v96
	v_div_scale_f32 v97, vcc, v82, v80, v82
	v_mul_f32_e32 v98, v97, v96
	v_fma_f32 v99, -v83, v98, v97
	v_fmac_f32_e32 v98, v99, v96
	v_fma_f32 v83, -v83, v98, v97
	v_div_fmas_f32 v83, v83, v96, v98
	v_div_fixup_f32 v80, v83, v80, v82
	v_pk_mul_f32 v[66:67], v[66:67], v[80:81]
	v_cvt_pk_bf16_f32 v65, v66, v67
	v_mul_f32_e32 v66, 0xbfb8aa3b, v84
	v_rndne_f32_e32 v67, v66
	v_sub_f32_e32 v80, v66, v67
	v_fma_f32 v66, v84, s54, -v66
	v_fmac_f32_e32 v66, 0xb2a5705f, v84
	v_add_f32_e32 v66, v80, v66
	v_exp_f32_e32 v66, v66
	v_cvt_i32_f32_e32 v67, v67
	v_ldexp_f32 v66, v66, v67
	v_mul_f32_e32 v67, 0xbfb8aa3b, v85
	v_rndne_f32_e32 v80, v67
	v_sub_f32_e32 v81, v67, v80
	v_fma_f32 v67, v85, s54, -v67
	v_fmac_f32_e32 v67, 0xb2a5705f, v85
	v_add_f32_e32 v67, v81, v67
	v_exp_f32_e32 v67, v67
	v_cvt_i32_f32_e32 v80, v80
	v_ldexp_f32 v67, v67, v80
	s_nop 0
	s_nop 1
	s_nop 1
	v_pk_add_f32 v[66:67], v[66:67], 1.0 op_sel_hi:[1,0]
	s_nop 0
	v_div_scale_f32 v80, s[10:11], v67, v67, v85
	v_rcp_f32_e32 v81, v80
	s_nop 0
	v_fma_f32 v82, -v80, v81, 1.0
	v_fmac_f32_e32 v81, v82, v81
	v_div_scale_f32 v82, vcc, v85, v67, v85
	v_mul_f32_e32 v83, v82, v81
	v_fma_f32 v96, -v80, v83, v82
	v_fmac_f32_e32 v83, v96, v81
	v_fma_f32 v80, -v80, v83, v82
	v_div_fmas_f32 v80, v80, v81, v83
	v_div_fixup_f32 v67, v80, v67, v85
	v_div_scale_f32 v80, s[10:11], v66, v66, v84
	v_rcp_f32_e32 v81, v80
	s_nop 0
	v_fma_f32 v82, -v80, v81, 1.0
	v_fmac_f32_e32 v81, v82, v81
	v_div_scale_f32 v82, vcc, v84, v66, v84
	v_mul_f32_e32 v83, v82, v81
	v_fma_f32 v85, -v80, v83, v82
	v_fmac_f32_e32 v83, v85, v81
	v_fma_f32 v80, -v80, v83, v82
	v_div_fmas_f32 v80, v80, v81, v83
	v_div_fixup_f32 v66, v80, v66, v84
	v_pk_mul_f32 v[66:67], v[68:69], v[66:67]
	v_mul_f32_e32 v68, 0xbfb8aa3b, v86
	v_rndne_f32_e32 v69, v68
	v_sub_f32_e32 v80, v68, v69
	v_fma_f32 v68, v86, s54, -v68
; DEVI void lds_put4(char* wl, int RS, int row, int col, float a, float b, float c, float d) { u32x2 w = {cvtpk(a, b), cvtpk(c, d)}; *(u32x2*)(wl + row * RS + col * 2) = w; }
; DEVI float siluf(float x) { return x / (1.f + expf(-x)); }
; DEVI void phase_gemm_f1(const Params& p, int l, char* lds) {
;     ...
; #pragma unroll
;     for (int cg2 = 0; cg2 < 2; ++cg2) {
; #pragma unroll
;       for (int mi = 0; mi < 2; ++mi) {
; #pragma unroll
;         for (int q = 0; q < 4; ++q) {
;           float h[4];
; #pragma unroll
;           for (int j = 0; j < 4; ++j) h[j] = siluf(acc[2 * cg2][mi][q * 4 + j]) * acc[2 * cg2 + 1][mi][q * 4 + j];
;           lds_put4(wl, 144, mi * 32 + r32, cg2 * 32 + q * 8 + hi * 4, h[0], h[1], h[2], h[3]);
;         }
	v_fmac_f32_e32 v68, 0xb2a5705f, v86
	v_add_f32_e32 v68, v80, v68
	v_exp_f32_e32 v68, v68
	v_cvt_i32_f32_e32 v69, v69
	v_ldexp_f32 v68, v68, v69
	v_mul_f32_e32 v69, 0xbfb8aa3b, v87
	v_rndne_f32_e32 v80, v69
	v_sub_f32_e32 v81, v69, v80
	v_fma_f32 v69, v87, s54, -v69
	v_fmac_f32_e32 v69, 0xb2a5705f, v87
	v_add_f32_e32 v69, v81, v69
	v_exp_f32_e32 v69, v69
	v_cvt_i32_f32_e32 v80, v80
	v_ldexp_f32 v69, v69, v80
	s_nop 0
	s_nop 1
	s_nop 1
	v_pk_add_f32 v[68:69], v[68:69], 1.0 op_sel_hi:[1,0]
	s_nop 0
	v_div_scale_f32 v80, s[10:11], v69, v69, v87
	v_rcp_f32_e32 v81, v80
	s_nop 0
	v_fma_f32 v82, -v80, v81, 1.0
	v_fmac_f32_e32 v81, v82, v81
	v_div_scale_f32 v82, vcc, v87, v69, v87
	v_mul_f32_e32 v83, v82, v81
	v_fma_f32 v84, -v80, v83, v82
	v_fmac_f32_e32 v83, v84, v81
	v_fma_f32 v80, -v80, v83, v82
	v_div_fmas_f32 v80, v80, v81, v83
	v_div_fixup_f32 v69, v80, v69, v87
	v_div_scale_f32 v80, s[10:11], v68, v68, v86
	v_rcp_f32_e32 v81, v80
	s_nop 0
	v_fma_f32 v82, -v80, v81, 1.0
	v_fmac_f32_e32 v81, v82, v81
	v_div_scale_f32 v82, vcc, v86, v68, v86
	v_mul_f32_e32 v83, v82, v81
	v_fma_f32 v84, -v80, v83, v82
	v_fmac_f32_e32 v83, v84, v81
	v_fma_f32 v80, -v80, v83, v82
	v_div_fmas_f32 v80, v80, v81, v83
	v_div_fixup_f32 v68, v80, v68, v86
	v_pk_mul_f32 v[68:69], v[70:71], v[68:69]
	v_cvt_pk_bf16_f32 v70, v66, v67
	v_cvt_pk_bf16_f32 v71, v68, v69
	v_add_u32_e32 v66, 0x1000, v225
	ds_write2_b64 v66, v[64:65], v[70:71] offset0:64 offset1:66
	v_mul_f32_e32 v64, 0xbfb8aa3b, v88
	v_rndne_f32_e32 v65, v64
	v_sub_f32_e32 v67, v64, v65
	v_fma_f32 v64, v88, s54, -v64
	v_fmac_f32_e32 v64, 0xb2a5705f, v88
	v_add_f32_e32 v64, v67, v64
	v_exp_f32_e32 v64, v64
	v_cvt_i32_f32_e32 v65, v65
	v_ldexp_f32 v64, v64, v65
	v_mul_f32_e32 v65, 0xbfb8aa3b, v89
	v_rndne_f32_e32 v67, v65
	v_sub_f32_e32 v68, v65, v67
	v_fma_f32 v65, v89, s54, -v65
	v_fmac_f32_e32 v65, 0xb2a5705f, v89
	v_add_f32_e32 v65, v68, v65
	v_exp_f32_e32 v65, v65
	v_cvt_i32_f32_e32 v67, v67
	v_ldexp_f32 v65, v65, v67
	s_nop 0
	s_nop 1
	s_nop 1
	v_pk_add_f32 v[64:65], v[64:65], 1.0 op_sel_hi:[1,0]
	s_nop 0
	v_div_scale_f32 v67, s[10:11], v65, v65, v89
	v_rcp_f32_e32 v68, v67
	s_nop 0
	v_fma_f32 v69, -v67, v68, 1.0
	v_fmac_f32_e32 v68, v69, v68
	v_div_scale_f32 v69, vcc, v89, v65, v89
	v_mul_f32_e32 v70, v69, v68
	v_fma_f32 v71, -v67, v70, v69
	v_fmac_f32_e32 v70, v71, v68
	v_fma_f32 v67, -v67, v70, v69
	v_div_fmas_f32 v67, v67, v68, v70
	v_div_fixup_f32 v65, v67, v65, v89
	v_div_scale_f32 v67, s[10:11], v64, v64, v88
	v_rcp_f32_e32 v68, v67
	s_nop 0
	v_fma_f32 v69, -v67, v68, 1.0
	v_fmac_f32_e32 v68, v69, v68
	v_div_scale_f32 v69, vcc, v88, v64, v88
	v_mul_f32_e32 v70, v69, v68
	v_fma_f32 v71, -v67, v70, v69
	v_fmac_f32_e32 v70, v71, v68
	v_fma_f32 v67, -v67, v70, v69
	v_div_fmas_f32 v67, v67, v68, v70
	v_div_fixup_f32 v64, v67, v64, v88
	v_mul_f32_e32 v67, 0xbfb8aa3b, v90
	v_rndne_f32_e32 v68, v67
	v_sub_f32_e32 v69, v67, v68
	v_fma_f32 v67, v90, s54, -v67
	v_fmac_f32_e32 v67, 0xb2a5705f, v90
	v_add_f32_e32 v67, v69, v67
	v_exp_f32_e32 v67, v67
	v_cvt_i32_f32_e32 v68, v68
	v_pk_mul_f32 v[64:65], v[72:73], v[64:65]
	v_ldexp_f32 v67, v67, v68
	v_cvt_pk_bf16_f32 v64, v64, v65
	s_nop 0
	v_mov_b32_e32 v68, v67
	v_mul_f32_e32 v67, 0xbfb8aa3b, v91
	v_rndne_f32_e32 v69, v67
	v_sub_f32_e32 v70, v67, v69
	v_fma_f32 v67, v91, s54, -v67
	v_fmac_f32_e32 v67, 0xb2a5705f, v91
	v_add_f32_e32 v67, v70, v67
	v_exp_f32_e32 v67, v67
	v_cvt_i32_f32_e32 v69, v69
	v_ldexp_f32 v67, v67, v69
	s_nop 0
	s_nop 1
	v_mov_b32_e32 v69, v67
	v_pk_add_f32 v[68:69], v[68:69], 1.0 op_sel_hi:[1,0]
	s_nop 0
	v_div_scale_f32 v67, s[10:11], v69, v69, v91
	v_rcp_f32_e32 v70, v67
	s_nop 0
	v_fma_f32 v71, -v67, v70, 1.0
	v_fmac_f32_e32 v70, v71, v70
	v_div_scale_f32 v71, vcc, v91, v69, v91
	v_mul_f32_e32 v72, v71, v70
	v_fma_f32 v73, -v67, v72, v71
	v_fmac_f32_e32 v72, v73, v70
	v_fma_f32 v67, -v67, v72, v71
	v_div_fmas_f32 v67, v67, v70, v72
	v_div_fixup_f32 v69, v67, v69, v91
	v_div_scale_f32 v67, s[10:11], v68, v68, v90
	v_rcp_f32_e32 v70, v67
	s_nop 0
	v_fma_f32 v71, -v67, v70, 1.0
	v_fmac_f32_e32 v70, v71, v70
	v_div_scale_f32 v71, vcc, v90, v68, v90
	v_mul_f32_e32 v72, v71, v70
	v_fma_f32 v73, -v67, v72, v71
	v_fmac_f32_e32 v72, v73, v70
	v_fma_f32 v67, -v67, v72, v71
	v_div_fmas_f32 v67, v67, v70, v72
	v_div_fixup_f32 v68, v67, v68, v90
	v_pk_mul_f32 v[68:69], v[74:75], v[68:69]
	v_mul_f32_e32 v67, 0xbfb8aa3b, v92
	v_cvt_pk_bf16_f32 v65, v68, v69
	v_rndne_f32_e32 v68, v67
	v_sub_f32_e32 v69, v67, v68
	v_fma_f32 v67, v92, s54, -v67
	v_fmac_f32_e32 v67, 0xb2a5705f, v92
	v_add_f32_e32 v67, v69, v67
	v_exp_f32_e32 v67, v67
	v_cvt_i32_f32_e32 v68, v68
	v_ldexp_f32 v67, v67, v68
	s_nop 0
	s_nop 1
	v_mov_b32_e32 v68, v67
	v_mul_f32_e32 v67, 0xbfb8aa3b, v93
	v_rndne_f32_e32 v69, v67
	v_sub_f32_e32 v70, v67, v69
	v_fma_f32 v67, v93, s54, -v67
	v_fmac_f32_e32 v67, 0xb2a5705f, v93
	v_add_f32_e32 v67, v70, v67
	v_exp_f32_e32 v67, v67
	v_cvt_i32_f32_e32 v69, v69
	v_ldexp_f32 v67, v67, v69
	s_nop 0
	s_nop 1
	v_mov_b32_e32 v69, v67
	v_pk_add_f32 v[68:69], v[68:69], 1.0 op_sel_hi:[1,0]
	s_nop 0
	v_div_scale_f32 v67, s[10:11], v69, v69, v93
	v_rcp_f32_e32 v70, v67
	s_nop 0
	v_fma_f32 v71, -v67, v70, 1.0
	v_fmac_f32_e32 v70, v71, v70
	v_div_scale_f32 v71, vcc, v93, v69, v93
	v_mul_f32_e32 v72, v71, v70
	v_fma_f32 v73, -v67, v72, v71
	v_fmac_f32_e32 v72, v73, v70
	v_fma_f32 v67, -v67, v72, v71
	v_div_fmas_f32 v67, v67, v70, v72
	v_div_fixup_f32 v69, v67, v69, v93
	v_div_scale_f32 v67, s[10:11], v68, v68, v92
	v_rcp_f32_e32 v70, v67
	s_nop 0
	v_fma_f32 v71, -v67, v70, 1.0
	v_fmac_f32_e32 v70, v71, v70
	v_div_scale_f32 v71, vcc, v92, v68, v92
; DEVI void lds_put4(char* wl, int RS, int row, int col, float a, float b, float c, float d) { u32x2 w = {cvtpk(a, b), cvtpk(c, d)}; *(u32x2*)(wl + row * RS + col * 2) = w; }
; DEVI float siluf(float x) { return x / (1.f + expf(-x)); }
; DEVI void phase_gemm_f1(const Params& p, int l, char* lds) {
;     ...
; #pragma unroll
;     for (int cg2 = 0; cg2 < 2; ++cg2) {
; #pragma unroll
;       for (int mi = 0; mi < 2; ++mi) {
; #pragma unroll
;         for (int q = 0; q < 4; ++q) {
;           float h[4];
; #pragma unroll
;           for (int j = 0; j < 4; ++j) h[j] = siluf(acc[2 * cg2][mi][q * 4 + j]) * acc[2 * cg2 + 1][mi][q * 4 + j];
;           lds_put4(wl, 144, mi * 32 + r32, cg2 * 32 + q * 8 + hi * 4, h[0], h[1], h[2], h[3]);
;         }
	v_mul_f32_e32 v72, v71, v70
	v_fma_f32 v73, -v67, v72, v71
	v_fmac_f32_e32 v72, v73, v70
	v_fma_f32 v67, -v67, v72, v71
	v_div_fmas_f32 v67, v67, v70, v72
	v_div_fixup_f32 v68, v67, v68, v92
	v_mul_f32_e32 v67, 0xbfb8aa3b, v94
	v_rndne_f32_e32 v70, v67
	v_sub_f32_e32 v71, v67, v70
	v_fma_f32 v67, v94, s54, -v67
	v_fmac_f32_e32 v67, 0xb2a5705f, v94
	v_add_f32_e32 v67, v71, v67
	v_exp_f32_e32 v67, v67
	v_cvt_i32_f32_e32 v70, v70
	v_pk_mul_f32 v[68:69], v[76:77], v[68:69]
	v_ldexp_f32 v67, v67, v70
	v_cvt_pk_bf16_f32 v68, v68, v69
	s_nop 0
	v_mov_b32_e32 v70, v67
	v_mul_f32_e32 v67, 0xbfb8aa3b, v95
	v_rndne_f32_e32 v71, v67
	v_sub_f32_e32 v72, v67, v71
	v_fma_f32 v67, v95, s54, -v67
	v_fmac_f32_e32 v67, 0xb2a5705f, v95
	v_add_f32_e32 v67, v72, v67
	v_exp_f32_e32 v67, v67
	v_cvt_i32_f32_e32 v71, v71
	v_ldexp_f32 v67, v67, v71
	s_nop 0
	s_nop 1
	v_mov_b32_e32 v71, v67
	v_pk_add_f32 v[70:71], v[70:71], 1.0 op_sel_hi:[1,0]
	s_nop 0
	v_div_scale_f32 v67, s[10:11], v71, v71, v95
	v_rcp_f32_e32 v72, v67
	s_nop 0
	v_fma_f32 v73, -v67, v72, 1.0
	v_fmac_f32_e32 v72, v73, v72
	v_div_scale_f32 v73, vcc, v95, v71, v95
	v_mul_f32_e32 v74, v73, v72
	v_fma_f32 v75, -v67, v74, v73
	v_fmac_f32_e32 v74, v75, v72
	v_fma_f32 v67, -v67, v74, v73
	v_div_fmas_f32 v67, v67, v72, v74
	v_div_fixup_f32 v71, v67, v71, v95
	v_div_scale_f32 v67, s[10:11], v70, v70, v94
	v_rcp_f32_e32 v72, v67
	s_nop 0
	v_fma_f32 v73, -v67, v72, 1.0
	v_fmac_f32_e32 v72, v73, v72
	v_div_scale_f32 v73, vcc, v94, v70, v94
	v_mul_f32_e32 v74, v73, v72
	v_fma_f32 v75, -v67, v74, v73
	v_fmac_f32_e32 v74, v75, v72
	v_fma_f32 v67, -v67, v74, v73
	v_div_fmas_f32 v67, v67, v72, v74
	v_div_fixup_f32 v70, v67, v70, v94
	v_pk_mul_f32 v[70:71], v[78:79], v[70:71]
	v_cvt_pk_bf16_f32 v69, v70, v71
	ds_write2_b64 v66, v[64:65], v[68:69] offset0:68 offset1:70
	v_mul_f32_e32 v64, 0xbfb8aa3b, v48
	v_rndne_f32_e32 v65, v64
	v_sub_f32_e32 v67, v64, v65
	v_fma_f32 v64, v48, s54, -v64
	v_fmac_f32_e32 v64, 0xb2a5705f, v48
	v_add_f32_e32 v64, v67, v64
	v_exp_f32_e32 v64, v64
	v_cvt_i32_f32_e32 v65, v65
	v_ldexp_f32 v64, v64, v65
	v_mul_f32_e32 v65, 0xbfb8aa3b, v49
	v_rndne_f32_e32 v67, v65
	v_sub_f32_e32 v68, v65, v67
	v_fma_f32 v65, v49, s54, -v65
	v_fmac_f32_e32 v65, 0xb2a5705f, v49
	v_add_f32_e32 v65, v68, v65
	v_exp_f32_e32 v65, v65
	v_cvt_i32_f32_e32 v67, v67
	v_ldexp_f32 v65, v65, v67
	s_nop 0
	s_nop 1
	s_nop 1
	v_pk_add_f32 v[64:65], v[64:65], 1.0 op_sel_hi:[1,0]
	s_nop 0
	v_div_scale_f32 v67, s[10:11], v65, v65, v49
	v_rcp_f32_e32 v68, v67
	s_nop 0
	v_fma_f32 v69, -v67, v68, 1.0
	v_fmac_f32_e32 v68, v69, v68
	v_div_scale_f32 v69, vcc, v49, v65, v49
	v_mul_f32_e32 v70, v69, v68
	v_fma_f32 v71, -v67, v70, v69
	v_fmac_f32_e32 v70, v71, v68
	v_fma_f32 v67, -v67, v70, v69
	v_div_fmas_f32 v67, v67, v68, v70
	v_div_fixup_f32 v49, v67, v65, v49
	v_div_scale_f32 v65, s[10:11], v64, v64, v48
	v_rcp_f32_e32 v67, v65
	s_nop 0
	v_fma_f32 v68, -v65, v67, 1.0
	v_fmac_f32_e32 v67, v68, v67
	v_div_scale_f32 v68, vcc, v48, v64, v48
	v_mul_f32_e32 v69, v68, v67
	v_fma_f32 v70, -v65, v69, v68
	v_fmac_f32_e32 v69, v70, v67
	v_fma_f32 v65, -v65, v69, v68
	v_div_fmas_f32 v65, v65, v67, v69
	v_div_fixup_f32 v48, v65, v64, v48
	v_pk_mul_f32 v[32:33], v[32:33], v[48:49]
	v_mul_f32_e32 v48, 0xbfb8aa3b, v50
	v_rndne_f32_e32 v49, v48
	v_sub_f32_e32 v64, v48, v49
	v_fma_f32 v48, v50, s54, -v48
	v_fmac_f32_e32 v48, 0xb2a5705f, v50
	v_add_f32_e32 v48, v64, v48
	v_exp_f32_e32 v48, v48
	v_cvt_i32_f32_e32 v49, v49
	v_cvt_pk_bf16_f32 v32, v32, v33
	v_ldexp_f32 v48, v48, v49
	v_mul_f32_e32 v49, 0xbfb8aa3b, v51
	v_rndne_f32_e32 v64, v49
	v_sub_f32_e32 v65, v49, v64
	v_fma_f32 v49, v51, s54, -v49
	v_fmac_f32_e32 v49, 0xb2a5705f, v51
	v_add_f32_e32 v49, v65, v49
	v_exp_f32_e32 v49, v49
	v_cvt_i32_f32_e32 v64, v64
	v_ldexp_f32 v49, v49, v64
	s_nop 0
	s_nop 1
	s_nop 1
	v_pk_add_f32 v[48:49], v[48:49], 1.0 op_sel_hi:[1,0]
	s_nop 0
	v_div_scale_f32 v64, s[10:11], v49, v49, v51
	v_rcp_f32_e32 v65, v64
	s_nop 0
	v_fma_f32 v67, -v64, v65, 1.0
	v_fmac_f32_e32 v65, v67, v65
	v_div_scale_f32 v67, vcc, v51, v49, v51
	v_mul_f32_e32 v68, v67, v65
	v_fma_f32 v69, -v64, v68, v67
	v_fmac_f32_e32 v68, v69, v65
	v_fma_f32 v64, -v64, v68, v67
	v_div_fmas_f32 v64, v64, v65, v68
	v_div_fixup_f32 v49, v64, v49, v51
	v_div_scale_f32 v51, s[10:11], v48, v48, v50
	v_rcp_f32_e32 v64, v51
	s_nop 0
	v_fma_f32 v65, -v51, v64, 1.0
	v_fmac_f32_e32 v64, v65, v64
	v_div_scale_f32 v65, vcc, v50, v48, v50
	v_mul_f32_e32 v67, v65, v64
	v_fma_f32 v68, -v51, v67, v65
	v_fmac_f32_e32 v67, v68, v64
	v_fma_f32 v51, -v51, v67, v65
	v_div_fmas_f32 v51, v51, v64, v67
	v_div_fixup_f32 v48, v51, v48, v50
	v_pk_mul_f32 v[34:35], v[34:35], v[48:49]
	v_cvt_pk_bf16_f32 v33, v34, v35
	v_mul_f32_e32 v34, 0xbfb8aa3b, v52
	v_rndne_f32_e32 v35, v34
	v_sub_f32_e32 v48, v34, v35
	v_fma_f32 v34, v52, s54, -v34
	v_fmac_f32_e32 v34, 0xb2a5705f, v52
	v_add_f32_e32 v34, v48, v34
	v_exp_f32_e32 v34, v34
	v_cvt_i32_f32_e32 v35, v35
	v_ldexp_f32 v34, v34, v35
	v_mul_f32_e32 v35, 0xbfb8aa3b, v53
	v_rndne_f32_e32 v48, v35
	v_sub_f32_e32 v49, v35, v48
	v_fma_f32 v35, v53, s54, -v35
	v_fmac_f32_e32 v35, 0xb2a5705f, v53
	v_add_f32_e32 v35, v49, v35
	v_exp_f32_e32 v35, v35
	v_cvt_i32_f32_e32 v48, v48
	v_ldexp_f32 v35, v35, v48
	s_nop 0
	s_nop 1
	s_nop 1
	v_pk_add_f32 v[34:35], v[34:35], 1.0 op_sel_hi:[1,0]
	s_nop 0
	v_div_scale_f32 v48, s[10:11], v35, v35, v53
	v_rcp_f32_e32 v49, v48
	s_nop 0
	v_fma_f32 v50, -v48, v49, 1.0
	v_fmac_f32_e32 v49, v50, v49
	v_div_scale_f32 v50, vcc, v53, v35, v53
	v_mul_f32_e32 v51, v50, v49
	v_fma_f32 v64, -v48, v51, v50
	v_fmac_f32_e32 v51, v64, v49
	v_fma_f32 v48, -v48, v51, v50
; DEVI void lds_put4(char* wl, int RS, int row, int col, float a, float b, float c, float d) { u32x2 w = {cvtpk(a, b), cvtpk(c, d)}; *(u32x2*)(wl + row * RS + col * 2) = w; }
; DEVI float siluf(float x) { return x / (1.f + expf(-x)); }
; DEVI void phase_gemm_f1(const Params& p, int l, char* lds) {
;     ...
; #pragma unroll
;     for (int cg2 = 0; cg2 < 2; ++cg2) {
; #pragma unroll
;       for (int mi = 0; mi < 2; ++mi) {
; #pragma unroll
;         for (int q = 0; q < 4; ++q) {
;           float h[4];
; #pragma unroll
;           for (int j = 0; j < 4; ++j) h[j] = siluf(acc[2 * cg2][mi][q * 4 + j]) * acc[2 * cg2 + 1][mi][q * 4 + j];
;           lds_put4(wl, 144, mi * 32 + r32, cg2 * 32 + q * 8 + hi * 4, h[0], h[1], h[2], h[3]);
;         }
	v_div_fmas_f32 v48, v48, v49, v51
	v_div_fixup_f32 v35, v48, v35, v53
	v_div_scale_f32 v48, s[10:11], v34, v34, v52
	v_rcp_f32_e32 v49, v48
	s_nop 0
	v_fma_f32 v50, -v48, v49, 1.0
	v_fmac_f32_e32 v49, v50, v49
	v_div_scale_f32 v50, vcc, v52, v34, v52
	v_mul_f32_e32 v51, v50, v49
	v_fma_f32 v53, -v48, v51, v50
	v_fmac_f32_e32 v51, v53, v49
	v_fma_f32 v48, -v48, v51, v50
	v_div_fmas_f32 v48, v48, v49, v51
	v_div_fixup_f32 v34, v48, v34, v52
	v_pk_mul_f32 v[34:35], v[36:37], v[34:35]
	v_mul_f32_e32 v36, 0xbfb8aa3b, v54
	v_rndne_f32_e32 v37, v36
	v_sub_f32_e32 v48, v36, v37
	v_fma_f32 v36, v54, s54, -v36
	v_fmac_f32_e32 v36, 0xb2a5705f, v54
	v_add_f32_e32 v36, v48, v36
	v_exp_f32_e32 v36, v36
	v_cvt_i32_f32_e32 v37, v37
	v_cvt_pk_bf16_f32 v34, v34, v35
	v_ldexp_f32 v36, v36, v37
	v_mul_f32_e32 v37, 0xbfb8aa3b, v55
	v_rndne_f32_e32 v48, v37
	v_sub_f32_e32 v49, v37, v48
	v_fma_f32 v37, v55, s54, -v37
	v_fmac_f32_e32 v37, 0xb2a5705f, v55
	v_add_f32_e32 v37, v49, v37
	v_exp_f32_e32 v37, v37
	v_cvt_i32_f32_e32 v48, v48
	v_ldexp_f32 v37, v37, v48
	s_nop 0
	s_nop 1
	s_nop 1
	v_pk_add_f32 v[36:37], v[36:37], 1.0 op_sel_hi:[1,0]
	s_nop 0
	v_div_scale_f32 v48, s[10:11], v37, v37, v55
	v_rcp_f32_e32 v49, v48
	s_nop 0
	v_fma_f32 v50, -v48, v49, 1.0
	v_fmac_f32_e32 v49, v50, v49
	v_div_scale_f32 v50, vcc, v55, v37, v55
	v_mul_f32_e32 v51, v50, v49
	v_fma_f32 v52, -v48, v51, v50
	v_fmac_f32_e32 v51, v52, v49
	v_fma_f32 v48, -v48, v51, v50
	v_div_fmas_f32 v48, v48, v49, v51
	v_div_fixup_f32 v37, v48, v37, v55
	v_div_scale_f32 v48, s[10:11], v36, v36, v54
	v_rcp_f32_e32 v49, v48
	s_nop 0
	v_fma_f32 v50, -v48, v49, 1.0
	v_fmac_f32_e32 v49, v50, v49
	v_div_scale_f32 v50, vcc, v54, v36, v54
	v_mul_f32_e32 v51, v50, v49
	v_fma_f32 v52, -v48, v51, v50
	v_fmac_f32_e32 v51, v52, v49
	v_fma_f32 v48, -v48, v51, v50
	v_div_fmas_f32 v48, v48, v49, v51
	v_div_fixup_f32 v36, v48, v36, v54
	v_pk_mul_f32 v[36:37], v[38:39], v[36:37]
	v_cvt_pk_bf16_f32 v35, v36, v37
	ds_write2_b64 v225, v[32:33], v[34:35] offset0:8 offset1:10
	v_mul_f32_e32 v32, 0xbfb8aa3b, v56
	v_rndne_f32_e32 v33, v32
	v_sub_f32_e32 v34, v32, v33
	v_fma_f32 v32, v56, s54, -v32
	v_fmac_f32_e32 v32, 0xb2a5705f, v56
	v_add_f32_e32 v32, v34, v32
	v_exp_f32_e32 v32, v32
	v_cvt_i32_f32_e32 v33, v33
	v_ldexp_f32 v32, v32, v33
	v_mul_f32_e32 v33, 0xbfb8aa3b, v57
	v_rndne_f32_e32 v34, v33
	v_sub_f32_e32 v35, v33, v34
	v_fma_f32 v33, v57, s54, -v33
	v_fmac_f32_e32 v33, 0xb2a5705f, v57
	v_add_f32_e32 v33, v35, v33
	v_exp_f32_e32 v33, v33
	v_cvt_i32_f32_e32 v34, v34
	v_ldexp_f32 v33, v33, v34
	s_nop 0
	s_nop 1
	s_nop 1
	v_pk_add_f32 v[32:33], v[32:33], 1.0 op_sel_hi:[1,0]
	s_nop 0
	v_div_scale_f32 v34, s[10:11], v33, v33, v57
	v_rcp_f32_e32 v35, v34
	s_nop 0
	v_fma_f32 v36, -v34, v35, 1.0
	v_fmac_f32_e32 v35, v36, v35
	v_div_scale_f32 v36, vcc, v57, v33, v57
	v_mul_f32_e32 v37, v36, v35
	v_fma_f32 v38, -v34, v37, v36
	v_fmac_f32_e32 v37, v38, v35
	v_fma_f32 v34, -v34, v37, v36
	v_div_fmas_f32 v34, v34, v35, v37
	v_div_fixup_f32 v33, v34, v33, v57
	v_div_scale_f32 v34, s[10:11], v32, v32, v56
	v_rcp_f32_e32 v35, v34
	s_nop 0
	v_fma_f32 v36, -v34, v35, 1.0
	v_fmac_f32_e32 v35, v36, v35
	v_div_scale_f32 v36, vcc, v56, v32, v56
	v_mul_f32_e32 v37, v36, v35
	v_fma_f32 v38, -v34, v37, v36
	v_fmac_f32_e32 v37, v38, v35
	v_fma_f32 v34, -v34, v37, v36
	v_div_fmas_f32 v34, v34, v35, v37
	v_div_fixup_f32 v32, v34, v32, v56
	v_mul_f32_e32 v34, 0xbfb8aa3b, v58
	v_rndne_f32_e32 v35, v34
	v_sub_f32_e32 v36, v34, v35
	v_fma_f32 v34, v58, s54, -v34
	v_fmac_f32_e32 v34, 0xb2a5705f, v58
	v_add_f32_e32 v34, v36, v34
	v_exp_f32_e32 v34, v34
	v_cvt_i32_f32_e32 v35, v35
	v_pk_mul_f32 v[32:33], v[40:41], v[32:33]
	v_ldexp_f32 v34, v34, v35
	v_mul_f32_e32 v35, 0xbfb8aa3b, v59
	v_rndne_f32_e32 v36, v35
	v_sub_f32_e32 v37, v35, v36
	v_fma_f32 v35, v59, s54, -v35
	v_fmac_f32_e32 v35, 0xb2a5705f, v59
	v_add_f32_e32 v35, v37, v35
	v_exp_f32_e32 v35, v35
	v_cvt_i32_f32_e32 v36, v36
	v_cvt_pk_bf16_f32 v32, v32, v33
	v_ldexp_f32 v35, v35, v36
	s_nop 1
	s_nop 1
	v_pk_add_f32 v[34:35], v[34:35], 1.0 op_sel_hi:[1,0]
	s_nop 0
	v_div_scale_f32 v36, s[10:11], v35, v35, v59
	v_rcp_f32_e32 v37, v36
	s_nop 0
	v_fma_f32 v38, -v36, v37, 1.0
	v_fmac_f32_e32 v37, v38, v37
	v_div_scale_f32 v38, vcc, v59, v35, v59
	v_mul_f32_e32 v39, v38, v37
	v_fma_f32 v40, -v36, v39, v38
	v_fmac_f32_e32 v39, v40, v37
	v_fma_f32 v36, -v36, v39, v38
	v_div_fmas_f32 v36, v36, v37, v39
	v_div_fixup_f32 v35, v36, v35, v59
	v_div_scale_f32 v36, s[10:11], v34, v34, v58
	v_rcp_f32_e32 v37, v36
	s_nop 0
	v_fma_f32 v38, -v36, v37, 1.0
	v_fmac_f32_e32 v37, v38, v37
	v_div_scale_f32 v38, vcc, v58, v34, v58
	v_mul_f32_e32 v39, v38, v37
	v_fma_f32 v40, -v36, v39, v38
	v_fmac_f32_e32 v39, v40, v37
	v_fma_f32 v36, -v36, v39, v38
	v_div_fmas_f32 v36, v36, v37, v39
	v_div_fixup_f32 v34, v36, v34, v58
	v_pk_mul_f32 v[34:35], v[42:43], v[34:35]
	v_cvt_pk_bf16_f32 v33, v34, v35
	v_mul_f32_e32 v34, 0xbfb8aa3b, v60
	v_rndne_f32_e32 v35, v34
	v_sub_f32_e32 v36, v34, v35
	v_fma_f32 v34, v60, s54, -v34
	v_fmac_f32_e32 v34, 0xb2a5705f, v60
	v_add_f32_e32 v34, v36, v34
	v_exp_f32_e32 v34, v34
	v_cvt_i32_f32_e32 v35, v35
	v_ldexp_f32 v34, v34, v35
	v_mul_f32_e32 v35, 0xbfb8aa3b, v61
	v_rndne_f32_e32 v36, v35
	v_sub_f32_e32 v37, v35, v36
	v_fma_f32 v35, v61, s54, -v35
	v_fmac_f32_e32 v35, 0xb2a5705f, v61
	v_add_f32_e32 v35, v37, v35
	v_exp_f32_e32 v35, v35
	v_cvt_i32_f32_e32 v36, v36
	v_ldexp_f32 v35, v35, v36
	s_nop 0
	s_nop 1
	s_nop 1
	v_pk_add_f32 v[34:35], v[34:35], 1.0 op_sel_hi:[1,0]
	s_nop 0
	v_div_scale_f32 v36, s[10:11], v35, v35, v61
	v_rcp_f32_e32 v37, v36
	s_nop 0
	v_fma_f32 v38, -v36, v37, 1.0
; DEVI void lds_put4(char* wl, int RS, int row, int col, float a, float b, float c, float d) { u32x2 w = {cvtpk(a, b), cvtpk(c, d)}; *(u32x2*)(wl + row * RS + col * 2) = w; }
; DEVI float siluf(float x) { return x / (1.f + expf(-x)); }
; DEVI void phase_gemm_f1(const Params& p, int l, char* lds) {
;     ...
; #pragma unroll
;     for (int cg2 = 0; cg2 < 2; ++cg2) {
; #pragma unroll
;       for (int mi = 0; mi < 2; ++mi) {
; #pragma unroll
;         for (int q = 0; q < 4; ++q) {
;           float h[4];
; #pragma unroll
;           for (int j = 0; j < 4; ++j) h[j] = siluf(acc[2 * cg2][mi][q * 4 + j]) * acc[2 * cg2 + 1][mi][q * 4 + j];
;           lds_put4(wl, 144, mi * 32 + r32, cg2 * 32 + q * 8 + hi * 4, h[0], h[1], h[2], h[3]);
;         }
	v_fmac_f32_e32 v37, v38, v37
	v_div_scale_f32 v38, vcc, v61, v35, v61
	v_mul_f32_e32 v39, v38, v37
	v_fma_f32 v40, -v36, v39, v38
	v_fmac_f32_e32 v39, v40, v37
	v_fma_f32 v36, -v36, v39, v38
	v_div_fmas_f32 v36, v36, v37, v39
	v_div_fixup_f32 v35, v36, v35, v61
	v_div_scale_f32 v36, s[10:11], v34, v34, v60
	v_rcp_f32_e32 v37, v36
	s_nop 0
	v_fma_f32 v38, -v36, v37, 1.0
	v_fmac_f32_e32 v37, v38, v37
	v_div_scale_f32 v38, vcc, v60, v34, v60
	v_mul_f32_e32 v39, v38, v37
	v_fma_f32 v40, -v36, v39, v38
	v_fmac_f32_e32 v39, v40, v37
	v_fma_f32 v36, -v36, v39, v38
	v_div_fmas_f32 v36, v36, v37, v39
	v_div_fixup_f32 v34, v36, v34, v60
	v_mul_f32_e32 v36, 0xbfb8aa3b, v62
	v_rndne_f32_e32 v37, v36
	v_sub_f32_e32 v38, v36, v37
	v_fma_f32 v36, v62, s54, -v36
	v_fmac_f32_e32 v36, 0xb2a5705f, v62
	v_add_f32_e32 v36, v38, v36
	v_exp_f32_e32 v36, v36
	v_cvt_i32_f32_e32 v37, v37
	v_pk_mul_f32 v[34:35], v[44:45], v[34:35]
	v_ldexp_f32 v36, v36, v37
	v_mul_f32_e32 v37, 0xbfb8aa3b, v63
	v_rndne_f32_e32 v38, v37
	v_sub_f32_e32 v39, v37, v38
	v_fma_f32 v37, v63, s54, -v37
	v_fmac_f32_e32 v37, 0xb2a5705f, v63
	v_add_f32_e32 v37, v39, v37
	v_exp_f32_e32 v37, v37
	v_cvt_i32_f32_e32 v38, v38
	v_cvt_pk_bf16_f32 v34, v34, v35
	v_ldexp_f32 v37, v37, v38
	s_nop 1
	s_nop 1
	v_pk_add_f32 v[36:37], v[36:37], 1.0 op_sel_hi:[1,0]
	s_nop 0
	v_div_scale_f32 v38, s[10:11], v37, v37, v63
	v_rcp_f32_e32 v39, v38
	s_nop 0
	v_fma_f32 v40, -v38, v39, 1.0
	v_fmac_f32_e32 v39, v40, v39
	v_div_scale_f32 v40, vcc, v63, v37, v63
	v_mul_f32_e32 v41, v40, v39
	v_fma_f32 v42, -v38, v41, v40
	v_fmac_f32_e32 v41, v42, v39
	v_fma_f32 v38, -v38, v41, v40
	v_div_fmas_f32 v38, v38, v39, v41
	v_div_fixup_f32 v37, v38, v37, v63
	v_div_scale_f32 v38, s[10:11], v36, v36, v62
	v_rcp_f32_e32 v39, v38
	s_nop 0
	v_fma_f32 v40, -v38, v39, 1.0
	v_fmac_f32_e32 v39, v40, v39
	v_div_scale_f32 v40, vcc, v62, v36, v62
	v_mul_f32_e32 v41, v40, v39
	v_fma_f32 v42, -v38, v41, v40
	v_fmac_f32_e32 v41, v42, v39
	v_fma_f32 v38, -v38, v41, v40
	v_div_fmas_f32 v38, v38, v39, v41
	v_div_fixup_f32 v36, v38, v36, v62
	v_pk_mul_f32 v[36:37], v[46:47], v[36:37]
	v_cvt_pk_bf16_f32 v35, v36, v37
	ds_write2_b64 v225, v[32:33], v[34:35] offset0:12 offset1:14
	v_mul_f32_e32 v32, 0xbfb8aa3b, v16
	v_rndne_f32_e32 v33, v32
	v_sub_f32_e32 v34, v32, v33
	v_fma_f32 v32, v16, s54, -v32
	v_fmac_f32_e32 v32, 0xb2a5705f, v16
	v_add_f32_e32 v32, v34, v32
	v_exp_f32_e32 v32, v32
	v_cvt_i32_f32_e32 v33, v33
	v_ldexp_f32 v32, v32, v33
	v_mul_f32_e32 v33, 0xbfb8aa3b, v17
	v_rndne_f32_e32 v34, v33
	v_sub_f32_e32 v35, v33, v34
	v_fma_f32 v33, v17, s54, -v33
	v_fmac_f32_e32 v33, 0xb2a5705f, v17
	v_add_f32_e32 v33, v35, v33
	v_exp_f32_e32 v33, v33
	v_cvt_i32_f32_e32 v34, v34
	v_ldexp_f32 v33, v33, v34
	s_nop 0
	s_nop 1
	s_nop 1
	v_pk_add_f32 v[32:33], v[32:33], 1.0 op_sel_hi:[1,0]
	s_nop 0
	v_div_scale_f32 v34, s[10:11], v33, v33, v17
	v_rcp_f32_e32 v35, v34
	s_nop 0
	v_fma_f32 v36, -v34, v35, 1.0
	v_fmac_f32_e32 v35, v36, v35
	v_div_scale_f32 v36, vcc, v17, v33, v17
	v_mul_f32_e32 v37, v36, v35
	v_fma_f32 v38, -v34, v37, v36
	v_fmac_f32_e32 v37, v38, v35
	v_fma_f32 v34, -v34, v37, v36
	v_div_fmas_f32 v34, v34, v35, v37
	v_div_fixup_f32 v17, v34, v33, v17
	v_div_scale_f32 v33, s[10:11], v32, v32, v16
	v_rcp_f32_e32 v34, v33
	s_nop 0
	v_fma_f32 v35, -v33, v34, 1.0
	v_fmac_f32_e32 v34, v35, v34
	v_div_scale_f32 v35, vcc, v16, v32, v16
	v_mul_f32_e32 v36, v35, v34
	v_fma_f32 v37, -v33, v36, v35
	v_fmac_f32_e32 v36, v37, v34
	v_fma_f32 v33, -v33, v36, v35
	v_div_fmas_f32 v33, v33, v34, v36
	v_div_fixup_f32 v16, v33, v32, v16
	v_pk_mul_f32 v[0:1], v[0:1], v[16:17]
	v_mul_f32_e32 v16, 0xbfb8aa3b, v18
	v_rndne_f32_e32 v17, v16
	v_sub_f32_e32 v32, v16, v17
	v_fma_f32 v16, v18, s54, -v16
	v_fmac_f32_e32 v16, 0xb2a5705f, v18
	v_add_f32_e32 v16, v32, v16
	v_exp_f32_e32 v16, v16
	v_cvt_i32_f32_e32 v17, v17
	v_cvt_pk_bf16_f32 v0, v0, v1
	v_ldexp_f32 v16, v16, v17
	v_mul_f32_e32 v17, 0xbfb8aa3b, v19
	v_rndne_f32_e32 v32, v17
	v_sub_f32_e32 v33, v17, v32
	v_fma_f32 v17, v19, s54, -v17
	v_fmac_f32_e32 v17, 0xb2a5705f, v19
	v_add_f32_e32 v17, v33, v17
	v_exp_f32_e32 v17, v17
	v_cvt_i32_f32_e32 v32, v32
	v_ldexp_f32 v17, v17, v32
	s_nop 0
	s_nop 1
	s_nop 1
	v_pk_add_f32 v[16:17], v[16:17], 1.0 op_sel_hi:[1,0]
	s_nop 0
	v_div_scale_f32 v32, s[10:11], v17, v17, v19
	v_rcp_f32_e32 v33, v32
	s_nop 0
	v_fma_f32 v34, -v32, v33, 1.0
	v_fmac_f32_e32 v33, v34, v33
	v_div_scale_f32 v34, vcc, v19, v17, v19
	v_mul_f32_e32 v35, v34, v33
	v_fma_f32 v36, -v32, v35, v34
	v_fmac_f32_e32 v35, v36, v33
	v_fma_f32 v32, -v32, v35, v34
	v_div_fmas_f32 v32, v32, v33, v35
	v_div_fixup_f32 v17, v32, v17, v19
	v_div_scale_f32 v19, s[10:11], v16, v16, v18
	v_rcp_f32_e32 v32, v19
	s_nop 0
	v_fma_f32 v33, -v19, v32, 1.0
	v_fmac_f32_e32 v32, v33, v32
	v_div_scale_f32 v33, vcc, v18, v16, v18
	v_mul_f32_e32 v34, v33, v32
	v_fma_f32 v35, -v19, v34, v33
	v_fmac_f32_e32 v34, v35, v32
	v_fma_f32 v19, -v19, v34, v33
	v_div_fmas_f32 v19, v19, v32, v34
	v_div_fixup_f32 v16, v19, v16, v18
	v_pk_mul_f32 v[2:3], v[2:3], v[16:17]
	v_cvt_pk_bf16_f32 v1, v2, v3
	v_mul_f32_e32 v2, 0xbfb8aa3b, v20
	v_rndne_f32_e32 v3, v2
	v_sub_f32_e32 v16, v2, v3
	v_fma_f32 v2, v20, s54, -v2
	v_fmac_f32_e32 v2, 0xb2a5705f, v20
	v_add_f32_e32 v2, v16, v2
	v_exp_f32_e32 v2, v2
	v_cvt_i32_f32_e32 v3, v3
	v_ldexp_f32 v2, v2, v3
	v_mul_f32_e32 v3, 0xbfb8aa3b, v21
	v_rndne_f32_e32 v16, v3
	v_sub_f32_e32 v17, v3, v16
	v_fma_f32 v3, v21, s54, -v3
	v_fmac_f32_e32 v3, 0xb2a5705f, v21
	v_add_f32_e32 v3, v17, v3
	v_exp_f32_e32 v3, v3
	v_cvt_i32_f32_e32 v16, v16
	v_ldexp_f32 v3, v3, v16
	s_nop 0
	s_nop 1
	s_nop 1
; DEVI void lds_put4(char* wl, int RS, int row, int col, float a, float b, float c, float d) { u32x2 w = {cvtpk(a, b), cvtpk(c, d)}; *(u32x2*)(wl + row * RS + col * 2) = w; }
; DEVI float siluf(float x) { return x / (1.f + expf(-x)); }
; DEVI void phase_gemm_f1(const Params& p, int l, char* lds) {
;     ...
; #pragma unroll
;     for (int cg2 = 0; cg2 < 2; ++cg2) {
; #pragma unroll
;       for (int mi = 0; mi < 2; ++mi) {
; #pragma unroll
;         for (int q = 0; q < 4; ++q) {
;           float h[4];
; #pragma unroll
;           for (int j = 0; j < 4; ++j) h[j] = siluf(acc[2 * cg2][mi][q * 4 + j]) * acc[2 * cg2 + 1][mi][q * 4 + j];
;           lds_put4(wl, 144, mi * 32 + r32, cg2 * 32 + q * 8 + hi * 4, h[0], h[1], h[2], h[3]);
;         }
;       }
;     }
;     wave_tile_store<64>(wl, hid + (long)(m0 + wm * 64) * FH + (tn * 4 + wn * 2) * 32, FH, lane);
	v_pk_add_f32 v[2:3], v[2:3], 1.0 op_sel_hi:[1,0]
	s_nop 0
	v_div_scale_f32 v16, s[10:11], v3, v3, v21
	v_rcp_f32_e32 v17, v16
	s_nop 0
	v_fma_f32 v18, -v16, v17, 1.0
	v_fmac_f32_e32 v17, v18, v17
	v_div_scale_f32 v18, vcc, v21, v3, v21
	v_mul_f32_e32 v19, v18, v17
	v_fma_f32 v32, -v16, v19, v18
	v_fmac_f32_e32 v19, v32, v17
	v_fma_f32 v16, -v16, v19, v18
	v_div_fmas_f32 v16, v16, v17, v19
	v_div_fixup_f32 v3, v16, v3, v21
	v_div_scale_f32 v16, s[10:11], v2, v2, v20
	v_rcp_f32_e32 v17, v16
	s_nop 0
	v_fma_f32 v18, -v16, v17, 1.0
	v_fmac_f32_e32 v17, v18, v17
	v_div_scale_f32 v18, vcc, v20, v2, v20
	v_mul_f32_e32 v19, v18, v17
	v_fma_f32 v21, -v16, v19, v18
	v_fmac_f32_e32 v19, v21, v17
	v_fma_f32 v16, -v16, v19, v18
	v_div_fmas_f32 v16, v16, v17, v19
	v_div_fixup_f32 v2, v16, v2, v20
	v_pk_mul_f32 v[2:3], v[4:5], v[2:3]
	v_mul_f32_e32 v4, 0xbfb8aa3b, v22
	v_rndne_f32_e32 v5, v4
	v_sub_f32_e32 v16, v4, v5
	v_fma_f32 v4, v22, s54, -v4
	v_fmac_f32_e32 v4, 0xb2a5705f, v22
	v_add_f32_e32 v4, v16, v4
	v_exp_f32_e32 v4, v4
	v_cvt_i32_f32_e32 v5, v5
	v_cvt_pk_bf16_f32 v2, v2, v3
	v_ldexp_f32 v4, v4, v5
	v_mul_f32_e32 v5, 0xbfb8aa3b, v23
	v_rndne_f32_e32 v16, v5
	v_sub_f32_e32 v17, v5, v16
	v_fma_f32 v5, v23, s54, -v5
	v_fmac_f32_e32 v5, 0xb2a5705f, v23
	v_add_f32_e32 v5, v17, v5
	v_exp_f32_e32 v5, v5
	v_cvt_i32_f32_e32 v16, v16
	v_ldexp_f32 v5, v5, v16
	s_nop 0
	s_nop 1
	s_nop 1
	v_pk_add_f32 v[4:5], v[4:5], 1.0 op_sel_hi:[1,0]
	s_nop 0
	v_div_scale_f32 v16, s[10:11], v5, v5, v23
	v_rcp_f32_e32 v17, v16
	s_nop 0
	v_fma_f32 v18, -v16, v17, 1.0
	v_fmac_f32_e32 v17, v18, v17
	v_div_scale_f32 v18, vcc, v23, v5, v23
	v_mul_f32_e32 v19, v18, v17
	v_fma_f32 v20, -v16, v19, v18
	v_fmac_f32_e32 v19, v20, v17
	v_fma_f32 v16, -v16, v19, v18
	v_div_fmas_f32 v16, v16, v17, v19
	v_div_fixup_f32 v5, v16, v5, v23
	v_div_scale_f32 v16, s[10:11], v4, v4, v22
	v_rcp_f32_e32 v17, v16
	s_nop 0
	v_fma_f32 v18, -v16, v17, 1.0
	v_fmac_f32_e32 v17, v18, v17
	v_div_scale_f32 v18, vcc, v22, v4, v22
	v_mul_f32_e32 v19, v18, v17
	v_fma_f32 v20, -v16, v19, v18
	v_fmac_f32_e32 v19, v20, v17
	v_fma_f32 v16, -v16, v19, v18
	v_div_fmas_f32 v16, v16, v17, v19
	v_div_fixup_f32 v4, v16, v4, v22
	v_pk_mul_f32 v[4:5], v[6:7], v[4:5]
	v_cvt_pk_bf16_f32 v3, v4, v5
	ds_write2_b64 v66, v[0:1], v[2:3] offset0:72 offset1:74
	v_mul_f32_e32 v0, 0xbfb8aa3b, v24
	v_rndne_f32_e32 v1, v0
	v_sub_f32_e32 v2, v0, v1
	v_fma_f32 v0, v24, s54, -v0
	v_fmac_f32_e32 v0, 0xb2a5705f, v24
	v_add_f32_e32 v0, v2, v0
	v_exp_f32_e32 v0, v0
	v_cvt_i32_f32_e32 v1, v1
	v_ldexp_f32 v0, v0, v1
	v_mul_f32_e32 v1, 0xbfb8aa3b, v25
	v_rndne_f32_e32 v2, v1
	v_sub_f32_e32 v3, v1, v2
	v_fma_f32 v1, v25, s54, -v1
	v_fmac_f32_e32 v1, 0xb2a5705f, v25
	v_add_f32_e32 v1, v3, v1
	v_exp_f32_e32 v1, v1
	v_cvt_i32_f32_e32 v2, v2
	v_ldexp_f32 v1, v1, v2
	s_nop 0
	s_nop 1
	s_nop 1
	v_pk_add_f32 v[0:1], v[0:1], 1.0 op_sel_hi:[1,0]
	s_nop 0
	v_div_scale_f32 v2, s[10:11], v1, v1, v25
	v_rcp_f32_e32 v3, v2
	s_nop 0
	v_fma_f32 v4, -v2, v3, 1.0
	v_fmac_f32_e32 v3, v4, v3
	v_div_scale_f32 v4, vcc, v25, v1, v25
	v_mul_f32_e32 v5, v4, v3
	v_fma_f32 v6, -v2, v5, v4
	v_fmac_f32_e32 v5, v6, v3
	v_fma_f32 v2, -v2, v5, v4
	v_div_fmas_f32 v2, v2, v3, v5
	v_div_fixup_f32 v1, v2, v1, v25
	v_div_scale_f32 v2, s[10:11], v0, v0, v24
	v_rcp_f32_e32 v3, v2
	s_nop 0
	v_fma_f32 v4, -v2, v3, 1.0
	v_fmac_f32_e32 v3, v4, v3
	v_div_scale_f32 v4, vcc, v24, v0, v24
	v_mul_f32_e32 v5, v4, v3
	v_fma_f32 v6, -v2, v5, v4
	v_fmac_f32_e32 v5, v6, v3
	v_fma_f32 v2, -v2, v5, v4
	v_div_fmas_f32 v2, v2, v3, v5
	v_div_fixup_f32 v0, v2, v0, v24
	v_mul_f32_e32 v2, 0xbfb8aa3b, v26
	v_rndne_f32_e32 v3, v2
	v_sub_f32_e32 v4, v2, v3
	v_fma_f32 v2, v26, s54, -v2
	v_fmac_f32_e32 v2, 0xb2a5705f, v26
	v_add_f32_e32 v2, v4, v2
	v_exp_f32_e32 v2, v2
	v_cvt_i32_f32_e32 v3, v3
	v_pk_mul_f32 v[0:1], v[8:9], v[0:1]
	v_ldexp_f32 v2, v2, v3
	v_mul_f32_e32 v3, 0xbfb8aa3b, v27
	v_rndne_f32_e32 v4, v3
	v_sub_f32_e32 v5, v3, v4
	v_fma_f32 v3, v27, s54, -v3
; DEVI void lds_put4(char* wl, int RS, int row, int col, float a, float b, float c, float d) { u32x2 w = {cvtpk(a, b), cvtpk(c, d)}; *(u32x2*)(wl + row * RS + col * 2) = w; }
; DEVI float siluf(float x) { return x / (1.f + expf(-x)); }
; DEVI void phase_gemm_f1(const Params& p, int l, char* lds) {
;     ...
;     char* wl = lds + wid * (64 * 144);
; #pragma unroll
;     for (int cg2 = 0; cg2 < 2; ++cg2) {
; #pragma unroll
;       for (int mi = 0; mi < 2; ++mi) {
; #pragma unroll
;         for (int q = 0; q < 4; ++q) {
;           float h[4];
; #pragma unroll
;           for (int j = 0; j < 4; ++j) h[j] = siluf(acc[2 * cg2][mi][q * 4 + j]) * acc[2 * cg2 + 1][mi][q * 4 + j];
;           lds_put4(wl, 144, mi * 32 + r32, cg2 * 32 + q * 8 + hi * 4, h[0], h[1], h[2], h[3]);
;         }
;       }
;     }
;     wave_tile_store<64>(wl, hid + (long)(m0 + wm * 64) * FH + (tn * 4 + wn * 2) * 32, FH, lane);
	v_fmac_f32_e32 v3, 0xb2a5705f, v27
	v_add_f32_e32 v3, v5, v3
	v_exp_f32_e32 v3, v3
	v_cvt_i32_f32_e32 v4, v4
	v_cvt_pk_bf16_f32 v0, v0, v1
	v_ldexp_f32 v3, v3, v4
	s_nop 1
	s_nop 1
	v_pk_add_f32 v[2:3], v[2:3], 1.0 op_sel_hi:[1,0]
	s_nop 0
	v_div_scale_f32 v4, s[10:11], v3, v3, v27
	v_rcp_f32_e32 v5, v4
	s_nop 0
	v_fma_f32 v6, -v4, v5, 1.0
	v_fmac_f32_e32 v5, v6, v5
	v_div_scale_f32 v6, vcc, v27, v3, v27
	v_mul_f32_e32 v7, v6, v5
	v_fma_f32 v8, -v4, v7, v6
	v_fmac_f32_e32 v7, v8, v5
	v_fma_f32 v4, -v4, v7, v6
	v_div_fmas_f32 v4, v4, v5, v7
	v_div_fixup_f32 v3, v4, v3, v27
	v_div_scale_f32 v4, s[10:11], v2, v2, v26
	v_rcp_f32_e32 v5, v4
	s_nop 0
	v_fma_f32 v6, -v4, v5, 1.0
	v_fmac_f32_e32 v5, v6, v5
	v_div_scale_f32 v6, vcc, v26, v2, v26
	v_mul_f32_e32 v7, v6, v5
	v_fma_f32 v8, -v4, v7, v6
	v_fmac_f32_e32 v7, v8, v5
	v_fma_f32 v4, -v4, v7, v6
	v_div_fmas_f32 v4, v4, v5, v7
	v_div_fixup_f32 v2, v4, v2, v26
	v_pk_mul_f32 v[2:3], v[10:11], v[2:3]
	v_cvt_pk_bf16_f32 v1, v2, v3
	v_mul_f32_e32 v2, 0xbfb8aa3b, v28
	v_rndne_f32_e32 v3, v2
	v_sub_f32_e32 v4, v2, v3
	v_fma_f32 v2, v28, s54, -v2
	v_fmac_f32_e32 v2, 0xb2a5705f, v28
	v_add_f32_e32 v2, v4, v2
	v_exp_f32_e32 v2, v2
	v_cvt_i32_f32_e32 v3, v3
	v_ldexp_f32 v2, v2, v3
	v_mul_f32_e32 v3, 0xbfb8aa3b, v29
	v_rndne_f32_e32 v4, v3
	v_sub_f32_e32 v5, v3, v4
	v_fma_f32 v3, v29, s54, -v3
	v_fmac_f32_e32 v3, 0xb2a5705f, v29
	v_add_f32_e32 v3, v5, v3
	v_exp_f32_e32 v3, v3
	v_cvt_i32_f32_e32 v4, v4
	v_ldexp_f32 v3, v3, v4
	s_nop 0
	s_nop 1
	s_nop 1
	v_pk_add_f32 v[2:3], v[2:3], 1.0 op_sel_hi:[1,0]
	s_nop 0
	v_div_scale_f32 v4, s[10:11], v3, v3, v29
	v_rcp_f32_e32 v5, v4
	s_nop 0
	v_fma_f32 v6, -v4, v5, 1.0
	v_fmac_f32_e32 v5, v6, v5
	v_div_scale_f32 v6, vcc, v29, v3, v29
	v_mul_f32_e32 v7, v6, v5
	v_fma_f32 v8, -v4, v7, v6
	v_fmac_f32_e32 v7, v8, v5
	v_fma_f32 v4, -v4, v7, v6
	v_div_fmas_f32 v4, v4, v5, v7
	v_div_fixup_f32 v3, v4, v3, v29
	v_div_scale_f32 v4, s[10:11], v2, v2, v28
	v_rcp_f32_e32 v5, v4
	s_nop 0
	v_fma_f32 v6, -v4, v5, 1.0
	v_fmac_f32_e32 v5, v6, v5
	v_div_scale_f32 v6, vcc, v28, v2, v28
	v_mul_f32_e32 v7, v6, v5
	v_fma_f32 v8, -v4, v7, v6
	v_fmac_f32_e32 v7, v8, v5
	v_fma_f32 v4, -v4, v7, v6
	v_div_fmas_f32 v4, v4, v5, v7
	v_div_fixup_f32 v2, v4, v2, v28
	v_mul_f32_e32 v4, 0xbfb8aa3b, v30
	v_rndne_f32_e32 v5, v4
	v_sub_f32_e32 v6, v4, v5
	v_fma_f32 v4, v30, s54, -v4
	v_fmac_f32_e32 v4, 0xb2a5705f, v30
	v_add_f32_e32 v4, v6, v4
	v_exp_f32_e32 v4, v4
	v_cvt_i32_f32_e32 v5, v5
	v_pk_mul_f32 v[2:3], v[12:13], v[2:3]
	v_ldexp_f32 v4, v4, v5
	v_mul_f32_e32 v5, 0xbfb8aa3b, v31
	v_rndne_f32_e32 v6, v5
	v_sub_f32_e32 v7, v5, v6
	v_fma_f32 v5, v31, s54, -v5
	v_fmac_f32_e32 v5, 0xb2a5705f, v31
	v_add_f32_e32 v5, v7, v5
	v_exp_f32_e32 v5, v5
	v_cvt_i32_f32_e32 v6, v6
	v_cvt_pk_bf16_f32 v2, v2, v3
	v_ldexp_f32 v5, v5, v6
	s_nop 1
	s_nop 1
	v_pk_add_f32 v[4:5], v[4:5], 1.0 op_sel_hi:[1,0]
	s_nop 0
	v_div_scale_f32 v6, s[10:11], v5, v5, v31
	v_rcp_f32_e32 v7, v6
	s_nop 0
	v_fma_f32 v8, -v6, v7, 1.0
	v_fmac_f32_e32 v7, v8, v7
	v_div_scale_f32 v8, vcc, v31, v5, v31
	v_mul_f32_e32 v9, v8, v7
	v_fma_f32 v10, -v6, v9, v8
	v_fmac_f32_e32 v9, v10, v7
	v_fma_f32 v6, -v6, v9, v8
	v_div_fmas_f32 v6, v6, v7, v9
	v_div_fixup_f32 v5, v6, v5, v31
	v_div_scale_f32 v6, s[10:11], v4, v4, v30
	v_rcp_f32_e32 v7, v6
	s_nop 0
	v_fma_f32 v8, -v6, v7, 1.0
	v_fmac_f32_e32 v7, v8, v7
	v_div_scale_f32 v8, vcc, v30, v4, v30
	v_mul_f32_e32 v9, v8, v7
	v_fma_f32 v10, -v6, v9, v8
	v_fmac_f32_e32 v9, v10, v7
	v_fma_f32 v6, -v6, v9, v8
	v_div_fmas_f32 v6, v6, v7, v9
	v_div_fixup_f32 v4, v6, v4, v30
	v_pk_mul_f32 v[4:5], v[14:15], v[4:5]
	s_nop 0
	v_cvt_pk_bf16_f32 v3, v4, v5
	ds_write2_b64 v66, v[0:1], v[2:3] offset0:76 offset1:78
	v_or_b32_e32 v2, s8, v222
	v_lshl_add_u32 v0, s9, 7, v223
	v_ashrrev_i32_e32 v1, 31, v0
	v_lshlrev_b64 v[0:1], 1, v[0:1]
	s_movk_i32 s8, 0x1600
	v_mad_i64_i32 v[0:1], s[8:9], v2, s8, v[0:1]
	v_lshl_add_u64 v[0:1], v[194:195], 0, v[0:1]
	s_mov_b64 s[8:9], 0
	v_mov_b32_e32 v2, v224
